# speedup vs baseline: 1.0241x; 1.0012x over previous
; __device__ __forceinline__ float sigmf(float x) { return 1.f / (1.f + __expf(-x)); }
; __device__ __forceinline__ float softplusf(float x) { return fmaxf(x, 0.f) + __logf(1.f + __expf(-fabsf(x))); }
; __device__ __forceinline__ void inproj_epilogue(const Params& p, int layer, int mt, int ntile, int tid,
;                                                 f32x16 (&acc)[2][2], unsigned char* smem) {
;     ...
;   const int m0 = mt * 128;
;   if (mode == 3) {
;     float* dt = (float*)(p.ws + OFF_DT) + (size_t)m0 * 16;
;     const float* bias = p.ssd_dt_bias + layer * 16;
;     acc_foreach(tid, acc, [&](int row, int col, float v) {
;       if (col < 16) *(dt + row * 16 + col) = softplusf(v + bias[col]);
;     });
;   } else {
;     bf16r* dstb = dst + (size_t)m0 * ld + c0;
;     bf16r* sT = (bf16r*)smem;
;     acc_foreach(tid, acc, [&](int row, int col, float v) {
;       int t = m0 + row;
;       float o = v;
;       if (mode == 1) o = (t >= NPADR) ? v : 0.f;
;       if (mode == 2) o = sigmf(v);
;       sT[row * 136 + col] = f2bf(o);
.LBB0_205:
	s_lshl_b32 s60, s6, 7
	s_ashr_i32 s61, s60, 31
	s_cmp_lg_u32 s7, 3
	s_mov_b64 s[4:5], -1
	s_cbranch_scc0 .LBB0_399
	v_mov_b32_e32 v106, v108
	s_movk_i32 s4, 0xffc0
	v_lshrrev_b32_e32 v107, 3, v106
	v_ashrrev_i32_e32 v96, 1, v106
	v_and_b32_e32 v107, 4, v107
	v_and_or_b32 v96, v96, s4, v107
	s_cmp_eq_u32 s7, 1
	s_cselect_b64 s[4:5], -1, 0
	v_add_u32_e32 v107, s60, v96
	s_cmp_eq_u32 s7, 2
	s_cselect_b64 s[12:13], -1, 0
	s_cmp_lg_u32 s7, 2
	v_cmp_lt_i32_e64 s[8:9], s43, v107
	s_cbranch_scc0 .Lgv_0
	s_cmp_eq_u32 s7, 1
	s_cbranch_scc0 .Lfp_0

; __device__ __forceinline__ float sigmf(float x) { return 1.f / (1.f + __expf(-x)); }
; __device__ __forceinline__ bf16r f2bf(float f) {
;   unsigned u = __float_as_uint(f);
;   u += 0x7fffu + ((u >> 16) & 1u);
;   return (bf16r)(u >> 16);
; }
; __device__ __forceinline__ void inproj_epilogue(const Params& p, int layer, int mt, int ntile, int tid,
;                                                 f32x16 (&acc)[2][2], unsigned char* smem) {
;     ...
;     acc_foreach(tid, acc, [&](int row, int col, float v) {
;       int t = m0 + row;
;       float o = v;
;       if (mode == 1) o = (t >= NPADR) ? v : 0.f;
;       if (mode == 2) o = sigmf(v);
;       sT[row * 136 + col] = f2bf(o);
;     });
.Lfp_0:
	v_bfe_u32 v110, v16, 16, 1
	v_and_b32_e32 v106, 0x5f, v106
	v_add3_u32 v111, v16, v110, s77
	v_mul_lo_u32 v110, v96, s78
	v_lshl_add_u32 v107, v106, 1, v110
	ds_write_b16_d16_hi v107, v111
	v_add3_u32 v111, s60, v96, 1
	v_cmp_lt_i32_e64 s[10:11], s43, v111
	v_cndmask_b32_e64 v111, 0, 1, s[12:13]
	v_cmp_ne_u32_e64 s[6:7], 1, v111
	v_bfe_u32 v112, v17, 16, 1
	v_add3_u32 v112, v17, v112, s77
	v_add_u32_e32 v111, 0x110, v110
	v_lshl_add_u32 v110, v106, 1, v111
	ds_write_b16_d16_hi v110, v112
	v_add3_u32 v112, s60, v96, 2
	v_cmp_lt_i32_e64 s[12:13], s43, v112
	v_bfe_u32 v113, v18, 16, 1
	v_add3_u32 v113, v18, v113, s77
	v_add_u32_e32 v112, 0x110, v111
	v_lshl_add_u32 v111, v106, 1, v112
	ds_write_b16_d16_hi v111, v113
	v_add3_u32 v113, s60, v96, 3
	v_cmp_lt_i32_e64 s[14:15], s43, v113
	v_bfe_u32 v114, v19, 16, 1
	v_add3_u32 v114, v19, v114, s77
	v_add_u32_e32 v113, 0x110, v112
	v_lshl_add_u32 v112, v106, 1, v113
	ds_write_b16_d16_hi v112, v114
	v_add3_u32 v114, s60, v96, 8
	v_cmp_lt_i32_e64 s[16:17], s43, v114
	v_bfe_u32 v115, v20, 16, 1
	v_add3_u32 v115, v20, v115, s77
	v_add_u32_e32 v114, 0x550, v113
	v_lshl_add_u32 v113, v106, 1, v114
	ds_write_b16_d16_hi v113, v115
	v_add3_u32 v115, s60, v96, 9
	v_cmp_lt_i32_e64 s[18:19], s43, v115
	v_bfe_u32 v116, v21, 16, 1
	v_add3_u32 v116, v21, v116, s77
	v_add_u32_e32 v115, 0x110, v114
	v_lshl_add_u32 v114, v106, 1, v115
	ds_write_b16_d16_hi v114, v116
	v_add3_u32 v116, s60, v96, 10
	v_cmp_lt_i32_e64 s[20:21], s43, v116
	v_bfe_u32 v117, v22, 16, 1
	v_add3_u32 v117, v22, v117, s77
	v_add_u32_e32 v116, 0x110, v115
	v_lshl_add_u32 v115, v106, 1, v116
	ds_write_b16_d16_hi v115, v117
	v_add3_u32 v117, s60, v96, 11
	v_cmp_lt_i32_e64 s[22:23], s43, v117
	v_bfe_u32 v118, v23, 16, 1
	v_add_u32_e32 v116, 0x110, v116
	v_add3_u32 v118, v23, v118, s77
	v_lshl_add_u32 v117, v106, 1, v116
	ds_write_b16_d16_hi v117, v118
	v_add3_u32 v118, s60, v96, 16
	v_cmp_lt_i32_e64 s[24:25], s43, v118
	v_bfe_u32 v119, v24, 16, 1
	v_add_u32_e32 v116, 0x550, v116
	v_add3_u32 v119, v24, v119, s77
	v_lshl_add_u32 v118, v106, 1, v116
	ds_write_b16_d16_hi v118, v119
	v_add3_u32 v119, s60, v96, 17
	v_cmp_lt_i32_e64 s[26:27], s43, v119
	v_bfe_u32 v120, v25, 16, 1
	v_add_u32_e32 v116, 0x110, v116
	v_add3_u32 v120, v25, v120, s77
	v_lshl_add_u32 v119, v106, 1, v116
	ds_write_b16_d16_hi v119, v120
	v_add3_u32 v120, s60, v96, 18
	v_cmp_lt_i32_e64 s[28:29], s43, v120
	v_bfe_u32 v121, v26, 16, 1
	v_add_u32_e32 v116, 0x110, v116
	v_add3_u32 v121, v26, v121, s77
	v_lshl_add_u32 v120, v106, 1, v116
	ds_write_b16_d16_hi v120, v121
	v_add3_u32 v121, s60, v96, 19
	v_cmp_lt_i32_e64 s[30:31], s43, v121
	v_bfe_u32 v122, v27, 16, 1
	v_add_u32_e32 v116, 0x110, v116
	v_add3_u32 v122, v27, v122, s77
	v_lshl_add_u32 v121, v106, 1, v116
	ds_write_b16_d16_hi v121, v122
	v_add3_u32 v122, s60, v96, 24
	v_cmp_lt_i32_e64 s[34:35], s43, v122
	v_bfe_u32 v123, v28, 16, 1
	v_add_u32_e32 v116, 0x550, v116
	v_add3_u32 v123, v28, v123, s77
	v_lshl_add_u32 v122, v106, 1, v116
	ds_write_b16_d16_hi v122, v123
	v_add3_u32 v123, s60, v96, 25
	v_cmp_lt_i32_e64 s[36:37], s43, v123
	v_bfe_u32 v124, v29, 16, 1
	v_add_u32_e32 v116, 0x110, v116
	v_add3_u32 v124, v29, v124, s77
	v_lshl_add_u32 v123, v106, 1, v116
	ds_write_b16_d16_hi v123, v124
	v_add3_u32 v124, s60, v96, 26
	v_cmp_lt_i32_e64 s[38:39], s43, v124
	v_bfe_u32 v125, v30, 16, 1
	v_add_u32_e32 v116, 0x110, v116
	v_add3_u32 v124, v30, v125, s77
	v_lshl_add_u32 v116, v106, 1, v116
	ds_write_b16_d16_hi v116, v124
	v_add3_u32 v124, s60, v96, 27
	v_cmp_lt_i32_e64 s[40:41], s43, v124
	v_bfe_u32 v125, v31, 16, 1
	v_add3_u32 v124, v31, v125, s77
	ds_write_b16_d16_hi v116, v124 offset:272
	v_bfe_u32 v124, v48, 16, 1
	v_add3_u32 v48, v48, v124, s77
	ds_write_b16_d16_hi v107, v48 offset:64
	v_bfe_u32 v48, v49, 16, 1
	v_add3_u32 v48, v49, v48, s77
	ds_write_b16_d16_hi v110, v48 offset:64
	v_bfe_u32 v49, v50, 16, 1
	v_add3_u32 v48, v50, v49, s77
	ds_write_b16_d16_hi v111, v48 offset:64
	v_bfe_u32 v49, v51, 16, 1
	v_add3_u32 v48, v51, v49, s77
	ds_write_b16_d16_hi v112, v48 offset:64
	v_bfe_u32 v49, v52, 16, 1
	v_add3_u32 v48, v52, v49, s77
	ds_write_b16_d16_hi v113, v48 offset:64
	v_bfe_u32 v49, v53, 16, 1
	v_add3_u32 v48, v53, v49, s77
	ds_write_b16_d16_hi v114, v48 offset:64
	v_bfe_u32 v49, v54, 16, 1
	v_add3_u32 v48, v54, v49, s77
	ds_write_b16_d16_hi v115, v48 offset:64
	v_bfe_u32 v49, v55, 16, 1
	v_add3_u32 v48, v55, v49, s77
	ds_write_b16_d16_hi v117, v48 offset:64
	v_bfe_u32 v49, v56, 16, 1
	v_add3_u32 v48, v56, v49, s77
	ds_write_b16_d16_hi v118, v48 offset:64
	v_bfe_u32 v49, v57, 16, 1
	v_add3_u32 v48, v57, v49, s77
	ds_write_b16_d16_hi v119, v48 offset:64
	v_bfe_u32 v49, v58, 16, 1
	v_add3_u32 v48, v58, v49, s77
	ds_write_b16_d16_hi v120, v48 offset:64
	v_bfe_u32 v49, v59, 16, 1
	v_add3_u32 v48, v59, v49, s77
	ds_write_b16_d16_hi v121, v48 offset:64
	v_bfe_u32 v49, v60, 16, 1
	v_add3_u32 v48, v60, v49, s77
	ds_write_b16_d16_hi v122, v48 offset:64
	v_bfe_u32 v49, v61, 16, 1
	v_add3_u32 v48, v61, v49, s77
	ds_write_b16_d16_hi v123, v48 offset:64
	v_bfe_u32 v49, v62, 16, 1
	v_add3_u32 v48, v62, v49, s77
; __device__ __forceinline__ float sigmf(float x) { return 1.f / (1.f + __expf(-x)); }
; __device__ __forceinline__ bf16r f2bf(float f) {
;   unsigned u = __float_as_uint(f);
;   u += 0x7fffu + ((u >> 16) & 1u);
;   return (bf16r)(u >> 16);
; }
; __device__ __forceinline__ void inproj_epilogue(const Params& p, int layer, int mt, int ntile, int tid,
;                                                 f32x16 (&acc)[2][2], unsigned char* smem) {
;     ...
;     acc_foreach(tid, acc, [&](int row, int col, float v) {
;       int t = m0 + row;
;       float o = v;
;       if (mode == 1) o = (t >= NPADR) ? v : 0.f;
;       if (mode == 2) o = sigmf(v);
;       sT[row * 136 + col] = f2bf(o);
;     });
	ds_write_b16_d16_hi v116, v48 offset:64
	v_bfe_u32 v50, v63, 16, 1
	v_add_u32_e32 v49, 0x110, v116
	v_add3_u32 v48, v63, v50, s77
	ds_write_b16_d16_hi v49, v48 offset:64
	v_or_b32_e32 v48, 32, v96
	v_add_u32_e32 v49, s60, v48
	v_cmp_lt_i32_e64 s[8:9], s43, v49
	v_bfe_u32 v50, v0, 16, 1
	v_add3_u32 v50, v0, v50, s77
	v_mul_lo_u32 v49, v48, s78
	v_lshl_add_u32 v48, v106, 1, v49
	ds_write_b16_d16_hi v48, v50
	v_add3_u32 v50, s60, v96, 33
	v_cmp_lt_i32_e64 s[10:11], s43, v50
	v_bfe_u32 v51, v1, 16, 1
	v_add3_u32 v51, v1, v51, s77
	v_add_u32_e32 v50, 0x110, v49
	v_lshl_add_u32 v49, v106, 1, v50
	ds_write_b16_d16_hi v49, v51
	v_add3_u32 v51, s60, v96, 34
	v_cmp_lt_i32_e64 s[12:13], s43, v51
	v_bfe_u32 v52, v2, 16, 1
	v_add3_u32 v52, v2, v52, s77
	v_add_u32_e32 v51, 0x110, v50
	v_lshl_add_u32 v50, v106, 1, v51
	ds_write_b16_d16_hi v50, v52
	v_add3_u32 v52, s60, v96, 35
	v_cmp_lt_i32_e64 s[14:15], s43, v52
	v_bfe_u32 v53, v3, 16, 1
	v_add3_u32 v53, v3, v53, s77
	v_add_u32_e32 v52, 0x110, v51
	v_lshl_add_u32 v51, v106, 1, v52
	ds_write_b16_d16_hi v51, v53
	v_add3_u32 v53, s60, v96, 40
	v_cmp_lt_i32_e64 s[16:17], s43, v53
	v_bfe_u32 v54, v4, 16, 1
	v_add3_u32 v54, v4, v54, s77
	v_add_u32_e32 v53, 0x550, v52
	v_lshl_add_u32 v52, v106, 1, v53
	ds_write_b16_d16_hi v52, v54
	v_add3_u32 v54, s60, v96, 41
	v_cmp_lt_i32_e64 s[18:19], s43, v54
	v_bfe_u32 v55, v5, 16, 1
	v_add3_u32 v55, v5, v55, s77
	v_add_u32_e32 v54, 0x110, v53
	v_lshl_add_u32 v53, v106, 1, v54
	ds_write_b16_d16_hi v53, v55
	v_add3_u32 v55, s60, v96, 42
	v_cmp_lt_i32_e64 s[20:21], s43, v55
	v_bfe_u32 v56, v6, 16, 1
	v_add3_u32 v56, v6, v56, s77
	v_add_u32_e32 v55, 0x110, v54
	v_lshl_add_u32 v54, v106, 1, v55
	ds_write_b16_d16_hi v54, v56
	v_add3_u32 v56, s60, v96, 43
	v_cmp_lt_i32_e64 s[22:23], s43, v56
	v_bfe_u32 v57, v7, 16, 1
	v_add_u32_e32 v55, 0x110, v55
	v_add3_u32 v57, v7, v57, s77
	v_lshl_add_u32 v56, v106, 1, v55
	ds_write_b16_d16_hi v56, v57
	v_add3_u32 v57, s60, v96, 48
	v_cmp_lt_i32_e64 s[24:25], s43, v57
	v_bfe_u32 v58, v8, 16, 1
	v_add_u32_e32 v55, 0x550, v55
	v_add3_u32 v58, v8, v58, s77
	v_lshl_add_u32 v57, v106, 1, v55
	ds_write_b16_d16_hi v57, v58
	v_add3_u32 v58, s60, v96, 49
	v_cmp_lt_i32_e64 s[26:27], s43, v58
	v_bfe_u32 v59, v9, 16, 1
	v_add_u32_e32 v55, 0x110, v55
	v_add3_u32 v59, v9, v59, s77
	v_lshl_add_u32 v58, v106, 1, v55
	ds_write_b16_d16_hi v58, v59
	v_add3_u32 v59, s60, v96, 50
	v_cmp_lt_i32_e64 s[28:29], s43, v59
	v_bfe_u32 v60, v10, 16, 1
	v_add_u32_e32 v55, 0x110, v55
	v_add3_u32 v60, v10, v60, s77
	v_lshl_add_u32 v59, v106, 1, v55
	ds_write_b16_d16_hi v59, v60
	v_add3_u32 v60, s60, v96, 51
	v_cmp_lt_i32_e64 s[30:31], s43, v60
	v_bfe_u32 v61, v11, 16, 1
	v_add_u32_e32 v55, 0x110, v55
	v_add3_u32 v61, v11, v61, s77
	v_lshl_add_u32 v60, v106, 1, v55
	ds_write_b16_d16_hi v60, v61
	v_add3_u32 v61, s60, v96, 56
	v_cmp_lt_i32_e64 s[34:35], s43, v61
	v_bfe_u32 v62, v12, 16, 1
	v_add_u32_e32 v55, 0x550, v55
	v_add3_u32 v62, v12, v62, s77
	v_lshl_add_u32 v61, v106, 1, v55
	ds_write_b16_d16_hi v61, v62
	v_add3_u32 v62, s60, v96, 57
	v_cmp_lt_i32_e64 s[36:37], s43, v62
	v_bfe_u32 v63, v13, 16, 1
	v_add_u32_e32 v55, 0x110, v55
	v_add3_u32 v63, v13, v63, s77
	v_lshl_add_u32 v62, v106, 1, v55
	ds_write_b16_d16_hi v62, v63
	v_add3_u32 v63, s60, v96, 58
	v_cmp_lt_i32_e64 s[38:39], s43, v63
	v_bfe_u32 v107, v14, 16, 1
	v_add_u32_e32 v55, 0x110, v55
	v_add3_u32 v63, v14, v107, s77
	v_lshl_add_u32 v55, v106, 1, v55
	ds_write_b16_d16_hi v55, v63
	v_add3_u32 v63, s60, v96, 59
	v_cmp_lt_i32_e64 s[40:41], s43, v63
	v_bfe_u32 v96, v15, 16, 1
	v_add3_u32 v63, v15, v96, s77
	ds_write_b16_d16_hi v55, v63 offset:272
	v_bfe_u32 v63, v32, 16, 1
	v_add3_u32 v32, v32, v63, s77
	ds_write_b16_d16_hi v48, v32 offset:64
	v_bfe_u32 v32, v33, 16, 1
	v_add3_u32 v32, v33, v32, s77
	ds_write_b16_d16_hi v49, v32 offset:64
	v_bfe_u32 v33, v34, 16, 1
	v_add3_u32 v32, v34, v33, s77
	ds_write_b16_d16_hi v50, v32 offset:64
	v_bfe_u32 v33, v35, 16, 1
	v_add3_u32 v32, v35, v33, s77
	ds_write_b16_d16_hi v51, v32 offset:64
	v_bfe_u32 v33, v36, 16, 1
	v_add3_u32 v32, v36, v33, s77
	ds_write_b16_d16_hi v52, v32 offset:64
	v_bfe_u32 v33, v37, 16, 1
	v_add3_u32 v32, v37, v33, s77
	ds_write_b16_d16_hi v53, v32 offset:64
	v_bfe_u32 v33, v38, 16, 1
	v_add3_u32 v32, v38, v33, s77
	ds_write_b16_d16_hi v54, v32 offset:64
	v_bfe_u32 v33, v39, 16, 1
	v_add3_u32 v32, v39, v33, s77
	ds_write_b16_d16_hi v56, v32 offset:64
	v_bfe_u32 v33, v40, 16, 1
	v_add3_u32 v32, v40, v33, s77
	ds_write_b16_d16_hi v57, v32 offset:64
	v_bfe_u32 v33, v41, 16, 1
	v_add3_u32 v32, v41, v33, s77
	ds_write_b16_d16_hi v58, v32 offset:64
	v_bfe_u32 v33, v42, 16, 1
	v_add3_u32 v32, v42, v33, s77
	ds_write_b16_d16_hi v59, v32 offset:64
	v_bfe_u32 v33, v43, 16, 1
	v_add3_u32 v32, v43, v33, s77
	ds_write_b16_d16_hi v60, v32 offset:64
	v_bfe_u32 v33, v44, 16, 1
	v_add3_u32 v32, v44, v33, s77
	ds_write_b16_d16_hi v61, v32 offset:64
	v_bfe_u32 v33, v45, 16, 1
	v_add3_u32 v32, v45, v33, s77
	ds_write_b16_d16_hi v62, v32 offset:64
	v_bfe_u32 v33, v46, 16, 1
	v_add3_u32 v32, v46, v33, s77
	ds_write_b16_d16_hi v55, v32 offset:64
	v_mov_b32_e32 v32, v47
	s_branch .LBB0_398

; __device__ __forceinline__ float sigmf(float x) { return 1.f / (1.f + __expf(-x)); }
; __device__ __forceinline__ float softplusf(float x) { return fmaxf(x, 0.f) + __logf(1.f + __expf(-fabsf(x))); }
; __device__ __forceinline__ void inproj_epilogue(const Params& p, int layer, int mt, int ntile, int tid,
;                                                 f32x16 (&acc)[2][2], unsigned char* smem) {
;     ...
;   const int m0 = mt * 128;
;   if (mode == 3) {
;     float* dt = (float*)(p.ws + OFF_DT) + (size_t)m0 * 16;
;     const float* bias = p.ssd_dt_bias + layer * 16;
;     acc_foreach(tid, acc, [&](int row, int col, float v) {
;       if (col < 16) *(dt + row * 16 + col) = softplusf(v + bias[col]);
;     });
;   } else {
;     bf16r* dstb = dst + (size_t)m0 * ld + c0;
;     bf16r* sT = (bf16r*)smem;
;     acc_foreach(tid, acc, [&](int row, int col, float v) {
;       int t = m0 + row;
;       float o = v;
;       if (mode == 1) o = (t >= NPADR) ? v : 0.f;
;       if (mode == 2) o = sigmf(v);
;       sT[row * 136 + col] = f2bf(o);
.LBB0_524:
	s_lshl_b32 s90, s6, 7
	s_ashr_i32 s91, s90, 31
	s_cmp_lg_u32 s7, 3
	s_mov_b64 s[4:5], -1
	s_cbranch_scc0 .LBB0_718
	v_mov_b32_e32 v106, v108
	s_movk_i32 s4, 0xffc0
	v_lshrrev_b32_e32 v107, 3, v106
	v_ashrrev_i32_e32 v96, 1, v106
	v_and_b32_e32 v107, 4, v107
	v_and_or_b32 v96, v96, s4, v107
	s_cmp_eq_u32 s7, 1
	s_cselect_b64 s[4:5], -1, 0
	v_add_u32_e32 v107, s90, v96
	s_cmp_eq_u32 s7, 2
	s_cselect_b64 s[12:13], -1, 0
	s_cmp_lg_u32 s7, 2
	v_cmp_lt_i32_e64 s[8:9], s76, v107
	s_cbranch_scc0 .Lgv_1
	s_cmp_eq_u32 s7, 1
	s_cbranch_scc0 .Lfp_1

; __device__ __forceinline__ float sigmf(float x) { return 1.f / (1.f + __expf(-x)); }
; __device__ __forceinline__ bf16r f2bf(float f) {
;   unsigned u = __float_as_uint(f);
;   u += 0x7fffu + ((u >> 16) & 1u);
;   return (bf16r)(u >> 16);
; }
; __device__ __forceinline__ void inproj_epilogue(const Params& p, int layer, int mt, int ntile, int tid,
;                                                 f32x16 (&acc)[2][2], unsigned char* smem) {
;     ...
;     acc_foreach(tid, acc, [&](int row, int col, float v) {
;       int t = m0 + row;
;       float o = v;
;       if (mode == 1) o = (t >= NPADR) ? v : 0.f;
;       if (mode == 2) o = sigmf(v);
;       sT[row * 136 + col] = f2bf(o);
;     });
.Lfp_1:
	v_bfe_u32 v110, v16, 16, 1
	v_and_b32_e32 v106, 0x5f, v106
	v_add3_u32 v111, v16, v110, s78
	v_mul_lo_u32 v110, v96, s79
	v_lshl_add_u32 v107, v106, 1, v110
	ds_write_b16_d16_hi v107, v111
	v_add3_u32 v111, s90, v96, 1
	v_cmp_lt_i32_e64 s[10:11], s76, v111
	v_cndmask_b32_e64 v111, 0, 1, s[12:13]
	v_cmp_ne_u32_e64 s[6:7], 1, v111
	v_bfe_u32 v112, v17, 16, 1
	v_add3_u32 v112, v17, v112, s78
	v_add_u32_e32 v111, 0x110, v110
	v_lshl_add_u32 v110, v106, 1, v111
	ds_write_b16_d16_hi v110, v112
	v_add3_u32 v112, s90, v96, 2
	v_cmp_lt_i32_e64 s[12:13], s76, v112
	v_bfe_u32 v113, v18, 16, 1
	v_add3_u32 v113, v18, v113, s78
	v_add_u32_e32 v112, 0x110, v111
	v_lshl_add_u32 v111, v106, 1, v112
	ds_write_b16_d16_hi v111, v113
	v_add3_u32 v113, s90, v96, 3
	v_cmp_lt_i32_e64 s[14:15], s76, v113
	v_bfe_u32 v114, v19, 16, 1
	v_add3_u32 v114, v19, v114, s78
	v_add_u32_e32 v113, 0x110, v112
	v_lshl_add_u32 v112, v106, 1, v113
	ds_write_b16_d16_hi v112, v114
	v_add3_u32 v114, s90, v96, 8
	v_cmp_lt_i32_e64 s[16:17], s76, v114
	v_bfe_u32 v115, v20, 16, 1
	v_add3_u32 v115, v20, v115, s78
	v_add_u32_e32 v114, 0x550, v113
	v_lshl_add_u32 v113, v106, 1, v114
	ds_write_b16_d16_hi v113, v115
	v_add3_u32 v115, s90, v96, 9
	v_cmp_lt_i32_e64 s[18:19], s76, v115
	v_bfe_u32 v116, v21, 16, 1
	v_add3_u32 v116, v21, v116, s78
	v_add_u32_e32 v115, 0x110, v114
	v_lshl_add_u32 v114, v106, 1, v115
	ds_write_b16_d16_hi v114, v116
	v_add3_u32 v116, s90, v96, 10
	v_cmp_lt_i32_e64 s[20:21], s76, v116
	v_bfe_u32 v117, v22, 16, 1
	v_add3_u32 v117, v22, v117, s78
	v_add_u32_e32 v116, 0x110, v115
	v_lshl_add_u32 v115, v106, 1, v116
	ds_write_b16_d16_hi v115, v117
	v_add3_u32 v117, s90, v96, 11
	v_cmp_lt_i32_e64 s[22:23], s76, v117
	v_bfe_u32 v118, v23, 16, 1
	v_add_u32_e32 v116, 0x110, v116
	v_add3_u32 v118, v23, v118, s78
	v_lshl_add_u32 v117, v106, 1, v116
	ds_write_b16_d16_hi v117, v118
	v_add3_u32 v118, s90, v96, 16
	v_cmp_lt_i32_e64 s[24:25], s76, v118
	v_bfe_u32 v119, v24, 16, 1
	v_add_u32_e32 v116, 0x550, v116
	v_add3_u32 v119, v24, v119, s78
	v_lshl_add_u32 v118, v106, 1, v116
	ds_write_b16_d16_hi v118, v119
	v_add3_u32 v119, s90, v96, 17
	v_cmp_lt_i32_e64 s[26:27], s76, v119
	v_bfe_u32 v120, v25, 16, 1
	v_add_u32_e32 v116, 0x110, v116
	v_add3_u32 v120, v25, v120, s78
	v_lshl_add_u32 v119, v106, 1, v116
	ds_write_b16_d16_hi v119, v120
	v_add3_u32 v120, s90, v96, 18
	v_cmp_lt_i32_e64 s[28:29], s76, v120
	v_bfe_u32 v121, v26, 16, 1
	v_add_u32_e32 v116, 0x110, v116
	v_add3_u32 v121, v26, v121, s78
	v_lshl_add_u32 v120, v106, 1, v116
	ds_write_b16_d16_hi v120, v121
	v_add3_u32 v121, s90, v96, 19
	v_cmp_lt_i32_e64 s[30:31], s76, v121
	v_bfe_u32 v122, v27, 16, 1
	v_add_u32_e32 v116, 0x110, v116
	v_add3_u32 v122, v27, v122, s78
	v_lshl_add_u32 v121, v106, 1, v116
	ds_write_b16_d16_hi v121, v122
	v_add3_u32 v122, s90, v96, 24
	v_cmp_lt_i32_e64 s[34:35], s76, v122
	v_bfe_u32 v123, v28, 16, 1
	v_add_u32_e32 v116, 0x550, v116
	v_add3_u32 v123, v28, v123, s78
	v_lshl_add_u32 v122, v106, 1, v116
	ds_write_b16_d16_hi v122, v123
	v_add3_u32 v123, s90, v96, 25
	v_cmp_lt_i32_e64 s[36:37], s76, v123
	v_bfe_u32 v124, v29, 16, 1
	v_add_u32_e32 v116, 0x110, v116
	v_add3_u32 v124, v29, v124, s78
	v_lshl_add_u32 v123, v106, 1, v116
	ds_write_b16_d16_hi v123, v124
	v_add3_u32 v124, s90, v96, 26
	v_cmp_lt_i32_e64 s[38:39], s76, v124
	v_bfe_u32 v125, v30, 16, 1
	v_add_u32_e32 v116, 0x110, v116
	v_add3_u32 v124, v30, v125, s78
	v_lshl_add_u32 v116, v106, 1, v116
	ds_write_b16_d16_hi v116, v124
	v_add3_u32 v124, s90, v96, 27
	v_cmp_lt_i32_e64 s[40:41], s76, v124
	v_bfe_u32 v125, v31, 16, 1
	v_add3_u32 v124, v31, v125, s78
	ds_write_b16_d16_hi v116, v124 offset:272
	v_bfe_u32 v124, v48, 16, 1
	v_add3_u32 v48, v48, v124, s78
	ds_write_b16_d16_hi v107, v48 offset:64
	v_bfe_u32 v48, v49, 16, 1
	v_add3_u32 v48, v49, v48, s78
	ds_write_b16_d16_hi v110, v48 offset:64
	v_bfe_u32 v49, v50, 16, 1
	v_add3_u32 v48, v50, v49, s78
	ds_write_b16_d16_hi v111, v48 offset:64
	v_bfe_u32 v49, v51, 16, 1
	v_add3_u32 v48, v51, v49, s78
	ds_write_b16_d16_hi v112, v48 offset:64
	v_bfe_u32 v49, v52, 16, 1
	v_add3_u32 v48, v52, v49, s78
	ds_write_b16_d16_hi v113, v48 offset:64
	v_bfe_u32 v49, v53, 16, 1
	v_add3_u32 v48, v53, v49, s78
	ds_write_b16_d16_hi v114, v48 offset:64
	v_bfe_u32 v49, v54, 16, 1
	v_add3_u32 v48, v54, v49, s78
	ds_write_b16_d16_hi v115, v48 offset:64
	v_bfe_u32 v49, v55, 16, 1
	v_add3_u32 v48, v55, v49, s78
	ds_write_b16_d16_hi v117, v48 offset:64
	v_bfe_u32 v49, v56, 16, 1
	v_add3_u32 v48, v56, v49, s78
	ds_write_b16_d16_hi v118, v48 offset:64
	v_bfe_u32 v49, v57, 16, 1
	v_add3_u32 v48, v57, v49, s78
	ds_write_b16_d16_hi v119, v48 offset:64
	v_bfe_u32 v49, v58, 16, 1
	v_add3_u32 v48, v58, v49, s78
	ds_write_b16_d16_hi v120, v48 offset:64
	v_bfe_u32 v49, v59, 16, 1
	v_add3_u32 v48, v59, v49, s78
	ds_write_b16_d16_hi v121, v48 offset:64
	v_bfe_u32 v49, v60, 16, 1
	v_add3_u32 v48, v60, v49, s78
	ds_write_b16_d16_hi v122, v48 offset:64
	v_bfe_u32 v49, v61, 16, 1
	v_add3_u32 v48, v61, v49, s78
	ds_write_b16_d16_hi v123, v48 offset:64
	v_bfe_u32 v49, v62, 16, 1
	v_add3_u32 v48, v62, v49, s78
; __device__ __forceinline__ float sigmf(float x) { return 1.f / (1.f + __expf(-x)); }
; __device__ __forceinline__ bf16r f2bf(float f) {
;   unsigned u = __float_as_uint(f);
;   u += 0x7fffu + ((u >> 16) & 1u);
;   return (bf16r)(u >> 16);
; }
; __device__ __forceinline__ void inproj_epilogue(const Params& p, int layer, int mt, int ntile, int tid,
;                                                 f32x16 (&acc)[2][2], unsigned char* smem) {
;     ...
;     acc_foreach(tid, acc, [&](int row, int col, float v) {
;       int t = m0 + row;
;       float o = v;
;       if (mode == 1) o = (t >= NPADR) ? v : 0.f;
;       if (mode == 2) o = sigmf(v);
;       sT[row * 136 + col] = f2bf(o);
;     });
	ds_write_b16_d16_hi v116, v48 offset:64
	v_bfe_u32 v50, v63, 16, 1
	v_add_u32_e32 v49, 0x110, v116
	v_add3_u32 v48, v63, v50, s78
	ds_write_b16_d16_hi v49, v48 offset:64
	v_or_b32_e32 v48, 32, v96
	v_add_u32_e32 v49, s90, v48
	v_cmp_lt_i32_e64 s[8:9], s76, v49
	v_bfe_u32 v50, v0, 16, 1
	v_add3_u32 v50, v0, v50, s78
	v_mul_lo_u32 v49, v48, s79
	v_lshl_add_u32 v48, v106, 1, v49
	ds_write_b16_d16_hi v48, v50
	v_add3_u32 v50, s90, v96, 33
	v_cmp_lt_i32_e64 s[10:11], s76, v50
	v_bfe_u32 v51, v1, 16, 1
	v_add3_u32 v51, v1, v51, s78
	v_add_u32_e32 v50, 0x110, v49
	v_lshl_add_u32 v49, v106, 1, v50
	ds_write_b16_d16_hi v49, v51
	v_add3_u32 v51, s90, v96, 34
	v_cmp_lt_i32_e64 s[12:13], s76, v51
	v_bfe_u32 v52, v2, 16, 1
	v_add3_u32 v52, v2, v52, s78
	v_add_u32_e32 v51, 0x110, v50
	v_lshl_add_u32 v50, v106, 1, v51
	ds_write_b16_d16_hi v50, v52
	v_add3_u32 v52, s90, v96, 35
	v_cmp_lt_i32_e64 s[14:15], s76, v52
	v_bfe_u32 v53, v3, 16, 1
	v_add3_u32 v53, v3, v53, s78
	v_add_u32_e32 v52, 0x110, v51
	v_lshl_add_u32 v51, v106, 1, v52
	ds_write_b16_d16_hi v51, v53
	v_add3_u32 v53, s90, v96, 40
	v_cmp_lt_i32_e64 s[16:17], s76, v53
	v_bfe_u32 v54, v4, 16, 1
	v_add3_u32 v54, v4, v54, s78
	v_add_u32_e32 v53, 0x550, v52
	v_lshl_add_u32 v52, v106, 1, v53
	ds_write_b16_d16_hi v52, v54
	v_add3_u32 v54, s90, v96, 41
	v_cmp_lt_i32_e64 s[18:19], s76, v54
	v_bfe_u32 v55, v5, 16, 1
	v_add3_u32 v55, v5, v55, s78
	v_add_u32_e32 v54, 0x110, v53
	v_lshl_add_u32 v53, v106, 1, v54
	ds_write_b16_d16_hi v53, v55
	v_add3_u32 v55, s90, v96, 42
	v_cmp_lt_i32_e64 s[20:21], s76, v55
	v_bfe_u32 v56, v6, 16, 1
	v_add3_u32 v56, v6, v56, s78
	v_add_u32_e32 v55, 0x110, v54
	v_lshl_add_u32 v54, v106, 1, v55
	ds_write_b16_d16_hi v54, v56
	v_add3_u32 v56, s90, v96, 43
	v_cmp_lt_i32_e64 s[22:23], s76, v56
	v_bfe_u32 v57, v7, 16, 1
	v_add_u32_e32 v55, 0x110, v55
	v_add3_u32 v57, v7, v57, s78
	v_lshl_add_u32 v56, v106, 1, v55
	ds_write_b16_d16_hi v56, v57
	v_add3_u32 v57, s90, v96, 48
	v_cmp_lt_i32_e64 s[24:25], s76, v57
	v_bfe_u32 v58, v8, 16, 1
	v_add_u32_e32 v55, 0x550, v55
	v_add3_u32 v58, v8, v58, s78
	v_lshl_add_u32 v57, v106, 1, v55
	ds_write_b16_d16_hi v57, v58
	v_add3_u32 v58, s90, v96, 49
	v_cmp_lt_i32_e64 s[26:27], s76, v58
	v_bfe_u32 v59, v9, 16, 1
	v_add_u32_e32 v55, 0x110, v55
	v_add3_u32 v59, v9, v59, s78
	v_lshl_add_u32 v58, v106, 1, v55
	ds_write_b16_d16_hi v58, v59
	v_add3_u32 v59, s90, v96, 50
	v_cmp_lt_i32_e64 s[28:29], s76, v59
	v_bfe_u32 v60, v10, 16, 1
	v_add_u32_e32 v55, 0x110, v55
	v_add3_u32 v60, v10, v60, s78
	v_lshl_add_u32 v59, v106, 1, v55
	ds_write_b16_d16_hi v59, v60
	v_add3_u32 v60, s90, v96, 51
	v_cmp_lt_i32_e64 s[30:31], s76, v60
	v_bfe_u32 v61, v11, 16, 1
	v_add_u32_e32 v55, 0x110, v55
	v_add3_u32 v61, v11, v61, s78
	v_lshl_add_u32 v60, v106, 1, v55
	ds_write_b16_d16_hi v60, v61
	v_add3_u32 v61, s90, v96, 56
	v_cmp_lt_i32_e64 s[34:35], s76, v61
	v_bfe_u32 v62, v12, 16, 1
	v_add_u32_e32 v55, 0x550, v55
	v_add3_u32 v62, v12, v62, s78
	v_lshl_add_u32 v61, v106, 1, v55
	ds_write_b16_d16_hi v61, v62
	v_add3_u32 v62, s90, v96, 57
	v_cmp_lt_i32_e64 s[36:37], s76, v62
	v_bfe_u32 v63, v13, 16, 1
	v_add_u32_e32 v55, 0x110, v55
	v_add3_u32 v63, v13, v63, s78
	v_lshl_add_u32 v62, v106, 1, v55
	ds_write_b16_d16_hi v62, v63
	v_add3_u32 v63, s90, v96, 58
	v_cmp_lt_i32_e64 s[38:39], s76, v63
	v_bfe_u32 v107, v14, 16, 1
	v_add_u32_e32 v55, 0x110, v55
	v_add3_u32 v63, v14, v107, s78
	v_lshl_add_u32 v55, v106, 1, v55
	ds_write_b16_d16_hi v55, v63
	v_add3_u32 v63, s90, v96, 59
	v_cmp_lt_i32_e64 s[40:41], s76, v63
	v_bfe_u32 v96, v15, 16, 1
	v_add3_u32 v63, v15, v96, s78
	ds_write_b16_d16_hi v55, v63 offset:272
	v_bfe_u32 v63, v32, 16, 1
	v_add3_u32 v32, v32, v63, s78
	ds_write_b16_d16_hi v48, v32 offset:64
	v_bfe_u32 v32, v33, 16, 1
	v_add3_u32 v32, v33, v32, s78
	ds_write_b16_d16_hi v49, v32 offset:64
	v_bfe_u32 v33, v34, 16, 1
	v_add3_u32 v32, v34, v33, s78
	ds_write_b16_d16_hi v50, v32 offset:64
	v_bfe_u32 v33, v35, 16, 1
	v_add3_u32 v32, v35, v33, s78
	ds_write_b16_d16_hi v51, v32 offset:64
	v_bfe_u32 v33, v36, 16, 1
	v_add3_u32 v32, v36, v33, s78
	ds_write_b16_d16_hi v52, v32 offset:64
	v_bfe_u32 v33, v37, 16, 1
	v_add3_u32 v32, v37, v33, s78
	ds_write_b16_d16_hi v53, v32 offset:64
	v_bfe_u32 v33, v38, 16, 1
	v_add3_u32 v32, v38, v33, s78
	ds_write_b16_d16_hi v54, v32 offset:64
	v_bfe_u32 v33, v39, 16, 1
	v_add3_u32 v32, v39, v33, s78
	ds_write_b16_d16_hi v56, v32 offset:64
	v_bfe_u32 v33, v40, 16, 1
	v_add3_u32 v32, v40, v33, s78
	ds_write_b16_d16_hi v57, v32 offset:64
	v_bfe_u32 v33, v41, 16, 1
	v_add3_u32 v32, v41, v33, s78
	ds_write_b16_d16_hi v58, v32 offset:64
	v_bfe_u32 v33, v42, 16, 1
	v_add3_u32 v32, v42, v33, s78
	ds_write_b16_d16_hi v59, v32 offset:64
	v_bfe_u32 v33, v43, 16, 1
	v_add3_u32 v32, v43, v33, s78
	ds_write_b16_d16_hi v60, v32 offset:64
	v_bfe_u32 v33, v44, 16, 1
	v_add3_u32 v32, v44, v33, s78
	ds_write_b16_d16_hi v61, v32 offset:64
	v_bfe_u32 v33, v45, 16, 1
	v_add3_u32 v32, v45, v33, s78
	ds_write_b16_d16_hi v62, v32 offset:64
	v_bfe_u32 v33, v46, 16, 1
	v_add3_u32 v32, v46, v33, s78
	ds_write_b16_d16_hi v55, v32 offset:64
	v_mov_b32_e32 v32, v47
	s_branch .LBB0_717

; __device__ __forceinline__ float sigmf(float x) { return 1.f / (1.f + __expf(-x)); }
; __device__ __forceinline__ float softplusf(float x) { return fmaxf(x, 0.f) + __logf(1.f + __expf(-fabsf(x))); }
; __device__ __forceinline__ void inproj_epilogue(const Params& p, int layer, int mt, int ntile, int tid,
;                                                 f32x16 (&acc)[2][2], unsigned char* smem) {
;     ...
;   const int m0 = mt * 128;
;   if (mode == 3) {
;     float* dt = (float*)(p.ws + OFF_DT) + (size_t)m0 * 16;
;     const float* bias = p.ssd_dt_bias + layer * 16;
;     acc_foreach(tid, acc, [&](int row, int col, float v) {
;       if (col < 16) *(dt + row * 16 + col) = softplusf(v + bias[col]);
;     });
;   } else {
;     bf16r* dstb = dst + (size_t)m0 * ld + c0;
;     bf16r* sT = (bf16r*)smem;
;     acc_foreach(tid, acc, [&](int row, int col, float v) {
;       int t = m0 + row;
;       float o = v;
;       if (mode == 1) o = (t >= NPADR) ? v : 0.f;
;       if (mode == 2) o = sigmf(v);
;       sT[row * 136 + col] = f2bf(o);
.LBB0_858:
	s_lshl_b32 s0, s6, 7
	s_ashr_i32 s1, s0, 31
	s_cmp_lg_u32 s7, 3
	s_mov_b64 s[4:5], -1
	s_cbranch_scc0 .LBB0_1052
	v_mov_b32_e32 v106, v108
	s_movk_i32 s4, 0xffc0
	v_lshrrev_b32_e32 v107, 3, v106
	v_ashrrev_i32_e32 v96, 1, v106
	v_and_b32_e32 v107, 4, v107
	v_and_or_b32 v96, v96, s4, v107
	s_cmp_eq_u32 s7, 1
	s_cselect_b64 s[4:5], -1, 0
	v_add_u32_e32 v107, s0, v96
	s_cmp_eq_u32 s7, 2
	s_cselect_b64 s[12:13], -1, 0
	s_cmp_lg_u32 s7, 2
	v_cmp_lt_i32_e64 s[8:9], s77, v107
	s_cbranch_scc0 .Lgv_2
	s_cmp_eq_u32 s7, 1
	s_cbranch_scc0 .Lfp_2

; __device__ __forceinline__ float sigmf(float x) { return 1.f / (1.f + __expf(-x)); }
; __device__ __forceinline__ bf16r f2bf(float f) {
;   unsigned u = __float_as_uint(f);
;   u += 0x7fffu + ((u >> 16) & 1u);
;   return (bf16r)(u >> 16);
; }
; __device__ __forceinline__ void inproj_epilogue(const Params& p, int layer, int mt, int ntile, int tid,
;                                                 f32x16 (&acc)[2][2], unsigned char* smem) {
;     ...
;     acc_foreach(tid, acc, [&](int row, int col, float v) {
;       int t = m0 + row;
;       float o = v;
;       if (mode == 1) o = (t >= NPADR) ? v : 0.f;
;       if (mode == 2) o = sigmf(v);
;       sT[row * 136 + col] = f2bf(o);
;     });
.Lfp_2:
	v_bfe_u32 v110, v16, 16, 1
	v_and_b32_e32 v106, 0x5f, v106
	v_add3_u32 v111, v16, v110, s79
	v_mul_lo_u32 v110, v96, s80
	v_lshl_add_u32 v107, v106, 1, v110
	ds_write_b16_d16_hi v107, v111
	v_add3_u32 v111, s0, v96, 1
	v_cmp_lt_i32_e64 s[10:11], s77, v111
	v_cndmask_b32_e64 v111, 0, 1, s[12:13]
	v_cmp_ne_u32_e64 s[6:7], 1, v111
	v_bfe_u32 v112, v17, 16, 1
	v_add3_u32 v112, v17, v112, s79
	v_add_u32_e32 v111, 0x110, v110
	v_lshl_add_u32 v110, v106, 1, v111
	ds_write_b16_d16_hi v110, v112
	v_add3_u32 v112, s0, v96, 2
	v_cmp_lt_i32_e64 s[12:13], s77, v112
	v_bfe_u32 v113, v18, 16, 1
	v_add3_u32 v113, v18, v113, s79
	v_add_u32_e32 v112, 0x110, v111
	v_lshl_add_u32 v111, v106, 1, v112
	ds_write_b16_d16_hi v111, v113
	v_add3_u32 v113, s0, v96, 3
	v_cmp_lt_i32_e64 s[14:15], s77, v113
	v_bfe_u32 v114, v19, 16, 1
	v_add3_u32 v114, v19, v114, s79
	v_add_u32_e32 v113, 0x110, v112
	v_lshl_add_u32 v112, v106, 1, v113
	ds_write_b16_d16_hi v112, v114
	v_add3_u32 v114, s0, v96, 8
	v_cmp_lt_i32_e64 s[16:17], s77, v114
	v_bfe_u32 v115, v20, 16, 1
	v_add3_u32 v115, v20, v115, s79
	v_add_u32_e32 v114, 0x550, v113
	v_lshl_add_u32 v113, v106, 1, v114
	ds_write_b16_d16_hi v113, v115
	v_add3_u32 v115, s0, v96, 9
	v_cmp_lt_i32_e64 s[18:19], s77, v115
	v_bfe_u32 v116, v21, 16, 1
	v_add3_u32 v116, v21, v116, s79
	v_add_u32_e32 v115, 0x110, v114
	v_lshl_add_u32 v114, v106, 1, v115
	ds_write_b16_d16_hi v114, v116
	v_add3_u32 v116, s0, v96, 10
	v_cmp_lt_i32_e64 s[20:21], s77, v116
	v_bfe_u32 v117, v22, 16, 1
	v_add3_u32 v117, v22, v117, s79
	v_add_u32_e32 v116, 0x110, v115
	v_lshl_add_u32 v115, v106, 1, v116
	ds_write_b16_d16_hi v115, v117
	v_add3_u32 v117, s0, v96, 11
	v_cmp_lt_i32_e64 s[22:23], s77, v117
	v_bfe_u32 v118, v23, 16, 1
	v_add_u32_e32 v116, 0x110, v116
	v_add3_u32 v118, v23, v118, s79
	v_lshl_add_u32 v117, v106, 1, v116
	ds_write_b16_d16_hi v117, v118
	v_add3_u32 v118, s0, v96, 16
	v_cmp_lt_i32_e64 s[24:25], s77, v118
	v_bfe_u32 v119, v24, 16, 1
	v_add_u32_e32 v116, 0x550, v116
	v_add3_u32 v119, v24, v119, s79
	v_lshl_add_u32 v118, v106, 1, v116
	ds_write_b16_d16_hi v118, v119
	v_add3_u32 v119, s0, v96, 17
	v_cmp_lt_i32_e64 s[26:27], s77, v119
	v_bfe_u32 v120, v25, 16, 1
	v_add_u32_e32 v116, 0x110, v116
	v_add3_u32 v120, v25, v120, s79
	v_lshl_add_u32 v119, v106, 1, v116
	ds_write_b16_d16_hi v119, v120
	v_add3_u32 v120, s0, v96, 18
	v_cmp_lt_i32_e64 s[28:29], s77, v120
	v_bfe_u32 v121, v26, 16, 1
	v_add_u32_e32 v116, 0x110, v116
	v_add3_u32 v121, v26, v121, s79
	v_lshl_add_u32 v120, v106, 1, v116
	ds_write_b16_d16_hi v120, v121
	v_add3_u32 v121, s0, v96, 19
	v_cmp_lt_i32_e64 s[30:31], s77, v121
	v_bfe_u32 v122, v27, 16, 1
	v_add_u32_e32 v116, 0x110, v116
	v_add3_u32 v122, v27, v122, s79
	v_lshl_add_u32 v121, v106, 1, v116
	ds_write_b16_d16_hi v121, v122
	v_add3_u32 v122, s0, v96, 24
	v_cmp_lt_i32_e64 s[34:35], s77, v122
	v_bfe_u32 v123, v28, 16, 1
	v_add_u32_e32 v116, 0x550, v116
	v_add3_u32 v123, v28, v123, s79
	v_lshl_add_u32 v122, v106, 1, v116
	ds_write_b16_d16_hi v122, v123
	v_add3_u32 v123, s0, v96, 25
	v_cmp_lt_i32_e64 s[36:37], s77, v123
	v_bfe_u32 v124, v29, 16, 1
	v_add_u32_e32 v116, 0x110, v116
	v_add3_u32 v124, v29, v124, s79
	v_lshl_add_u32 v123, v106, 1, v116
	ds_write_b16_d16_hi v123, v124
	v_add3_u32 v124, s0, v96, 26
	v_cmp_lt_i32_e64 s[38:39], s77, v124
	v_bfe_u32 v125, v30, 16, 1
	v_add_u32_e32 v116, 0x110, v116
	v_add3_u32 v124, v30, v125, s79
	v_lshl_add_u32 v116, v106, 1, v116
	ds_write_b16_d16_hi v116, v124
	v_add3_u32 v124, s0, v96, 27
	v_cmp_lt_i32_e64 s[40:41], s77, v124
	v_bfe_u32 v125, v31, 16, 1
	v_add3_u32 v124, v31, v125, s79
	ds_write_b16_d16_hi v116, v124 offset:272
	v_bfe_u32 v124, v48, 16, 1
	v_add3_u32 v48, v48, v124, s79
	ds_write_b16_d16_hi v107, v48 offset:64
	v_bfe_u32 v48, v49, 16, 1
	v_add3_u32 v48, v49, v48, s79
	ds_write_b16_d16_hi v110, v48 offset:64
	v_bfe_u32 v49, v50, 16, 1
	v_add3_u32 v48, v50, v49, s79
	ds_write_b16_d16_hi v111, v48 offset:64
	v_bfe_u32 v49, v51, 16, 1
	v_add3_u32 v48, v51, v49, s79
	ds_write_b16_d16_hi v112, v48 offset:64
	v_bfe_u32 v49, v52, 16, 1
	v_add3_u32 v48, v52, v49, s79
	ds_write_b16_d16_hi v113, v48 offset:64
	v_bfe_u32 v49, v53, 16, 1
	v_add3_u32 v48, v53, v49, s79
	ds_write_b16_d16_hi v114, v48 offset:64
	v_bfe_u32 v49, v54, 16, 1
	v_add3_u32 v48, v54, v49, s79
	ds_write_b16_d16_hi v115, v48 offset:64
	v_bfe_u32 v49, v55, 16, 1
	v_add3_u32 v48, v55, v49, s79
	ds_write_b16_d16_hi v117, v48 offset:64
	v_bfe_u32 v49, v56, 16, 1
	v_add3_u32 v48, v56, v49, s79
	ds_write_b16_d16_hi v118, v48 offset:64
	v_bfe_u32 v49, v57, 16, 1
	v_add3_u32 v48, v57, v49, s79
	ds_write_b16_d16_hi v119, v48 offset:64
	v_bfe_u32 v49, v58, 16, 1
	v_add3_u32 v48, v58, v49, s79
	ds_write_b16_d16_hi v120, v48 offset:64
	v_bfe_u32 v49, v59, 16, 1
	v_add3_u32 v48, v59, v49, s79
	ds_write_b16_d16_hi v121, v48 offset:64
	v_bfe_u32 v49, v60, 16, 1
	v_add3_u32 v48, v60, v49, s79
	ds_write_b16_d16_hi v122, v48 offset:64
	v_bfe_u32 v49, v61, 16, 1
	v_add3_u32 v48, v61, v49, s79
	ds_write_b16_d16_hi v123, v48 offset:64
	v_bfe_u32 v49, v62, 16, 1
	v_add3_u32 v48, v62, v49, s79
; __device__ __forceinline__ float sigmf(float x) { return 1.f / (1.f + __expf(-x)); }
; __device__ __forceinline__ bf16r f2bf(float f) {
;   unsigned u = __float_as_uint(f);
;   u += 0x7fffu + ((u >> 16) & 1u);
;   return (bf16r)(u >> 16);
; }
; __device__ __forceinline__ void inproj_epilogue(const Params& p, int layer, int mt, int ntile, int tid,
;                                                 f32x16 (&acc)[2][2], unsigned char* smem) {
;     ...
;     acc_foreach(tid, acc, [&](int row, int col, float v) {
;       int t = m0 + row;
;       float o = v;
;       if (mode == 1) o = (t >= NPADR) ? v : 0.f;
;       if (mode == 2) o = sigmf(v);
;       sT[row * 136 + col] = f2bf(o);
;     });
	ds_write_b16_d16_hi v116, v48 offset:64
	v_bfe_u32 v50, v63, 16, 1
	v_add_u32_e32 v49, 0x110, v116
	v_add3_u32 v48, v63, v50, s79
	ds_write_b16_d16_hi v49, v48 offset:64
	v_or_b32_e32 v48, 32, v96
	v_add_u32_e32 v49, s0, v48
	v_cmp_lt_i32_e64 s[8:9], s77, v49
	v_bfe_u32 v50, v0, 16, 1
	v_add3_u32 v50, v0, v50, s79
	v_mul_lo_u32 v49, v48, s80
	v_lshl_add_u32 v48, v106, 1, v49
	ds_write_b16_d16_hi v48, v50
	v_add3_u32 v50, s0, v96, 33
	v_cmp_lt_i32_e64 s[10:11], s77, v50
	v_bfe_u32 v51, v1, 16, 1
	v_add3_u32 v51, v1, v51, s79
	v_add_u32_e32 v50, 0x110, v49
	v_lshl_add_u32 v49, v106, 1, v50
	ds_write_b16_d16_hi v49, v51
	v_add3_u32 v51, s0, v96, 34
	v_cmp_lt_i32_e64 s[12:13], s77, v51
	v_bfe_u32 v52, v2, 16, 1
	v_add3_u32 v52, v2, v52, s79
	v_add_u32_e32 v51, 0x110, v50
	v_lshl_add_u32 v50, v106, 1, v51
	ds_write_b16_d16_hi v50, v52
	v_add3_u32 v52, s0, v96, 35
	v_cmp_lt_i32_e64 s[14:15], s77, v52
	v_bfe_u32 v53, v3, 16, 1
	v_add3_u32 v53, v3, v53, s79
	v_add_u32_e32 v52, 0x110, v51
	v_lshl_add_u32 v51, v106, 1, v52
	ds_write_b16_d16_hi v51, v53
	v_add3_u32 v53, s0, v96, 40
	v_cmp_lt_i32_e64 s[16:17], s77, v53
	v_bfe_u32 v54, v4, 16, 1
	v_add3_u32 v54, v4, v54, s79
	v_add_u32_e32 v53, 0x550, v52
	v_lshl_add_u32 v52, v106, 1, v53
	ds_write_b16_d16_hi v52, v54
	v_add3_u32 v54, s0, v96, 41
	v_cmp_lt_i32_e64 s[18:19], s77, v54
	v_bfe_u32 v55, v5, 16, 1
	v_add3_u32 v55, v5, v55, s79
	v_add_u32_e32 v54, 0x110, v53
	v_lshl_add_u32 v53, v106, 1, v54
	ds_write_b16_d16_hi v53, v55
	v_add3_u32 v55, s0, v96, 42
	v_cmp_lt_i32_e64 s[20:21], s77, v55
	v_bfe_u32 v56, v6, 16, 1
	v_add3_u32 v56, v6, v56, s79
	v_add_u32_e32 v55, 0x110, v54
	v_lshl_add_u32 v54, v106, 1, v55
	ds_write_b16_d16_hi v54, v56
	v_add3_u32 v56, s0, v96, 43
	v_cmp_lt_i32_e64 s[22:23], s77, v56
	v_bfe_u32 v57, v7, 16, 1
	v_add_u32_e32 v55, 0x110, v55
	v_add3_u32 v57, v7, v57, s79
	v_lshl_add_u32 v56, v106, 1, v55
	ds_write_b16_d16_hi v56, v57
	v_add3_u32 v57, s0, v96, 48
	v_cmp_lt_i32_e64 s[24:25], s77, v57
	v_bfe_u32 v58, v8, 16, 1
	v_add_u32_e32 v55, 0x550, v55
	v_add3_u32 v58, v8, v58, s79
	v_lshl_add_u32 v57, v106, 1, v55
	ds_write_b16_d16_hi v57, v58
	v_add3_u32 v58, s0, v96, 49
	v_cmp_lt_i32_e64 s[26:27], s77, v58
	v_bfe_u32 v59, v9, 16, 1
	v_add_u32_e32 v55, 0x110, v55
	v_add3_u32 v59, v9, v59, s79
	v_lshl_add_u32 v58, v106, 1, v55
	ds_write_b16_d16_hi v58, v59
	v_add3_u32 v59, s0, v96, 50
	v_cmp_lt_i32_e64 s[28:29], s77, v59
	v_bfe_u32 v60, v10, 16, 1
	v_add_u32_e32 v55, 0x110, v55
	v_add3_u32 v60, v10, v60, s79
	v_lshl_add_u32 v59, v106, 1, v55
	ds_write_b16_d16_hi v59, v60
	v_add3_u32 v60, s0, v96, 51
	v_cmp_lt_i32_e64 s[30:31], s77, v60
	v_bfe_u32 v61, v11, 16, 1
	v_add_u32_e32 v55, 0x110, v55
	v_add3_u32 v61, v11, v61, s79
	v_lshl_add_u32 v60, v106, 1, v55
	ds_write_b16_d16_hi v60, v61
	v_add3_u32 v61, s0, v96, 56
	v_cmp_lt_i32_e64 s[34:35], s77, v61
	v_bfe_u32 v62, v12, 16, 1
	v_add_u32_e32 v55, 0x550, v55
	v_add3_u32 v62, v12, v62, s79
	v_lshl_add_u32 v61, v106, 1, v55
	ds_write_b16_d16_hi v61, v62
	v_add3_u32 v62, s0, v96, 57
	v_cmp_lt_i32_e64 s[36:37], s77, v62
	v_bfe_u32 v63, v13, 16, 1
	v_add_u32_e32 v55, 0x110, v55
	v_add3_u32 v63, v13, v63, s79
	v_lshl_add_u32 v62, v106, 1, v55
	ds_write_b16_d16_hi v62, v63
	v_add3_u32 v63, s0, v96, 58
	v_cmp_lt_i32_e64 s[38:39], s77, v63
	v_bfe_u32 v107, v14, 16, 1
	v_add_u32_e32 v55, 0x110, v55
	v_add3_u32 v63, v14, v107, s79
	v_lshl_add_u32 v55, v106, 1, v55
	ds_write_b16_d16_hi v55, v63
	v_add3_u32 v63, s0, v96, 59
	v_cmp_lt_i32_e64 s[40:41], s77, v63
	v_bfe_u32 v96, v15, 16, 1
	v_add3_u32 v63, v15, v96, s79
	ds_write_b16_d16_hi v55, v63 offset:272
	v_bfe_u32 v63, v32, 16, 1
	v_add3_u32 v32, v32, v63, s79
	ds_write_b16_d16_hi v48, v32 offset:64
	v_bfe_u32 v32, v33, 16, 1
	v_add3_u32 v32, v33, v32, s79
	ds_write_b16_d16_hi v49, v32 offset:64
	v_bfe_u32 v33, v34, 16, 1
	v_add3_u32 v32, v34, v33, s79
	ds_write_b16_d16_hi v50, v32 offset:64
	v_bfe_u32 v33, v35, 16, 1
	v_add3_u32 v32, v35, v33, s79
	ds_write_b16_d16_hi v51, v32 offset:64
	v_bfe_u32 v33, v36, 16, 1
	v_add3_u32 v32, v36, v33, s79
	ds_write_b16_d16_hi v52, v32 offset:64
	v_bfe_u32 v33, v37, 16, 1
	v_add3_u32 v32, v37, v33, s79
	ds_write_b16_d16_hi v53, v32 offset:64
	v_bfe_u32 v33, v38, 16, 1
	v_add3_u32 v32, v38, v33, s79
	ds_write_b16_d16_hi v54, v32 offset:64
	v_bfe_u32 v33, v39, 16, 1
	v_add3_u32 v32, v39, v33, s79
	ds_write_b16_d16_hi v56, v32 offset:64
	v_bfe_u32 v33, v40, 16, 1
	v_add3_u32 v32, v40, v33, s79
	ds_write_b16_d16_hi v57, v32 offset:64
	v_bfe_u32 v33, v41, 16, 1
	v_add3_u32 v32, v41, v33, s79
	ds_write_b16_d16_hi v58, v32 offset:64
	v_bfe_u32 v33, v42, 16, 1
	v_add3_u32 v32, v42, v33, s79
	ds_write_b16_d16_hi v59, v32 offset:64
	v_bfe_u32 v33, v43, 16, 1
	v_add3_u32 v32, v43, v33, s79
	ds_write_b16_d16_hi v60, v32 offset:64
	v_bfe_u32 v33, v44, 16, 1
	v_add3_u32 v32, v44, v33, s79
	ds_write_b16_d16_hi v61, v32 offset:64
	v_bfe_u32 v33, v45, 16, 1
	v_add3_u32 v32, v45, v33, s79
	ds_write_b16_d16_hi v62, v32 offset:64
	v_bfe_u32 v33, v46, 16, 1
	v_add3_u32 v32, v46, v33, s79
	ds_write_b16_d16_hi v55, v32 offset:64
	v_mov_b32_e32 v32, v47
	s_branch .LBB0_1051

; __device__ __forceinline__ float sigmf(float x) { return 1.f / (1.f + __expf(-x)); }
; __device__ __forceinline__ float softplusf(float x) { return fmaxf(x, 0.f) + __logf(1.f + __expf(-fabsf(x))); }
; __device__ __forceinline__ void inproj_epilogue(const Params& p, int layer, int mt, int ntile, int tid,
;                                                 f32x16 (&acc)[2][2], unsigned char* smem) {
;     ...
;   const int m0 = mt * 128;
;   if (mode == 3) {
;     float* dt = (float*)(p.ws + OFF_DT) + (size_t)m0 * 16;
;     const float* bias = p.ssd_dt_bias + layer * 16;
;     acc_foreach(tid, acc, [&](int row, int col, float v) {
;       if (col < 16) *(dt + row * 16 + col) = softplusf(v + bias[col]);
;     });
;   } else {
;     bf16r* dstb = dst + (size_t)m0 * ld + c0;
;     bf16r* sT = (bf16r*)smem;
;     acc_foreach(tid, acc, [&](int row, int col, float v) {
;       int t = m0 + row;
;       float o = v;
;       if (mode == 1) o = (t >= NPADR) ? v : 0.f;
;       if (mode == 2) o = sigmf(v);
;       sT[row * 136 + col] = f2bf(o);
.LBB0_1642:
	s_lshl_b32 s96, s6, 7
	s_ashr_i32 s97, s96, 31
	s_cmp_lg_u32 s7, 3
	s_mov_b64 s[4:5], -1
	s_cbranch_scc0 .LBB0_1836
	v_mov_b32_e32 v106, v108
	s_movk_i32 s4, 0xffc0
	v_lshrrev_b32_e32 v107, 3, v106
	v_ashrrev_i32_e32 v96, 1, v106
	v_and_b32_e32 v107, 4, v107
	v_and_or_b32 v96, v96, s4, v107
	s_cmp_eq_u32 s7, 1
	s_cselect_b64 s[4:5], -1, 0
	v_add_u32_e32 v107, s96, v96
	s_cmp_eq_u32 s7, 2
	s_cselect_b64 s[12:13], -1, 0
	s_cmp_lg_u32 s7, 2
	v_cmp_lt_i32_e64 s[8:9], s76, v107
	s_cbranch_scc0 .Lgv_3
	s_cmp_eq_u32 s7, 1
	s_cbranch_scc0 .Lfp_3

; __device__ __forceinline__ float sigmf(float x) { return 1.f / (1.f + __expf(-x)); }
; __device__ __forceinline__ bf16r f2bf(float f) {
;   unsigned u = __float_as_uint(f);
;   u += 0x7fffu + ((u >> 16) & 1u);
;   return (bf16r)(u >> 16);
; }
; __device__ __forceinline__ void inproj_epilogue(const Params& p, int layer, int mt, int ntile, int tid,
;                                                 f32x16 (&acc)[2][2], unsigned char* smem) {
;     ...
;     acc_foreach(tid, acc, [&](int row, int col, float v) {
;       int t = m0 + row;
;       float o = v;
;       if (mode == 1) o = (t >= NPADR) ? v : 0.f;
;       if (mode == 2) o = sigmf(v);
;       sT[row * 136 + col] = f2bf(o);
;     });
.Lfp_3:
	v_bfe_u32 v110, v16, 16, 1
	v_and_b32_e32 v106, 0x5f, v106
	v_add3_u32 v111, v16, v110, s78
	v_mul_lo_u32 v110, v96, s79
	v_lshl_add_u32 v107, v106, 1, v110
	ds_write_b16_d16_hi v107, v111
	v_add3_u32 v111, s96, v96, 1
	v_cmp_lt_i32_e64 s[10:11], s76, v111
	v_cndmask_b32_e64 v111, 0, 1, s[12:13]
	v_cmp_ne_u32_e64 s[6:7], 1, v111
	v_bfe_u32 v112, v17, 16, 1
	v_add3_u32 v112, v17, v112, s78
	v_add_u32_e32 v111, 0x110, v110
	v_lshl_add_u32 v110, v106, 1, v111
	ds_write_b16_d16_hi v110, v112
	v_add3_u32 v112, s96, v96, 2
	v_cmp_lt_i32_e64 s[12:13], s76, v112
	v_bfe_u32 v113, v18, 16, 1
	v_add3_u32 v113, v18, v113, s78
	v_add_u32_e32 v112, 0x110, v111
	v_lshl_add_u32 v111, v106, 1, v112
	ds_write_b16_d16_hi v111, v113
	v_add3_u32 v113, s96, v96, 3
	v_cmp_lt_i32_e64 s[14:15], s76, v113
	v_bfe_u32 v114, v19, 16, 1
	v_add3_u32 v114, v19, v114, s78
	v_add_u32_e32 v113, 0x110, v112
	v_lshl_add_u32 v112, v106, 1, v113
	ds_write_b16_d16_hi v112, v114
	v_add3_u32 v114, s96, v96, 8
	v_cmp_lt_i32_e64 s[16:17], s76, v114
	v_bfe_u32 v115, v20, 16, 1
	v_add3_u32 v115, v20, v115, s78
	v_add_u32_e32 v114, 0x550, v113
	v_lshl_add_u32 v113, v106, 1, v114
	ds_write_b16_d16_hi v113, v115
	v_add3_u32 v115, s96, v96, 9
	v_cmp_lt_i32_e64 s[18:19], s76, v115
	v_bfe_u32 v116, v21, 16, 1
	v_add3_u32 v116, v21, v116, s78
	v_add_u32_e32 v115, 0x110, v114
	v_lshl_add_u32 v114, v106, 1, v115
	ds_write_b16_d16_hi v114, v116
	v_add3_u32 v116, s96, v96, 10
	v_cmp_lt_i32_e64 s[20:21], s76, v116
	v_bfe_u32 v117, v22, 16, 1
	v_add3_u32 v117, v22, v117, s78
	v_add_u32_e32 v116, 0x110, v115
	v_lshl_add_u32 v115, v106, 1, v116
	ds_write_b16_d16_hi v115, v117
	v_add3_u32 v117, s96, v96, 11
	v_cmp_lt_i32_e64 s[22:23], s76, v117
	v_bfe_u32 v118, v23, 16, 1
	v_add_u32_e32 v116, 0x110, v116
	v_add3_u32 v118, v23, v118, s78
	v_lshl_add_u32 v117, v106, 1, v116
	ds_write_b16_d16_hi v117, v118
	v_add3_u32 v118, s96, v96, 16
	v_cmp_lt_i32_e64 s[24:25], s76, v118
	v_bfe_u32 v119, v24, 16, 1
	v_add_u32_e32 v116, 0x550, v116
	v_add3_u32 v119, v24, v119, s78
	v_lshl_add_u32 v118, v106, 1, v116
	ds_write_b16_d16_hi v118, v119
	v_add3_u32 v119, s96, v96, 17
	v_cmp_lt_i32_e64 s[26:27], s76, v119
	v_bfe_u32 v120, v25, 16, 1
	v_add_u32_e32 v116, 0x110, v116
	v_add3_u32 v120, v25, v120, s78
	v_lshl_add_u32 v119, v106, 1, v116
	ds_write_b16_d16_hi v119, v120
	v_add3_u32 v120, s96, v96, 18
	v_cmp_lt_i32_e64 s[28:29], s76, v120
	v_bfe_u32 v121, v26, 16, 1
	v_add_u32_e32 v116, 0x110, v116
	v_add3_u32 v121, v26, v121, s78
	v_lshl_add_u32 v120, v106, 1, v116
	ds_write_b16_d16_hi v120, v121
	v_add3_u32 v121, s96, v96, 19
	v_cmp_lt_i32_e64 s[30:31], s76, v121
	v_bfe_u32 v122, v27, 16, 1
	v_add_u32_e32 v116, 0x110, v116
	v_add3_u32 v122, v27, v122, s78
	v_lshl_add_u32 v121, v106, 1, v116
	ds_write_b16_d16_hi v121, v122
	v_add3_u32 v122, s96, v96, 24
	v_cmp_lt_i32_e64 s[34:35], s76, v122
	v_bfe_u32 v123, v28, 16, 1
	v_add_u32_e32 v116, 0x550, v116
	v_add3_u32 v123, v28, v123, s78
	v_lshl_add_u32 v122, v106, 1, v116
	ds_write_b16_d16_hi v122, v123
	v_add3_u32 v123, s96, v96, 25
	v_cmp_lt_i32_e64 s[36:37], s76, v123
	v_bfe_u32 v124, v29, 16, 1
	v_add_u32_e32 v116, 0x110, v116
	v_add3_u32 v124, v29, v124, s78
	v_lshl_add_u32 v123, v106, 1, v116
	ds_write_b16_d16_hi v123, v124
	v_add3_u32 v124, s96, v96, 26
	v_cmp_lt_i32_e64 s[38:39], s76, v124
	v_bfe_u32 v125, v30, 16, 1
	v_add_u32_e32 v116, 0x110, v116
	v_add3_u32 v124, v30, v125, s78
	v_lshl_add_u32 v116, v106, 1, v116
	ds_write_b16_d16_hi v116, v124
	v_add3_u32 v124, s96, v96, 27
	v_cmp_lt_i32_e64 s[40:41], s76, v124
	v_bfe_u32 v125, v31, 16, 1
	v_add3_u32 v124, v31, v125, s78
	ds_write_b16_d16_hi v116, v124 offset:272
	v_bfe_u32 v124, v48, 16, 1
	v_add3_u32 v48, v48, v124, s78
	ds_write_b16_d16_hi v107, v48 offset:64
	v_bfe_u32 v48, v49, 16, 1
	v_add3_u32 v48, v49, v48, s78
	ds_write_b16_d16_hi v110, v48 offset:64
	v_bfe_u32 v49, v50, 16, 1
	v_add3_u32 v48, v50, v49, s78
	ds_write_b16_d16_hi v111, v48 offset:64
	v_bfe_u32 v49, v51, 16, 1
	v_add3_u32 v48, v51, v49, s78
	ds_write_b16_d16_hi v112, v48 offset:64
	v_bfe_u32 v49, v52, 16, 1
	v_add3_u32 v48, v52, v49, s78
	ds_write_b16_d16_hi v113, v48 offset:64
	v_bfe_u32 v49, v53, 16, 1
	v_add3_u32 v48, v53, v49, s78
	ds_write_b16_d16_hi v114, v48 offset:64
	v_bfe_u32 v49, v54, 16, 1
	v_add3_u32 v48, v54, v49, s78
	ds_write_b16_d16_hi v115, v48 offset:64
	v_bfe_u32 v49, v55, 16, 1
	v_add3_u32 v48, v55, v49, s78
	ds_write_b16_d16_hi v117, v48 offset:64
	v_bfe_u32 v49, v56, 16, 1
	v_add3_u32 v48, v56, v49, s78
	ds_write_b16_d16_hi v118, v48 offset:64
	v_bfe_u32 v49, v57, 16, 1
	v_add3_u32 v48, v57, v49, s78
	ds_write_b16_d16_hi v119, v48 offset:64
	v_bfe_u32 v49, v58, 16, 1
	v_add3_u32 v48, v58, v49, s78
	ds_write_b16_d16_hi v120, v48 offset:64
	v_bfe_u32 v49, v59, 16, 1
	v_add3_u32 v48, v59, v49, s78
	ds_write_b16_d16_hi v121, v48 offset:64
	v_bfe_u32 v49, v60, 16, 1
	v_add3_u32 v48, v60, v49, s78
	ds_write_b16_d16_hi v122, v48 offset:64
	v_bfe_u32 v49, v61, 16, 1
	v_add3_u32 v48, v61, v49, s78
	ds_write_b16_d16_hi v123, v48 offset:64
	v_bfe_u32 v49, v62, 16, 1
	v_add3_u32 v48, v62, v49, s78
; __device__ __forceinline__ float sigmf(float x) { return 1.f / (1.f + __expf(-x)); }
; __device__ __forceinline__ bf16r f2bf(float f) {
;   unsigned u = __float_as_uint(f);
;   u += 0x7fffu + ((u >> 16) & 1u);
;   return (bf16r)(u >> 16);
; }
; __device__ __forceinline__ void inproj_epilogue(const Params& p, int layer, int mt, int ntile, int tid,
;                                                 f32x16 (&acc)[2][2], unsigned char* smem) {
;     ...
;     acc_foreach(tid, acc, [&](int row, int col, float v) {
;       int t = m0 + row;
;       float o = v;
;       if (mode == 1) o = (t >= NPADR) ? v : 0.f;
;       if (mode == 2) o = sigmf(v);
;       sT[row * 136 + col] = f2bf(o);
;     });
	ds_write_b16_d16_hi v116, v48 offset:64
	v_bfe_u32 v50, v63, 16, 1
	v_add_u32_e32 v49, 0x110, v116
	v_add3_u32 v48, v63, v50, s78
	ds_write_b16_d16_hi v49, v48 offset:64
	v_or_b32_e32 v48, 32, v96
	v_add_u32_e32 v49, s96, v48
	v_cmp_lt_i32_e64 s[8:9], s76, v49
	v_bfe_u32 v50, v0, 16, 1
	v_add3_u32 v50, v0, v50, s78
	v_mul_lo_u32 v49, v48, s79
	v_lshl_add_u32 v48, v106, 1, v49
	ds_write_b16_d16_hi v48, v50
	v_add3_u32 v50, s96, v96, 33
	v_cmp_lt_i32_e64 s[10:11], s76, v50
	v_bfe_u32 v51, v1, 16, 1
	v_add3_u32 v51, v1, v51, s78
	v_add_u32_e32 v50, 0x110, v49
	v_lshl_add_u32 v49, v106, 1, v50
	ds_write_b16_d16_hi v49, v51
	v_add3_u32 v51, s96, v96, 34
	v_cmp_lt_i32_e64 s[12:13], s76, v51
	v_bfe_u32 v52, v2, 16, 1
	v_add3_u32 v52, v2, v52, s78
	v_add_u32_e32 v51, 0x110, v50
	v_lshl_add_u32 v50, v106, 1, v51
	ds_write_b16_d16_hi v50, v52
	v_add3_u32 v52, s96, v96, 35
	v_cmp_lt_i32_e64 s[14:15], s76, v52
	v_bfe_u32 v53, v3, 16, 1
	v_add3_u32 v53, v3, v53, s78
	v_add_u32_e32 v52, 0x110, v51
	v_lshl_add_u32 v51, v106, 1, v52
	ds_write_b16_d16_hi v51, v53
	v_add3_u32 v53, s96, v96, 40
	v_cmp_lt_i32_e64 s[16:17], s76, v53
	v_bfe_u32 v54, v4, 16, 1
	v_add3_u32 v54, v4, v54, s78
	v_add_u32_e32 v53, 0x550, v52
	v_lshl_add_u32 v52, v106, 1, v53
	ds_write_b16_d16_hi v52, v54
	v_add3_u32 v54, s96, v96, 41
	v_cmp_lt_i32_e64 s[18:19], s76, v54
	v_bfe_u32 v55, v5, 16, 1
	v_add3_u32 v55, v5, v55, s78
	v_add_u32_e32 v54, 0x110, v53
	v_lshl_add_u32 v53, v106, 1, v54
	ds_write_b16_d16_hi v53, v55
	v_add3_u32 v55, s96, v96, 42
	v_cmp_lt_i32_e64 s[20:21], s76, v55
	v_bfe_u32 v56, v6, 16, 1
	v_add3_u32 v56, v6, v56, s78
	v_add_u32_e32 v55, 0x110, v54
	v_lshl_add_u32 v54, v106, 1, v55
	ds_write_b16_d16_hi v54, v56
	v_add3_u32 v56, s96, v96, 43
	v_cmp_lt_i32_e64 s[22:23], s76, v56
	v_bfe_u32 v57, v7, 16, 1
	v_add_u32_e32 v55, 0x110, v55
	v_add3_u32 v57, v7, v57, s78
	v_lshl_add_u32 v56, v106, 1, v55
	ds_write_b16_d16_hi v56, v57
	v_add3_u32 v57, s96, v96, 48
	v_cmp_lt_i32_e64 s[24:25], s76, v57
	v_bfe_u32 v58, v8, 16, 1
	v_add_u32_e32 v55, 0x550, v55
	v_add3_u32 v58, v8, v58, s78
	v_lshl_add_u32 v57, v106, 1, v55
	ds_write_b16_d16_hi v57, v58
	v_add3_u32 v58, s96, v96, 49
	v_cmp_lt_i32_e64 s[26:27], s76, v58
	v_bfe_u32 v59, v9, 16, 1
	v_add_u32_e32 v55, 0x110, v55
	v_add3_u32 v59, v9, v59, s78
	v_lshl_add_u32 v58, v106, 1, v55
	ds_write_b16_d16_hi v58, v59
	v_add3_u32 v59, s96, v96, 50
	v_cmp_lt_i32_e64 s[28:29], s76, v59
	v_bfe_u32 v60, v10, 16, 1
	v_add_u32_e32 v55, 0x110, v55
	v_add3_u32 v60, v10, v60, s78
	v_lshl_add_u32 v59, v106, 1, v55
	ds_write_b16_d16_hi v59, v60
	v_add3_u32 v60, s96, v96, 51
	v_cmp_lt_i32_e64 s[30:31], s76, v60
	v_bfe_u32 v61, v11, 16, 1
	v_add_u32_e32 v55, 0x110, v55
	v_add3_u32 v61, v11, v61, s78
	v_lshl_add_u32 v60, v106, 1, v55
	ds_write_b16_d16_hi v60, v61
	v_add3_u32 v61, s96, v96, 56
	v_cmp_lt_i32_e64 s[34:35], s76, v61
	v_bfe_u32 v62, v12, 16, 1
	v_add_u32_e32 v55, 0x550, v55
	v_add3_u32 v62, v12, v62, s78
	v_lshl_add_u32 v61, v106, 1, v55
	ds_write_b16_d16_hi v61, v62
	v_add3_u32 v62, s96, v96, 57
	v_cmp_lt_i32_e64 s[36:37], s76, v62
	v_bfe_u32 v63, v13, 16, 1
	v_add_u32_e32 v55, 0x110, v55
	v_add3_u32 v63, v13, v63, s78
	v_lshl_add_u32 v62, v106, 1, v55
	ds_write_b16_d16_hi v62, v63
	v_add3_u32 v63, s96, v96, 58
	v_cmp_lt_i32_e64 s[38:39], s76, v63
	v_bfe_u32 v107, v14, 16, 1
	v_add_u32_e32 v55, 0x110, v55
	v_add3_u32 v63, v14, v107, s78
	v_lshl_add_u32 v55, v106, 1, v55
	ds_write_b16_d16_hi v55, v63
	v_add3_u32 v63, s96, v96, 59
	v_cmp_lt_i32_e64 s[40:41], s76, v63
	v_bfe_u32 v96, v15, 16, 1
	v_add3_u32 v63, v15, v96, s78
	ds_write_b16_d16_hi v55, v63 offset:272
	v_bfe_u32 v63, v32, 16, 1
	v_add3_u32 v32, v32, v63, s78
	ds_write_b16_d16_hi v48, v32 offset:64
	v_bfe_u32 v32, v33, 16, 1
	v_add3_u32 v32, v33, v32, s78
	ds_write_b16_d16_hi v49, v32 offset:64
	v_bfe_u32 v33, v34, 16, 1
	v_add3_u32 v32, v34, v33, s78
	ds_write_b16_d16_hi v50, v32 offset:64
	v_bfe_u32 v33, v35, 16, 1
	v_add3_u32 v32, v35, v33, s78
	ds_write_b16_d16_hi v51, v32 offset:64
	v_bfe_u32 v33, v36, 16, 1
	v_add3_u32 v32, v36, v33, s78
	ds_write_b16_d16_hi v52, v32 offset:64
	v_bfe_u32 v33, v37, 16, 1
	v_add3_u32 v32, v37, v33, s78
	ds_write_b16_d16_hi v53, v32 offset:64
	v_bfe_u32 v33, v38, 16, 1
	v_add3_u32 v32, v38, v33, s78
	ds_write_b16_d16_hi v54, v32 offset:64
	v_bfe_u32 v33, v39, 16, 1
	v_add3_u32 v32, v39, v33, s78
	ds_write_b16_d16_hi v56, v32 offset:64
	v_bfe_u32 v33, v40, 16, 1
	v_add3_u32 v32, v40, v33, s78
	ds_write_b16_d16_hi v57, v32 offset:64
	v_bfe_u32 v33, v41, 16, 1
	v_add3_u32 v32, v41, v33, s78
	ds_write_b16_d16_hi v58, v32 offset:64
	v_bfe_u32 v33, v42, 16, 1
	v_add3_u32 v32, v42, v33, s78
	ds_write_b16_d16_hi v59, v32 offset:64
	v_bfe_u32 v33, v43, 16, 1
	v_add3_u32 v32, v43, v33, s78
	ds_write_b16_d16_hi v60, v32 offset:64
	v_bfe_u32 v33, v44, 16, 1
	v_add3_u32 v32, v44, v33, s78
	ds_write_b16_d16_hi v61, v32 offset:64
	v_bfe_u32 v33, v45, 16, 1
	v_add3_u32 v32, v45, v33, s78
	ds_write_b16_d16_hi v62, v32 offset:64
	v_bfe_u32 v33, v46, 16, 1
	v_add3_u32 v32, v46, v33, s78
	ds_write_b16_d16_hi v55, v32 offset:64
	v_mov_b32_e32 v32, v47
	s_branch .LBB0_1835

; __device__ __forceinline__ float sigmf(float x) { return 1.f / (1.f + __expf(-x)); }
; __device__ __forceinline__ float softplusf(float x) { return fmaxf(x, 0.f) + __logf(1.f + __expf(-fabsf(x))); }
; __device__ __forceinline__ void inproj_epilogue(const Params& p, int layer, int mt, int ntile, int tid,
;                                                 f32x16 (&acc)[2][2], unsigned char* smem) {
;     ...
;   const int m0 = mt * 128;
;   if (mode == 3) {
;     float* dt = (float*)(p.ws + OFF_DT) + (size_t)m0 * 16;
;     const float* bias = p.ssd_dt_bias + layer * 16;
;     acc_foreach(tid, acc, [&](int row, int col, float v) {
;       if (col < 16) *(dt + row * 16 + col) = softplusf(v + bias[col]);
;     });
;   } else {
;     bf16r* dstb = dst + (size_t)m0 * ld + c0;
;     bf16r* sT = (bf16r*)smem;
;     acc_foreach(tid, acc, [&](int row, int col, float v) {
;       int t = m0 + row;
;       float o = v;
;       if (mode == 1) o = (t >= NPADR) ? v : 0.f;
;       if (mode == 2) o = sigmf(v);
;       sT[row * 136 + col] = f2bf(o);
.LBB0_2033:
	s_lshl_b32 s84, s6, 7
	s_ashr_i32 s85, s84, 31
	s_cmp_lg_u32 s7, 3
	s_mov_b64 s[4:5], -1
	s_cbranch_scc0 .LBB0_2227
	v_mov_b32_e32 v106, v108
	s_movk_i32 s4, 0xffc0
	v_lshrrev_b32_e32 v107, 3, v106
	v_ashrrev_i32_e32 v96, 1, v106
	v_and_b32_e32 v107, 4, v107
	v_and_or_b32 v96, v96, s4, v107
	s_cmp_eq_u32 s7, 1
	s_cselect_b64 s[4:5], -1, 0
	v_add_u32_e32 v107, s84, v96
	s_cmp_eq_u32 s7, 2
	s_cselect_b64 s[12:13], -1, 0
	s_cmp_lg_u32 s7, 2
	v_cmp_lt_i32_e64 s[8:9], s76, v107
	s_cbranch_scc0 .Lgv_4
	s_cmp_eq_u32 s7, 1
	s_cbranch_scc0 .Lfp_4

; __device__ __forceinline__ float sigmf(float x) { return 1.f / (1.f + __expf(-x)); }
; __device__ __forceinline__ bf16r f2bf(float f) {
;   unsigned u = __float_as_uint(f);
;   u += 0x7fffu + ((u >> 16) & 1u);
;   return (bf16r)(u >> 16);
; }
; __device__ __forceinline__ void inproj_epilogue(const Params& p, int layer, int mt, int ntile, int tid,
;                                                 f32x16 (&acc)[2][2], unsigned char* smem) {
;     ...
;     acc_foreach(tid, acc, [&](int row, int col, float v) {
;       int t = m0 + row;
;       float o = v;
;       if (mode == 1) o = (t >= NPADR) ? v : 0.f;
;       if (mode == 2) o = sigmf(v);
;       sT[row * 136 + col] = f2bf(o);
;     });
.Lfp_4:
	v_bfe_u32 v110, v16, 16, 1
	v_and_b32_e32 v106, 0x5f, v106
	v_add3_u32 v111, v16, v110, s78
	v_mul_lo_u32 v110, v96, s79
	v_lshl_add_u32 v107, v106, 1, v110
	ds_write_b16_d16_hi v107, v111
	v_add3_u32 v111, s84, v96, 1
	v_cmp_lt_i32_e64 s[10:11], s76, v111
	v_cndmask_b32_e64 v111, 0, 1, s[12:13]
	v_cmp_ne_u32_e64 s[6:7], 1, v111
	v_bfe_u32 v112, v17, 16, 1
	v_add3_u32 v112, v17, v112, s78
	v_add_u32_e32 v111, 0x110, v110
	v_lshl_add_u32 v110, v106, 1, v111
	ds_write_b16_d16_hi v110, v112
	v_add3_u32 v112, s84, v96, 2
	v_cmp_lt_i32_e64 s[12:13], s76, v112
	v_bfe_u32 v113, v18, 16, 1
	v_add3_u32 v113, v18, v113, s78
	v_add_u32_e32 v112, 0x110, v111
	v_lshl_add_u32 v111, v106, 1, v112
	ds_write_b16_d16_hi v111, v113
	v_add3_u32 v113, s84, v96, 3
	v_cmp_lt_i32_e64 s[14:15], s76, v113
	v_bfe_u32 v114, v19, 16, 1
	v_add3_u32 v114, v19, v114, s78
	v_add_u32_e32 v113, 0x110, v112
	v_lshl_add_u32 v112, v106, 1, v113
	ds_write_b16_d16_hi v112, v114
	v_add3_u32 v114, s84, v96, 8
	v_cmp_lt_i32_e64 s[16:17], s76, v114
	v_bfe_u32 v115, v20, 16, 1
	v_add3_u32 v115, v20, v115, s78
	v_add_u32_e32 v114, 0x550, v113
	v_lshl_add_u32 v113, v106, 1, v114
	ds_write_b16_d16_hi v113, v115
	v_add3_u32 v115, s84, v96, 9
	v_cmp_lt_i32_e64 s[18:19], s76, v115
	v_bfe_u32 v116, v21, 16, 1
	v_add3_u32 v116, v21, v116, s78
	v_add_u32_e32 v115, 0x110, v114
	v_lshl_add_u32 v114, v106, 1, v115
	ds_write_b16_d16_hi v114, v116
	v_add3_u32 v116, s84, v96, 10
	v_cmp_lt_i32_e64 s[20:21], s76, v116
	v_bfe_u32 v117, v22, 16, 1
	v_add3_u32 v117, v22, v117, s78
	v_add_u32_e32 v116, 0x110, v115
	v_lshl_add_u32 v115, v106, 1, v116
	ds_write_b16_d16_hi v115, v117
	v_add3_u32 v117, s84, v96, 11
	v_cmp_lt_i32_e64 s[22:23], s76, v117
	v_bfe_u32 v118, v23, 16, 1
	v_add_u32_e32 v116, 0x110, v116
	v_add3_u32 v118, v23, v118, s78
	v_lshl_add_u32 v117, v106, 1, v116
	ds_write_b16_d16_hi v117, v118
	v_add3_u32 v118, s84, v96, 16
	v_cmp_lt_i32_e64 s[24:25], s76, v118
	v_bfe_u32 v119, v24, 16, 1
	v_add_u32_e32 v116, 0x550, v116
	v_add3_u32 v119, v24, v119, s78
	v_lshl_add_u32 v118, v106, 1, v116
	ds_write_b16_d16_hi v118, v119
	v_add3_u32 v119, s84, v96, 17
	v_cmp_lt_i32_e64 s[26:27], s76, v119
	v_bfe_u32 v120, v25, 16, 1
	v_add_u32_e32 v116, 0x110, v116
	v_add3_u32 v120, v25, v120, s78
	v_lshl_add_u32 v119, v106, 1, v116
	ds_write_b16_d16_hi v119, v120
	v_add3_u32 v120, s84, v96, 18
	v_cmp_lt_i32_e64 s[28:29], s76, v120
	v_bfe_u32 v121, v26, 16, 1
	v_add_u32_e32 v116, 0x110, v116
	v_add3_u32 v121, v26, v121, s78
	v_lshl_add_u32 v120, v106, 1, v116
	ds_write_b16_d16_hi v120, v121
	v_add3_u32 v121, s84, v96, 19
	v_cmp_lt_i32_e64 s[30:31], s76, v121
	v_bfe_u32 v122, v27, 16, 1
	v_add_u32_e32 v116, 0x110, v116
	v_add3_u32 v122, v27, v122, s78
	v_lshl_add_u32 v121, v106, 1, v116
	ds_write_b16_d16_hi v121, v122
	v_add3_u32 v122, s84, v96, 24
	v_cmp_lt_i32_e64 s[34:35], s76, v122
	v_bfe_u32 v123, v28, 16, 1
	v_add_u32_e32 v116, 0x550, v116
	v_add3_u32 v123, v28, v123, s78
	v_lshl_add_u32 v122, v106, 1, v116
	ds_write_b16_d16_hi v122, v123
	v_add3_u32 v123, s84, v96, 25
	v_cmp_lt_i32_e64 s[36:37], s76, v123
	v_bfe_u32 v124, v29, 16, 1
	v_add_u32_e32 v116, 0x110, v116
	v_add3_u32 v124, v29, v124, s78
	v_lshl_add_u32 v123, v106, 1, v116
	ds_write_b16_d16_hi v123, v124
	v_add3_u32 v124, s84, v96, 26
	v_cmp_lt_i32_e64 s[38:39], s76, v124
	v_bfe_u32 v125, v30, 16, 1
	v_add_u32_e32 v116, 0x110, v116
	v_add3_u32 v124, v30, v125, s78
	v_lshl_add_u32 v116, v106, 1, v116
	ds_write_b16_d16_hi v116, v124
	v_add3_u32 v124, s84, v96, 27
	v_cmp_lt_i32_e64 s[40:41], s76, v124
	v_bfe_u32 v125, v31, 16, 1
	v_add3_u32 v124, v31, v125, s78
	ds_write_b16_d16_hi v116, v124 offset:272
	v_bfe_u32 v124, v48, 16, 1
	v_add3_u32 v48, v48, v124, s78
	ds_write_b16_d16_hi v107, v48 offset:64
	v_bfe_u32 v48, v49, 16, 1
	v_add3_u32 v48, v49, v48, s78
	ds_write_b16_d16_hi v110, v48 offset:64
	v_bfe_u32 v49, v50, 16, 1
	v_add3_u32 v48, v50, v49, s78
	ds_write_b16_d16_hi v111, v48 offset:64
	v_bfe_u32 v49, v51, 16, 1
	v_add3_u32 v48, v51, v49, s78
	ds_write_b16_d16_hi v112, v48 offset:64
	v_bfe_u32 v49, v52, 16, 1
	v_add3_u32 v48, v52, v49, s78
	ds_write_b16_d16_hi v113, v48 offset:64
	v_bfe_u32 v49, v53, 16, 1
	v_add3_u32 v48, v53, v49, s78
	ds_write_b16_d16_hi v114, v48 offset:64
	v_bfe_u32 v49, v54, 16, 1
	v_add3_u32 v48, v54, v49, s78
	ds_write_b16_d16_hi v115, v48 offset:64
	v_bfe_u32 v49, v55, 16, 1
	v_add3_u32 v48, v55, v49, s78
	ds_write_b16_d16_hi v117, v48 offset:64
	v_bfe_u32 v49, v56, 16, 1
	v_add3_u32 v48, v56, v49, s78
	ds_write_b16_d16_hi v118, v48 offset:64
	v_bfe_u32 v49, v57, 16, 1
	v_add3_u32 v48, v57, v49, s78
	ds_write_b16_d16_hi v119, v48 offset:64
	v_bfe_u32 v49, v58, 16, 1
	v_add3_u32 v48, v58, v49, s78
	ds_write_b16_d16_hi v120, v48 offset:64
	v_bfe_u32 v49, v59, 16, 1
	v_add3_u32 v48, v59, v49, s78
	ds_write_b16_d16_hi v121, v48 offset:64
	v_bfe_u32 v49, v60, 16, 1
	v_add3_u32 v48, v60, v49, s78
	ds_write_b16_d16_hi v122, v48 offset:64
	v_bfe_u32 v49, v61, 16, 1
	v_add3_u32 v48, v61, v49, s78
	ds_write_b16_d16_hi v123, v48 offset:64
	v_bfe_u32 v49, v62, 16, 1
	v_add3_u32 v48, v62, v49, s78
; __device__ __forceinline__ float sigmf(float x) { return 1.f / (1.f + __expf(-x)); }
; __device__ __forceinline__ bf16r f2bf(float f) {
;   unsigned u = __float_as_uint(f);
;   u += 0x7fffu + ((u >> 16) & 1u);
;   return (bf16r)(u >> 16);
; }
; __device__ __forceinline__ void inproj_epilogue(const Params& p, int layer, int mt, int ntile, int tid,
;                                                 f32x16 (&acc)[2][2], unsigned char* smem) {
;     ...
;     acc_foreach(tid, acc, [&](int row, int col, float v) {
;       int t = m0 + row;
;       float o = v;
;       if (mode == 1) o = (t >= NPADR) ? v : 0.f;
;       if (mode == 2) o = sigmf(v);
;       sT[row * 136 + col] = f2bf(o);
;     });
	ds_write_b16_d16_hi v116, v48 offset:64
	v_bfe_u32 v50, v63, 16, 1
	v_add_u32_e32 v49, 0x110, v116
	v_add3_u32 v48, v63, v50, s78
	ds_write_b16_d16_hi v49, v48 offset:64
	v_or_b32_e32 v48, 32, v96
	v_add_u32_e32 v49, s84, v48
	v_cmp_lt_i32_e64 s[8:9], s76, v49
	v_bfe_u32 v50, v0, 16, 1
	v_add3_u32 v50, v0, v50, s78
	v_mul_lo_u32 v49, v48, s79
	v_lshl_add_u32 v48, v106, 1, v49
	ds_write_b16_d16_hi v48, v50
	v_add3_u32 v50, s84, v96, 33
	v_cmp_lt_i32_e64 s[10:11], s76, v50
	v_bfe_u32 v51, v1, 16, 1
	v_add3_u32 v51, v1, v51, s78
	v_add_u32_e32 v50, 0x110, v49
	v_lshl_add_u32 v49, v106, 1, v50
	ds_write_b16_d16_hi v49, v51
	v_add3_u32 v51, s84, v96, 34
	v_cmp_lt_i32_e64 s[12:13], s76, v51
	v_bfe_u32 v52, v2, 16, 1
	v_add3_u32 v52, v2, v52, s78
	v_add_u32_e32 v51, 0x110, v50
	v_lshl_add_u32 v50, v106, 1, v51
	ds_write_b16_d16_hi v50, v52
	v_add3_u32 v52, s84, v96, 35
	v_cmp_lt_i32_e64 s[14:15], s76, v52
	v_bfe_u32 v53, v3, 16, 1
	v_add3_u32 v53, v3, v53, s78
	v_add_u32_e32 v52, 0x110, v51
	v_lshl_add_u32 v51, v106, 1, v52
	ds_write_b16_d16_hi v51, v53
	v_add3_u32 v53, s84, v96, 40
	v_cmp_lt_i32_e64 s[16:17], s76, v53
	v_bfe_u32 v54, v4, 16, 1
	v_add3_u32 v54, v4, v54, s78
	v_add_u32_e32 v53, 0x550, v52
	v_lshl_add_u32 v52, v106, 1, v53
	ds_write_b16_d16_hi v52, v54
	v_add3_u32 v54, s84, v96, 41
	v_cmp_lt_i32_e64 s[18:19], s76, v54
	v_bfe_u32 v55, v5, 16, 1
	v_add3_u32 v55, v5, v55, s78
	v_add_u32_e32 v54, 0x110, v53
	v_lshl_add_u32 v53, v106, 1, v54
	ds_write_b16_d16_hi v53, v55
	v_add3_u32 v55, s84, v96, 42
	v_cmp_lt_i32_e64 s[20:21], s76, v55
	v_bfe_u32 v56, v6, 16, 1
	v_add3_u32 v56, v6, v56, s78
	v_add_u32_e32 v55, 0x110, v54
	v_lshl_add_u32 v54, v106, 1, v55
	ds_write_b16_d16_hi v54, v56
	v_add3_u32 v56, s84, v96, 43
	v_cmp_lt_i32_e64 s[22:23], s76, v56
	v_bfe_u32 v57, v7, 16, 1
	v_add_u32_e32 v55, 0x110, v55
	v_add3_u32 v57, v7, v57, s78
	v_lshl_add_u32 v56, v106, 1, v55
	ds_write_b16_d16_hi v56, v57
	v_add3_u32 v57, s84, v96, 48
	v_cmp_lt_i32_e64 s[24:25], s76, v57
	v_bfe_u32 v58, v8, 16, 1
	v_add_u32_e32 v55, 0x550, v55
	v_add3_u32 v58, v8, v58, s78
	v_lshl_add_u32 v57, v106, 1, v55
	ds_write_b16_d16_hi v57, v58
	v_add3_u32 v58, s84, v96, 49
	v_cmp_lt_i32_e64 s[26:27], s76, v58
	v_bfe_u32 v59, v9, 16, 1
	v_add_u32_e32 v55, 0x110, v55
	v_add3_u32 v59, v9, v59, s78
	v_lshl_add_u32 v58, v106, 1, v55
	ds_write_b16_d16_hi v58, v59
	v_add3_u32 v59, s84, v96, 50
	v_cmp_lt_i32_e64 s[28:29], s76, v59
	v_bfe_u32 v60, v10, 16, 1
	v_add_u32_e32 v55, 0x110, v55
	v_add3_u32 v60, v10, v60, s78
	v_lshl_add_u32 v59, v106, 1, v55
	ds_write_b16_d16_hi v59, v60
	v_add3_u32 v60, s84, v96, 51
	v_cmp_lt_i32_e64 s[30:31], s76, v60
	v_bfe_u32 v61, v11, 16, 1
	v_add_u32_e32 v55, 0x110, v55
	v_add3_u32 v61, v11, v61, s78
	v_lshl_add_u32 v60, v106, 1, v55
	ds_write_b16_d16_hi v60, v61
	v_add3_u32 v61, s84, v96, 56
	v_cmp_lt_i32_e64 s[34:35], s76, v61
	v_bfe_u32 v62, v12, 16, 1
	v_add_u32_e32 v55, 0x550, v55
	v_add3_u32 v62, v12, v62, s78
	v_lshl_add_u32 v61, v106, 1, v55
	ds_write_b16_d16_hi v61, v62
	v_add3_u32 v62, s84, v96, 57
	v_cmp_lt_i32_e64 s[36:37], s76, v62
	v_bfe_u32 v63, v13, 16, 1
	v_add_u32_e32 v55, 0x110, v55
	v_add3_u32 v63, v13, v63, s78
	v_lshl_add_u32 v62, v106, 1, v55
	ds_write_b16_d16_hi v62, v63
	v_add3_u32 v63, s84, v96, 58
	v_cmp_lt_i32_e64 s[38:39], s76, v63
	v_bfe_u32 v107, v14, 16, 1
	v_add_u32_e32 v55, 0x110, v55
	v_add3_u32 v63, v14, v107, s78
	v_lshl_add_u32 v55, v106, 1, v55
	ds_write_b16_d16_hi v55, v63
	v_add3_u32 v63, s84, v96, 59
	v_cmp_lt_i32_e64 s[40:41], s76, v63
	v_bfe_u32 v96, v15, 16, 1
	v_add3_u32 v63, v15, v96, s78
	ds_write_b16_d16_hi v55, v63 offset:272
	v_bfe_u32 v63, v32, 16, 1
	v_add3_u32 v32, v32, v63, s78
	ds_write_b16_d16_hi v48, v32 offset:64
	v_bfe_u32 v32, v33, 16, 1
	v_add3_u32 v32, v33, v32, s78
	ds_write_b16_d16_hi v49, v32 offset:64
	v_bfe_u32 v33, v34, 16, 1
	v_add3_u32 v32, v34, v33, s78
	ds_write_b16_d16_hi v50, v32 offset:64
	v_bfe_u32 v33, v35, 16, 1
	v_add3_u32 v32, v35, v33, s78
	ds_write_b16_d16_hi v51, v32 offset:64
	v_bfe_u32 v33, v36, 16, 1
	v_add3_u32 v32, v36, v33, s78
	ds_write_b16_d16_hi v52, v32 offset:64
	v_bfe_u32 v33, v37, 16, 1
	v_add3_u32 v32, v37, v33, s78
	ds_write_b16_d16_hi v53, v32 offset:64
	v_bfe_u32 v33, v38, 16, 1
	v_add3_u32 v32, v38, v33, s78
	ds_write_b16_d16_hi v54, v32 offset:64
	v_bfe_u32 v33, v39, 16, 1
	v_add3_u32 v32, v39, v33, s78
	ds_write_b16_d16_hi v56, v32 offset:64
	v_bfe_u32 v33, v40, 16, 1
	v_add3_u32 v32, v40, v33, s78
	ds_write_b16_d16_hi v57, v32 offset:64
	v_bfe_u32 v33, v41, 16, 1
	v_add3_u32 v32, v41, v33, s78
	ds_write_b16_d16_hi v58, v32 offset:64
	v_bfe_u32 v33, v42, 16, 1
	v_add3_u32 v32, v42, v33, s78
	ds_write_b16_d16_hi v59, v32 offset:64
	v_bfe_u32 v33, v43, 16, 1
	v_add3_u32 v32, v43, v33, s78
	ds_write_b16_d16_hi v60, v32 offset:64
	v_bfe_u32 v33, v44, 16, 1
	v_add3_u32 v32, v44, v33, s78
	ds_write_b16_d16_hi v61, v32 offset:64
	v_bfe_u32 v33, v45, 16, 1
	v_add3_u32 v32, v45, v33, s78
	ds_write_b16_d16_hi v62, v32 offset:64
	v_bfe_u32 v33, v46, 16, 1
	v_add3_u32 v32, v46, v33, s78
	ds_write_b16_d16_hi v55, v32 offset:64
	v_mov_b32_e32 v32, v47
	s_branch .LBB0_2226

; __device__ __forceinline__ float sigmf(float x) { return 1.f / (1.f + __expf(-x)); }
; __device__ __forceinline__ float softplusf(float x) { return fmaxf(x, 0.f) + __logf(1.f + __expf(-fabsf(x))); }
; __device__ __forceinline__ void inproj_epilogue(const Params& p, int layer, int mt, int ntile, int tid,
;                                                 f32x16 (&acc)[2][2], unsigned char* smem) {
;     ...
;   const int m0 = mt * 128;
;   if (mode == 3) {
;     float* dt = (float*)(p.ws + OFF_DT) + (size_t)m0 * 16;
;     const float* bias = p.ssd_dt_bias + layer * 16;
;     acc_foreach(tid, acc, [&](int row, int col, float v) {
;       if (col < 16) *(dt + row * 16 + col) = softplusf(v + bias[col]);
;     });
;   } else {
;     bf16r* dstb = dst + (size_t)m0 * ld + c0;
;     bf16r* sT = (bf16r*)smem;
;     acc_foreach(tid, acc, [&](int row, int col, float v) {
;       int t = m0 + row;
;       float o = v;
;       if (mode == 1) o = (t >= NPADR) ? v : 0.f;
;       if (mode == 2) o = sigmf(v);
;       sT[row * 136 + col] = f2bf(o);
.LBB0_2713:
	s_lshl_b32 s96, s6, 7
	s_ashr_i32 s97, s96, 31
	s_cmp_lg_u32 s7, 3
	s_mov_b64 s[4:5], -1
	s_cbranch_scc0 .LBB0_2907
	v_mov_b32_e32 v106, v108
	s_movk_i32 s4, 0xffc0
	v_lshrrev_b32_e32 v107, 3, v106
	v_ashrrev_i32_e32 v96, 1, v106
	v_and_b32_e32 v107, 4, v107
	v_and_or_b32 v96, v96, s4, v107
	s_cmp_eq_u32 s7, 1
	s_cselect_b64 s[4:5], -1, 0
	v_add_u32_e32 v107, s96, v96
	s_cmp_eq_u32 s7, 2
	s_cselect_b64 s[10:11], -1, 0
	s_cmp_lg_u32 s7, 2
	v_cmp_lt_i32_e64 s[8:9], s79, v107
	s_cbranch_scc0 .Lgv_5
	s_cmp_eq_u32 s7, 1
	s_cbranch_scc0 .Lfp_5

; __device__ __forceinline__ float sigmf(float x) { return 1.f / (1.f + __expf(-x)); }
; __device__ __forceinline__ bf16r f2bf(float f) {
;   unsigned u = __float_as_uint(f);
;   u += 0x7fffu + ((u >> 16) & 1u);
;   return (bf16r)(u >> 16);
; }
; __device__ __forceinline__ void inproj_epilogue(const Params& p, int layer, int mt, int ntile, int tid,
;                                                 f32x16 (&acc)[2][2], unsigned char* smem) {
;     ...
;     acc_foreach(tid, acc, [&](int row, int col, float v) {
;       int t = m0 + row;
;       float o = v;
;       if (mode == 1) o = (t >= NPADR) ? v : 0.f;
;       if (mode == 2) o = sigmf(v);
;       sT[row * 136 + col] = f2bf(o);
;     });
.Lfp_5:
	v_bfe_u32 v110, v16, 16, 1
	v_and_b32_e32 v106, 0x5f, v106
	v_add3_u32 v111, v16, v110, s81
	v_mul_lo_u32 v110, v96, s82
	v_lshl_add_u32 v107, v106, 1, v110
	ds_write_b16_d16_hi v107, v111
	v_add3_u32 v111, s96, v96, 1
	v_cndmask_b32_e64 v112, 0, 1, s[10:11]
	v_cmp_ne_u32_e64 s[6:7], 1, v112
	v_cmp_lt_i32_e64 s[10:11], s79, v111
	v_bfe_u32 v112, v17, 16, 1
	v_add3_u32 v112, v17, v112, s81
	v_add_u32_e32 v111, 0x110, v110
	v_lshl_add_u32 v110, v106, 1, v111
	ds_write_b16_d16_hi v110, v112
	v_add3_u32 v112, s96, v96, 2
	v_cmp_lt_i32_e64 s[12:13], s79, v112
	v_bfe_u32 v113, v18, 16, 1
	v_add3_u32 v113, v18, v113, s81
	v_add_u32_e32 v112, 0x110, v111
	v_lshl_add_u32 v111, v106, 1, v112
	ds_write_b16_d16_hi v111, v113
	v_add3_u32 v113, s96, v96, 3
	v_cmp_lt_i32_e64 s[14:15], s79, v113
	v_bfe_u32 v114, v19, 16, 1
	v_add3_u32 v114, v19, v114, s81
	v_add_u32_e32 v113, 0x110, v112
	v_lshl_add_u32 v112, v106, 1, v113
	ds_write_b16_d16_hi v112, v114
	v_add3_u32 v114, s96, v96, 8
	v_cmp_lt_i32_e64 s[16:17], s79, v114
	v_bfe_u32 v115, v20, 16, 1
	v_add3_u32 v115, v20, v115, s81
	v_add_u32_e32 v114, 0x550, v113
	v_lshl_add_u32 v113, v106, 1, v114
	ds_write_b16_d16_hi v113, v115
	v_add3_u32 v115, s96, v96, 9
	v_cmp_lt_i32_e64 s[18:19], s79, v115
	v_bfe_u32 v116, v21, 16, 1
	v_add3_u32 v116, v21, v116, s81
	v_add_u32_e32 v115, 0x110, v114
	v_lshl_add_u32 v114, v106, 1, v115
	ds_write_b16_d16_hi v114, v116
	v_add3_u32 v116, s96, v96, 10
	v_cmp_lt_i32_e64 s[20:21], s79, v116
	v_bfe_u32 v117, v22, 16, 1
	v_add3_u32 v117, v22, v117, s81
	v_add_u32_e32 v116, 0x110, v115
	v_lshl_add_u32 v115, v106, 1, v116
	ds_write_b16_d16_hi v115, v117
	v_add3_u32 v117, s96, v96, 11
	v_cmp_lt_i32_e64 s[22:23], s79, v117
	v_bfe_u32 v118, v23, 16, 1
	v_add_u32_e32 v116, 0x110, v116
	v_add3_u32 v118, v23, v118, s81
	v_lshl_add_u32 v117, v106, 1, v116
	ds_write_b16_d16_hi v117, v118
	v_add3_u32 v118, s96, v96, 16
	v_cmp_lt_i32_e64 s[24:25], s79, v118
	v_bfe_u32 v119, v24, 16, 1
	v_add_u32_e32 v116, 0x550, v116
	v_add3_u32 v119, v24, v119, s81
	v_lshl_add_u32 v118, v106, 1, v116
	ds_write_b16_d16_hi v118, v119
	v_add3_u32 v119, s96, v96, 17
	v_cmp_lt_i32_e64 s[26:27], s79, v119
	v_bfe_u32 v120, v25, 16, 1
	v_add_u32_e32 v116, 0x110, v116
	v_add3_u32 v120, v25, v120, s81
	v_lshl_add_u32 v119, v106, 1, v116
	ds_write_b16_d16_hi v119, v120
	v_add3_u32 v120, s96, v96, 18
	v_cmp_lt_i32_e64 s[28:29], s79, v120
	v_bfe_u32 v121, v26, 16, 1
	v_add_u32_e32 v116, 0x110, v116
	v_add3_u32 v121, v26, v121, s81
	v_lshl_add_u32 v120, v106, 1, v116
	ds_write_b16_d16_hi v120, v121
	v_add3_u32 v121, s96, v96, 19
	v_cmp_lt_i32_e64 s[30:31], s79, v121
	v_bfe_u32 v122, v27, 16, 1
	v_add_u32_e32 v116, 0x110, v116
	v_add3_u32 v122, v27, v122, s81
	v_lshl_add_u32 v121, v106, 1, v116
	ds_write_b16_d16_hi v121, v122
	v_add3_u32 v122, s96, v96, 24
	v_cmp_lt_i32_e64 s[34:35], s79, v122
	v_bfe_u32 v123, v28, 16, 1
	v_add_u32_e32 v116, 0x550, v116
	v_add3_u32 v123, v28, v123, s81
	v_lshl_add_u32 v122, v106, 1, v116
	ds_write_b16_d16_hi v122, v123
	v_add3_u32 v123, s96, v96, 25
	v_cmp_lt_i32_e64 s[36:37], s79, v123
	v_bfe_u32 v124, v29, 16, 1
	v_add_u32_e32 v116, 0x110, v116
	v_add3_u32 v124, v29, v124, s81
	v_lshl_add_u32 v123, v106, 1, v116
	ds_write_b16_d16_hi v123, v124
	v_add3_u32 v124, s96, v96, 26
	v_cmp_lt_i32_e64 s[38:39], s79, v124
	v_bfe_u32 v125, v30, 16, 1
	v_add_u32_e32 v116, 0x110, v116
	v_add3_u32 v124, v30, v125, s81
	v_lshl_add_u32 v116, v106, 1, v116
	ds_write_b16_d16_hi v116, v124
	v_add3_u32 v124, s96, v96, 27
	v_cmp_lt_i32_e64 s[40:41], s79, v124
	v_bfe_u32 v125, v31, 16, 1
	v_add3_u32 v124, v31, v125, s81
	ds_write_b16_d16_hi v116, v124 offset:272
	v_bfe_u32 v124, v48, 16, 1
	v_add3_u32 v48, v48, v124, s81
	ds_write_b16_d16_hi v107, v48 offset:64
	v_bfe_u32 v48, v49, 16, 1
	v_add3_u32 v48, v49, v48, s81
	ds_write_b16_d16_hi v110, v48 offset:64
	v_bfe_u32 v49, v50, 16, 1
	v_add3_u32 v48, v50, v49, s81
	ds_write_b16_d16_hi v111, v48 offset:64
	v_bfe_u32 v49, v51, 16, 1
	v_add3_u32 v48, v51, v49, s81
	ds_write_b16_d16_hi v112, v48 offset:64
	v_bfe_u32 v49, v52, 16, 1
	v_add3_u32 v48, v52, v49, s81
	ds_write_b16_d16_hi v113, v48 offset:64
	v_bfe_u32 v49, v53, 16, 1
	v_add3_u32 v48, v53, v49, s81
	ds_write_b16_d16_hi v114, v48 offset:64
	v_bfe_u32 v49, v54, 16, 1
	v_add3_u32 v48, v54, v49, s81
	ds_write_b16_d16_hi v115, v48 offset:64
	v_bfe_u32 v49, v55, 16, 1
	v_add3_u32 v48, v55, v49, s81
	ds_write_b16_d16_hi v117, v48 offset:64
	v_bfe_u32 v49, v56, 16, 1
	v_add3_u32 v48, v56, v49, s81
	ds_write_b16_d16_hi v118, v48 offset:64
	v_bfe_u32 v49, v57, 16, 1
	v_add3_u32 v48, v57, v49, s81
	ds_write_b16_d16_hi v119, v48 offset:64
	v_bfe_u32 v49, v58, 16, 1
	v_add3_u32 v48, v58, v49, s81
	ds_write_b16_d16_hi v120, v48 offset:64
	v_bfe_u32 v49, v59, 16, 1
	v_add3_u32 v48, v59, v49, s81
	ds_write_b16_d16_hi v121, v48 offset:64
	v_bfe_u32 v49, v60, 16, 1
	v_add3_u32 v48, v60, v49, s81
	ds_write_b16_d16_hi v122, v48 offset:64
	v_bfe_u32 v49, v61, 16, 1
	v_add3_u32 v48, v61, v49, s81
	ds_write_b16_d16_hi v123, v48 offset:64
	v_bfe_u32 v49, v62, 16, 1
	v_add3_u32 v48, v62, v49, s81
; __device__ __forceinline__ float sigmf(float x) { return 1.f / (1.f + __expf(-x)); }
; __device__ __forceinline__ bf16r f2bf(float f) {
;   unsigned u = __float_as_uint(f);
;   u += 0x7fffu + ((u >> 16) & 1u);
;   return (bf16r)(u >> 16);
; }
; __device__ __forceinline__ void inproj_epilogue(const Params& p, int layer, int mt, int ntile, int tid,
;                                                 f32x16 (&acc)[2][2], unsigned char* smem) {
;     ...
;     acc_foreach(tid, acc, [&](int row, int col, float v) {
;       int t = m0 + row;
;       float o = v;
;       if (mode == 1) o = (t >= NPADR) ? v : 0.f;
;       if (mode == 2) o = sigmf(v);
;       sT[row * 136 + col] = f2bf(o);
;     });
	ds_write_b16_d16_hi v116, v48 offset:64
	v_bfe_u32 v50, v63, 16, 1
	v_add_u32_e32 v49, 0x110, v116
	v_add3_u32 v48, v63, v50, s81
	ds_write_b16_d16_hi v49, v48 offset:64
	v_or_b32_e32 v48, 32, v96
	v_add_u32_e32 v49, s96, v48
	v_cmp_lt_i32_e64 s[8:9], s79, v49
	v_bfe_u32 v50, v0, 16, 1
	v_add3_u32 v50, v0, v50, s81
	v_mul_lo_u32 v49, v48, s82
	v_lshl_add_u32 v48, v106, 1, v49
	ds_write_b16_d16_hi v48, v50
	v_add3_u32 v50, s96, v96, 33
	v_cmp_lt_i32_e64 s[10:11], s79, v50
	v_bfe_u32 v51, v1, 16, 1
	v_add3_u32 v51, v1, v51, s81
	v_add_u32_e32 v50, 0x110, v49
	v_lshl_add_u32 v49, v106, 1, v50
	ds_write_b16_d16_hi v49, v51
	v_add3_u32 v51, s96, v96, 34
	v_cmp_lt_i32_e64 s[12:13], s79, v51
	v_bfe_u32 v52, v2, 16, 1
	v_add3_u32 v52, v2, v52, s81
	v_add_u32_e32 v51, 0x110, v50
	v_lshl_add_u32 v50, v106, 1, v51
	ds_write_b16_d16_hi v50, v52
	v_add3_u32 v52, s96, v96, 35
	v_cmp_lt_i32_e64 s[14:15], s79, v52
	v_bfe_u32 v53, v3, 16, 1
	v_add3_u32 v53, v3, v53, s81
	v_add_u32_e32 v52, 0x110, v51
	v_lshl_add_u32 v51, v106, 1, v52
	ds_write_b16_d16_hi v51, v53
	v_add3_u32 v53, s96, v96, 40
	v_cmp_lt_i32_e64 s[16:17], s79, v53
	v_bfe_u32 v54, v4, 16, 1
	v_add3_u32 v54, v4, v54, s81
	v_add_u32_e32 v53, 0x550, v52
	v_lshl_add_u32 v52, v106, 1, v53
	ds_write_b16_d16_hi v52, v54
	v_add3_u32 v54, s96, v96, 41
	v_cmp_lt_i32_e64 s[18:19], s79, v54
	v_bfe_u32 v55, v5, 16, 1
	v_add3_u32 v55, v5, v55, s81
	v_add_u32_e32 v54, 0x110, v53
	v_lshl_add_u32 v53, v106, 1, v54
	ds_write_b16_d16_hi v53, v55
	v_add3_u32 v55, s96, v96, 42
	v_cmp_lt_i32_e64 s[20:21], s79, v55
	v_bfe_u32 v56, v6, 16, 1
	v_add3_u32 v56, v6, v56, s81
	v_add_u32_e32 v55, 0x110, v54
	v_lshl_add_u32 v54, v106, 1, v55
	ds_write_b16_d16_hi v54, v56
	v_add3_u32 v56, s96, v96, 43
	v_cmp_lt_i32_e64 s[22:23], s79, v56
	v_bfe_u32 v57, v7, 16, 1
	v_add_u32_e32 v55, 0x110, v55
	v_add3_u32 v57, v7, v57, s81
	v_lshl_add_u32 v56, v106, 1, v55
	ds_write_b16_d16_hi v56, v57
	v_add3_u32 v57, s96, v96, 48
	v_cmp_lt_i32_e64 s[24:25], s79, v57
	v_bfe_u32 v58, v8, 16, 1
	v_add_u32_e32 v55, 0x550, v55
	v_add3_u32 v58, v8, v58, s81
	v_lshl_add_u32 v57, v106, 1, v55
	ds_write_b16_d16_hi v57, v58
	v_add3_u32 v58, s96, v96, 49
	v_cmp_lt_i32_e64 s[26:27], s79, v58
	v_bfe_u32 v59, v9, 16, 1
	v_add_u32_e32 v55, 0x110, v55
	v_add3_u32 v59, v9, v59, s81
	v_lshl_add_u32 v58, v106, 1, v55
	ds_write_b16_d16_hi v58, v59
	v_add3_u32 v59, s96, v96, 50
	v_cmp_lt_i32_e64 s[28:29], s79, v59
	v_bfe_u32 v60, v10, 16, 1
	v_add_u32_e32 v55, 0x110, v55
	v_add3_u32 v60, v10, v60, s81
	v_lshl_add_u32 v59, v106, 1, v55
	ds_write_b16_d16_hi v59, v60
	v_add3_u32 v60, s96, v96, 51
	v_cmp_lt_i32_e64 s[30:31], s79, v60
	v_bfe_u32 v61, v11, 16, 1
	v_add_u32_e32 v55, 0x110, v55
	v_add3_u32 v61, v11, v61, s81
	v_lshl_add_u32 v60, v106, 1, v55
	ds_write_b16_d16_hi v60, v61
	v_add3_u32 v61, s96, v96, 56
	v_cmp_lt_i32_e64 s[34:35], s79, v61
	v_bfe_u32 v62, v12, 16, 1
	v_add_u32_e32 v55, 0x550, v55
	v_add3_u32 v62, v12, v62, s81
	v_lshl_add_u32 v61, v106, 1, v55
	ds_write_b16_d16_hi v61, v62
	v_add3_u32 v62, s96, v96, 57
	v_cmp_lt_i32_e64 s[36:37], s79, v62
	v_bfe_u32 v63, v13, 16, 1
	v_add_u32_e32 v55, 0x110, v55
	v_add3_u32 v63, v13, v63, s81
	v_lshl_add_u32 v62, v106, 1, v55
	ds_write_b16_d16_hi v62, v63
	v_add3_u32 v63, s96, v96, 58
	v_cmp_lt_i32_e64 s[38:39], s79, v63
	v_bfe_u32 v107, v14, 16, 1
	v_add_u32_e32 v55, 0x110, v55
	v_add3_u32 v63, v14, v107, s81
	v_lshl_add_u32 v55, v106, 1, v55
	ds_write_b16_d16_hi v55, v63
	v_add3_u32 v63, s96, v96, 59
	v_cmp_lt_i32_e64 s[40:41], s79, v63
	v_bfe_u32 v96, v15, 16, 1
	v_add3_u32 v63, v15, v96, s81
	ds_write_b16_d16_hi v55, v63 offset:272
	v_bfe_u32 v63, v32, 16, 1
	v_add3_u32 v32, v32, v63, s81
	ds_write_b16_d16_hi v48, v32 offset:64
	v_bfe_u32 v32, v33, 16, 1
	v_add3_u32 v32, v33, v32, s81
	ds_write_b16_d16_hi v49, v32 offset:64
	v_bfe_u32 v33, v34, 16, 1
	v_add3_u32 v32, v34, v33, s81
	ds_write_b16_d16_hi v50, v32 offset:64
	v_bfe_u32 v33, v35, 16, 1
	v_add3_u32 v32, v35, v33, s81
	ds_write_b16_d16_hi v51, v32 offset:64
	v_bfe_u32 v33, v36, 16, 1
	v_add3_u32 v32, v36, v33, s81
	ds_write_b16_d16_hi v52, v32 offset:64
	v_bfe_u32 v33, v37, 16, 1
	v_add3_u32 v32, v37, v33, s81
	ds_write_b16_d16_hi v53, v32 offset:64
	v_bfe_u32 v33, v38, 16, 1
	v_add3_u32 v32, v38, v33, s81
	ds_write_b16_d16_hi v54, v32 offset:64
	v_bfe_u32 v33, v39, 16, 1
	v_add3_u32 v32, v39, v33, s81
	ds_write_b16_d16_hi v56, v32 offset:64
	v_bfe_u32 v33, v40, 16, 1
	v_add3_u32 v32, v40, v33, s81
	ds_write_b16_d16_hi v57, v32 offset:64
	v_bfe_u32 v33, v41, 16, 1
	v_add3_u32 v32, v41, v33, s81
	ds_write_b16_d16_hi v58, v32 offset:64
	v_bfe_u32 v33, v42, 16, 1
	v_add3_u32 v32, v42, v33, s81
	ds_write_b16_d16_hi v59, v32 offset:64
	v_bfe_u32 v33, v43, 16, 1
	v_add3_u32 v32, v43, v33, s81
	ds_write_b16_d16_hi v60, v32 offset:64
	v_bfe_u32 v33, v44, 16, 1
	v_add3_u32 v32, v44, v33, s81
	ds_write_b16_d16_hi v61, v32 offset:64
	v_bfe_u32 v33, v45, 16, 1
	v_add3_u32 v32, v45, v33, s81
	ds_write_b16_d16_hi v62, v32 offset:64
	v_bfe_u32 v33, v46, 16, 1
	v_add3_u32 v32, v46, v33, s81
	ds_write_b16_d16_hi v55, v32 offset:64
	v_mov_b32_e32 v32, v47
	s_branch .LBB0_2906

; __device__ __forceinline__ float sigmf(float x) { return 1.f / (1.f + __expf(-x)); }
; __device__ __forceinline__ float softplusf(float x) { return fmaxf(x, 0.f) + __logf(1.f + __expf(-fabsf(x))); }
; __device__ __forceinline__ void inproj_epilogue(const Params& p, int layer, int mt, int ntile, int tid,
;                                                 f32x16 (&acc)[2][2], unsigned char* smem) {
;     ...
;   const int m0 = mt * 128;
;   if (mode == 3) {
;     float* dt = (float*)(p.ws + OFF_DT) + (size_t)m0 * 16;
;     const float* bias = p.ssd_dt_bias + layer * 16;
;     acc_foreach(tid, acc, [&](int row, int col, float v) {
;       if (col < 16) *(dt + row * 16 + col) = softplusf(v + bias[col]);
;     });
;   } else {
;     bf16r* dstb = dst + (size_t)m0 * ld + c0;
;     bf16r* sT = (bf16r*)smem;
;     acc_foreach(tid, acc, [&](int row, int col, float v) {
;       int t = m0 + row;
;       float o = v;
;       if (mode == 1) o = (t >= NPADR) ? v : 0.f;
;       if (mode == 2) o = sigmf(v);
;       sT[row * 136 + col] = f2bf(o);
.LBB0_3032:
	s_lshl_b32 s94, s6, 7
	s_ashr_i32 s95, s94, 31
	s_cmp_lg_u32 s7, 3
	s_mov_b64 s[4:5], -1
	s_cbranch_scc0 .LBB0_3226
	v_mov_b32_e32 v106, v108
	s_movk_i32 s4, 0xffc0
	v_lshrrev_b32_e32 v107, 3, v106
	v_ashrrev_i32_e32 v96, 1, v106
	v_and_b32_e32 v107, 4, v107
	v_and_or_b32 v96, v96, s4, v107
	s_cmp_eq_u32 s7, 1
	s_cselect_b64 s[4:5], -1, 0
	v_add_u32_e32 v107, s94, v96
	s_cmp_eq_u32 s7, 2
	s_cselect_b64 s[10:11], -1, 0
	s_cmp_lg_u32 s7, 2
	v_cmp_lt_i32_e64 s[8:9], s77, v107
	s_cbranch_scc0 .Lgv_6
	s_cmp_eq_u32 s7, 1
	s_cbranch_scc0 .Lfp_6

; __device__ __forceinline__ float sigmf(float x) { return 1.f / (1.f + __expf(-x)); }
; __device__ __forceinline__ bf16r f2bf(float f) {
;   unsigned u = __float_as_uint(f);
;   u += 0x7fffu + ((u >> 16) & 1u);
;   return (bf16r)(u >> 16);
; }
; __device__ __forceinline__ void inproj_epilogue(const Params& p, int layer, int mt, int ntile, int tid,
;                                                 f32x16 (&acc)[2][2], unsigned char* smem) {
;     ...
;     acc_foreach(tid, acc, [&](int row, int col, float v) {
;       int t = m0 + row;
;       float o = v;
;       if (mode == 1) o = (t >= NPADR) ? v : 0.f;
;       if (mode == 2) o = sigmf(v);
;       sT[row * 136 + col] = f2bf(o);
;     });
.Lfp_6:
	v_bfe_u32 v110, v16, 16, 1
	v_and_b32_e32 v106, 0x5f, v106
	v_add3_u32 v111, v16, v110, s79
	v_mul_lo_u32 v110, v96, s80
	v_lshl_add_u32 v107, v106, 1, v110
	ds_write_b16_d16_hi v107, v111
	v_add3_u32 v111, s94, v96, 1
	v_cndmask_b32_e64 v112, 0, 1, s[10:11]
	v_cmp_ne_u32_e64 s[6:7], 1, v112
	v_cmp_lt_i32_e64 s[10:11], s77, v111
	v_bfe_u32 v112, v17, 16, 1
	v_add3_u32 v112, v17, v112, s79
	v_add_u32_e32 v111, 0x110, v110
	v_lshl_add_u32 v110, v106, 1, v111
	ds_write_b16_d16_hi v110, v112
	v_add3_u32 v112, s94, v96, 2
	v_cmp_lt_i32_e64 s[12:13], s77, v112
	v_bfe_u32 v113, v18, 16, 1
	v_add3_u32 v113, v18, v113, s79
	v_add_u32_e32 v112, 0x110, v111
	v_lshl_add_u32 v111, v106, 1, v112
	ds_write_b16_d16_hi v111, v113
	v_add3_u32 v113, s94, v96, 3
	v_cmp_lt_i32_e64 s[14:15], s77, v113
	v_bfe_u32 v114, v19, 16, 1
	v_add3_u32 v114, v19, v114, s79
	v_add_u32_e32 v113, 0x110, v112
	v_lshl_add_u32 v112, v106, 1, v113
	ds_write_b16_d16_hi v112, v114
	v_add3_u32 v114, s94, v96, 8
	v_cmp_lt_i32_e64 s[16:17], s77, v114
	v_bfe_u32 v115, v20, 16, 1
	v_add3_u32 v115, v20, v115, s79
	v_add_u32_e32 v114, 0x550, v113
	v_lshl_add_u32 v113, v106, 1, v114
	ds_write_b16_d16_hi v113, v115
	v_add3_u32 v115, s94, v96, 9
	v_cmp_lt_i32_e64 s[18:19], s77, v115
	v_bfe_u32 v116, v21, 16, 1
	v_add3_u32 v116, v21, v116, s79
	v_add_u32_e32 v115, 0x110, v114
	v_lshl_add_u32 v114, v106, 1, v115
	ds_write_b16_d16_hi v114, v116
	v_add3_u32 v116, s94, v96, 10
	v_cmp_lt_i32_e64 s[20:21], s77, v116
	v_bfe_u32 v117, v22, 16, 1
	v_add3_u32 v117, v22, v117, s79
	v_add_u32_e32 v116, 0x110, v115
	v_lshl_add_u32 v115, v106, 1, v116
	ds_write_b16_d16_hi v115, v117
	v_add3_u32 v117, s94, v96, 11
	v_cmp_lt_i32_e64 s[22:23], s77, v117
	v_bfe_u32 v118, v23, 16, 1
	v_add_u32_e32 v116, 0x110, v116
	v_add3_u32 v118, v23, v118, s79
	v_lshl_add_u32 v117, v106, 1, v116
	ds_write_b16_d16_hi v117, v118
	v_add3_u32 v118, s94, v96, 16
	v_cmp_lt_i32_e64 s[24:25], s77, v118
	v_bfe_u32 v119, v24, 16, 1
	v_add_u32_e32 v116, 0x550, v116
	v_add3_u32 v119, v24, v119, s79
	v_lshl_add_u32 v118, v106, 1, v116
	ds_write_b16_d16_hi v118, v119
	v_add3_u32 v119, s94, v96, 17
	v_cmp_lt_i32_e64 s[26:27], s77, v119
	v_bfe_u32 v120, v25, 16, 1
	v_add_u32_e32 v116, 0x110, v116
	v_add3_u32 v120, v25, v120, s79
	v_lshl_add_u32 v119, v106, 1, v116
	ds_write_b16_d16_hi v119, v120
	v_add3_u32 v120, s94, v96, 18
	v_cmp_lt_i32_e64 s[28:29], s77, v120
	v_bfe_u32 v121, v26, 16, 1
	v_add_u32_e32 v116, 0x110, v116
	v_add3_u32 v121, v26, v121, s79
	v_lshl_add_u32 v120, v106, 1, v116
	ds_write_b16_d16_hi v120, v121
	v_add3_u32 v121, s94, v96, 19
	v_cmp_lt_i32_e64 s[30:31], s77, v121
	v_bfe_u32 v122, v27, 16, 1
	v_add_u32_e32 v116, 0x110, v116
	v_add3_u32 v122, v27, v122, s79
	v_lshl_add_u32 v121, v106, 1, v116
	ds_write_b16_d16_hi v121, v122
	v_add3_u32 v122, s94, v96, 24
	v_cmp_lt_i32_e64 s[34:35], s77, v122
	v_bfe_u32 v123, v28, 16, 1
	v_add_u32_e32 v116, 0x550, v116
	v_add3_u32 v123, v28, v123, s79
	v_lshl_add_u32 v122, v106, 1, v116
	ds_write_b16_d16_hi v122, v123
	v_add3_u32 v123, s94, v96, 25
	v_cmp_lt_i32_e64 s[36:37], s77, v123
	v_bfe_u32 v124, v29, 16, 1
	v_add_u32_e32 v116, 0x110, v116
	v_add3_u32 v124, v29, v124, s79
	v_lshl_add_u32 v123, v106, 1, v116
	ds_write_b16_d16_hi v123, v124
	v_add3_u32 v124, s94, v96, 26
	v_cmp_lt_i32_e64 s[38:39], s77, v124
	v_bfe_u32 v125, v30, 16, 1
	v_add_u32_e32 v116, 0x110, v116
	v_add3_u32 v124, v30, v125, s79
	v_lshl_add_u32 v116, v106, 1, v116
	ds_write_b16_d16_hi v116, v124
	v_add3_u32 v124, s94, v96, 27
	v_cmp_lt_i32_e64 s[40:41], s77, v124
	v_bfe_u32 v125, v31, 16, 1
	v_add3_u32 v124, v31, v125, s79
	ds_write_b16_d16_hi v116, v124 offset:272
	v_bfe_u32 v124, v48, 16, 1
	v_add3_u32 v48, v48, v124, s79
	ds_write_b16_d16_hi v107, v48 offset:64
	v_bfe_u32 v48, v49, 16, 1
	v_add3_u32 v48, v49, v48, s79
	ds_write_b16_d16_hi v110, v48 offset:64
	v_bfe_u32 v49, v50, 16, 1
	v_add3_u32 v48, v50, v49, s79
	ds_write_b16_d16_hi v111, v48 offset:64
	v_bfe_u32 v49, v51, 16, 1
	v_add3_u32 v48, v51, v49, s79
	ds_write_b16_d16_hi v112, v48 offset:64
	v_bfe_u32 v49, v52, 16, 1
	v_add3_u32 v48, v52, v49, s79
	ds_write_b16_d16_hi v113, v48 offset:64
	v_bfe_u32 v49, v53, 16, 1
	v_add3_u32 v48, v53, v49, s79
	ds_write_b16_d16_hi v114, v48 offset:64
	v_bfe_u32 v49, v54, 16, 1
	v_add3_u32 v48, v54, v49, s79
	ds_write_b16_d16_hi v115, v48 offset:64
	v_bfe_u32 v49, v55, 16, 1
	v_add3_u32 v48, v55, v49, s79
	ds_write_b16_d16_hi v117, v48 offset:64
	v_bfe_u32 v49, v56, 16, 1
	v_add3_u32 v48, v56, v49, s79
	ds_write_b16_d16_hi v118, v48 offset:64
	v_bfe_u32 v49, v57, 16, 1
	v_add3_u32 v48, v57, v49, s79
	ds_write_b16_d16_hi v119, v48 offset:64
	v_bfe_u32 v49, v58, 16, 1
	v_add3_u32 v48, v58, v49, s79
	ds_write_b16_d16_hi v120, v48 offset:64
	v_bfe_u32 v49, v59, 16, 1
	v_add3_u32 v48, v59, v49, s79
	ds_write_b16_d16_hi v121, v48 offset:64
	v_bfe_u32 v49, v60, 16, 1
	v_add3_u32 v48, v60, v49, s79
	ds_write_b16_d16_hi v122, v48 offset:64
	v_bfe_u32 v49, v61, 16, 1
	v_add3_u32 v48, v61, v49, s79
	ds_write_b16_d16_hi v123, v48 offset:64
	v_bfe_u32 v49, v62, 16, 1
	v_add3_u32 v48, v62, v49, s79
; __device__ __forceinline__ float sigmf(float x) { return 1.f / (1.f + __expf(-x)); }
; template <int MT, int NT, class F>
; __device__ __forceinline__ void acc_foreach(int tid, f32x16 (&acc)[MT][NT], F f) {
;     ...
; #pragma unroll
;   for (int mt = 0; mt < MT; mt++)
; #pragma unroll
;     for (int nt = 0; nt < NT; nt++)
; #pragma unroll
;       for (int i = 0; i < 16; i++) {
;         int row = wm * (MT * 32) + mt * 32 + (i & 3) + 8 * (i >> 2) + 4 * hi;
;         int col = wn * (NT * 32) + nt * 32 + c;
;         f(row, col, acc[mt][nt][i]);
;         if (i == 15) __builtin_amdgcn_sched_barrier(0);
;       }
; __device__ __forceinline__ void inproj_epilogue(const Params& p, int layer, int mt, int ntile, int tid,
;                                                 f32x16 (&acc)[2][2], unsigned char* smem) {
;     ...
;     acc_foreach(tid, acc, [&](int row, int col, float v) {
;       int t = m0 + row;
;       float o = v;
;       if (mode == 1) o = (t >= NPADR) ? v : 0.f;
;       if (mode == 2) o = sigmf(v);
;       sT[row * 136 + col] = f2bf(o);
;     });
	ds_write_b16_d16_hi v116, v48 offset:64
	v_bfe_u32 v50, v63, 16, 1
	v_add_u32_e32 v49, 0x110, v116
	v_add3_u32 v48, v63, v50, s79
	ds_write_b16_d16_hi v49, v48 offset:64
	v_or_b32_e32 v48, 32, v96
	v_add_u32_e32 v49, s94, v48
	v_cmp_lt_i32_e64 s[8:9], s77, v49
	v_bfe_u32 v50, v0, 16, 1
	v_add3_u32 v50, v0, v50, s79
	v_mul_lo_u32 v49, v48, s80
	v_lshl_add_u32 v48, v106, 1, v49
	ds_write_b16_d16_hi v48, v50
	v_add3_u32 v50, s94, v96, 33
	v_cmp_lt_i32_e64 s[10:11], s77, v50
	v_bfe_u32 v51, v1, 16, 1
	v_add3_u32 v51, v1, v51, s79
	v_add_u32_e32 v50, 0x110, v49
	v_lshl_add_u32 v49, v106, 1, v50
	ds_write_b16_d16_hi v49, v51
	v_add3_u32 v51, s94, v96, 34
	v_cmp_lt_i32_e64 s[12:13], s77, v51
	v_bfe_u32 v52, v2, 16, 1
	v_add3_u32 v52, v2, v52, s79
	v_add_u32_e32 v51, 0x110, v50
	v_lshl_add_u32 v50, v106, 1, v51
	ds_write_b16_d16_hi v50, v52
	v_add3_u32 v52, s94, v96, 35
	v_cmp_lt_i32_e64 s[14:15], s77, v52
	v_bfe_u32 v53, v3, 16, 1
	v_add3_u32 v53, v3, v53, s79
	v_add_u32_e32 v52, 0x110, v51
	v_lshl_add_u32 v51, v106, 1, v52
	ds_write_b16_d16_hi v51, v53
	v_add3_u32 v53, s94, v96, 40
	v_cmp_lt_i32_e64 s[16:17], s77, v53
	v_bfe_u32 v54, v4, 16, 1
	v_add3_u32 v54, v4, v54, s79
	v_add_u32_e32 v53, 0x550, v52
	v_lshl_add_u32 v52, v106, 1, v53
	ds_write_b16_d16_hi v52, v54
	v_add3_u32 v54, s94, v96, 41
	v_cmp_lt_i32_e64 s[18:19], s77, v54
	v_bfe_u32 v55, v5, 16, 1
	v_add3_u32 v55, v5, v55, s79
	v_add_u32_e32 v54, 0x110, v53
	v_lshl_add_u32 v53, v106, 1, v54
	ds_write_b16_d16_hi v53, v55
	v_add3_u32 v55, s94, v96, 42
	v_cmp_lt_i32_e64 s[20:21], s77, v55
	v_bfe_u32 v56, v6, 16, 1
	v_add3_u32 v56, v6, v56, s79
	v_add_u32_e32 v55, 0x110, v54
	v_lshl_add_u32 v54, v106, 1, v55
	ds_write_b16_d16_hi v54, v56
	v_add3_u32 v56, s94, v96, 43
	v_cmp_lt_i32_e64 s[22:23], s77, v56
	v_bfe_u32 v57, v7, 16, 1
	v_add_u32_e32 v55, 0x110, v55
	v_add3_u32 v57, v7, v57, s79
	v_lshl_add_u32 v56, v106, 1, v55
	ds_write_b16_d16_hi v56, v57
	v_add3_u32 v57, s94, v96, 48
	v_cmp_lt_i32_e64 s[24:25], s77, v57
	v_bfe_u32 v58, v8, 16, 1
	v_add_u32_e32 v55, 0x550, v55
	v_add3_u32 v58, v8, v58, s79
	v_lshl_add_u32 v57, v106, 1, v55
	ds_write_b16_d16_hi v57, v58
	v_add3_u32 v58, s94, v96, 49
	v_cmp_lt_i32_e64 s[26:27], s77, v58
	v_bfe_u32 v59, v9, 16, 1
	v_add_u32_e32 v55, 0x110, v55
	v_add3_u32 v59, v9, v59, s79
	v_lshl_add_u32 v58, v106, 1, v55
	ds_write_b16_d16_hi v58, v59
	v_add3_u32 v59, s94, v96, 50
	v_cmp_lt_i32_e64 s[28:29], s77, v59
	v_bfe_u32 v60, v10, 16, 1
	v_add_u32_e32 v55, 0x110, v55
	v_add3_u32 v60, v10, v60, s79
	v_lshl_add_u32 v59, v106, 1, v55
	ds_write_b16_d16_hi v59, v60
	v_add3_u32 v60, s94, v96, 51
	v_cmp_lt_i32_e64 s[30:31], s77, v60
	v_bfe_u32 v61, v11, 16, 1
	v_add_u32_e32 v55, 0x110, v55
	v_add3_u32 v61, v11, v61, s79
	v_lshl_add_u32 v60, v106, 1, v55
	ds_write_b16_d16_hi v60, v61
	v_add3_u32 v61, s94, v96, 56
	v_cmp_lt_i32_e64 s[34:35], s77, v61
	v_bfe_u32 v62, v12, 16, 1
	v_add_u32_e32 v55, 0x550, v55
	v_add3_u32 v62, v12, v62, s79
	v_lshl_add_u32 v61, v106, 1, v55
	ds_write_b16_d16_hi v61, v62
	v_add3_u32 v62, s94, v96, 57
	v_cmp_lt_i32_e64 s[36:37], s77, v62
	v_bfe_u32 v63, v13, 16, 1
	v_add_u32_e32 v55, 0x110, v55
	v_add3_u32 v63, v13, v63, s79
	v_lshl_add_u32 v62, v106, 1, v55
	ds_write_b16_d16_hi v62, v63
	v_add3_u32 v63, s94, v96, 58
	v_cmp_lt_i32_e64 s[38:39], s77, v63
	v_bfe_u32 v107, v14, 16, 1
	v_add_u32_e32 v55, 0x110, v55
	v_add3_u32 v63, v14, v107, s79
	v_lshl_add_u32 v55, v106, 1, v55
	ds_write_b16_d16_hi v55, v63
	v_add3_u32 v63, s94, v96, 59
	v_cmp_lt_i32_e64 s[40:41], s77, v63
	v_bfe_u32 v96, v15, 16, 1
	v_add3_u32 v63, v15, v96, s79
	ds_write_b16_d16_hi v55, v63 offset:272
	v_bfe_u32 v63, v32, 16, 1
	v_add3_u32 v32, v32, v63, s79
	ds_write_b16_d16_hi v48, v32 offset:64
	v_bfe_u32 v32, v33, 16, 1
	v_add3_u32 v32, v33, v32, s79
	ds_write_b16_d16_hi v49, v32 offset:64
	v_bfe_u32 v33, v34, 16, 1
	v_add3_u32 v32, v34, v33, s79
	ds_write_b16_d16_hi v50, v32 offset:64
	v_bfe_u32 v33, v35, 16, 1
	v_add3_u32 v32, v35, v33, s79
	ds_write_b16_d16_hi v51, v32 offset:64
	v_bfe_u32 v33, v36, 16, 1
	v_add3_u32 v32, v36, v33, s79
	ds_write_b16_d16_hi v52, v32 offset:64
	v_bfe_u32 v33, v37, 16, 1
	v_add3_u32 v32, v37, v33, s79
	ds_write_b16_d16_hi v53, v32 offset:64
	v_bfe_u32 v33, v38, 16, 1
	v_add3_u32 v32, v38, v33, s79
	ds_write_b16_d16_hi v54, v32 offset:64
	v_bfe_u32 v33, v39, 16, 1
	v_add3_u32 v32, v39, v33, s79
	ds_write_b16_d16_hi v56, v32 offset:64
	v_bfe_u32 v33, v40, 16, 1
	v_add3_u32 v32, v40, v33, s79
	ds_write_b16_d16_hi v57, v32 offset:64
	v_bfe_u32 v33, v41, 16, 1
	v_add3_u32 v32, v41, v33, s79
	ds_write_b16_d16_hi v58, v32 offset:64
	v_bfe_u32 v33, v42, 16, 1
	v_add3_u32 v32, v42, v33, s79
	ds_write_b16_d16_hi v59, v32 offset:64
	v_bfe_u32 v33, v43, 16, 1
	v_add3_u32 v32, v43, v33, s79
	ds_write_b16_d16_hi v60, v32 offset:64
	v_bfe_u32 v33, v44, 16, 1
	v_add3_u32 v32, v44, v33, s79
	ds_write_b16_d16_hi v61, v32 offset:64
	v_bfe_u32 v33, v45, 16, 1
	v_add3_u32 v32, v45, v33, s79
	ds_write_b16_d16_hi v62, v32 offset:64
	v_bfe_u32 v33, v46, 16, 1
	v_add3_u32 v32, v46, v33, s79
	ds_write_b16_d16_hi v55, v32 offset:64
	v_mov_b32_e32 v32, v47
	s_branch .LBB0_3225

; __device__ __forceinline__ float sigmf(float x) { return 1.f / (1.f + __expf(-x)); }
; __device__ __forceinline__ float softplusf(float x) { return fmaxf(x, 0.f) + __logf(1.f + __expf(-fabsf(x))); }
; template <int MT, int NT, class F>
; __device__ __forceinline__ void acc_foreach(int tid, f32x16 (&acc)[MT][NT], F f) {
;     ...
;   const int lane = tid & 63, w = tid >> 6;
;   const int wm = w >> 1, wn = w & 1, hi = lane >> 5, c = lane & 31;
; #pragma unroll
;   for (int mt = 0; mt < MT; mt++)
; #pragma unroll
;     for (int nt = 0; nt < NT; nt++)
; #pragma unroll
;       for (int i = 0; i < 16; i++) {
;         int row = wm * (MT * 32) + mt * 32 + (i & 3) + 8 * (i >> 2) + 4 * hi;
;         int col = wn * (NT * 32) + nt * 32 + c;
; __device__ __forceinline__ void inproj_epilogue(const Params& p, int layer, int mt, int ntile, int tid,
;                                                 f32x16 (&acc)[2][2], unsigned char* smem) {
;     ...
;   const int m0 = mt * 128;
;   if (mode == 3) {
;     float* dt = (float*)(p.ws + OFF_DT) + (size_t)m0 * 16;
;     const float* bias = p.ssd_dt_bias + layer * 16;
;     acc_foreach(tid, acc, [&](int row, int col, float v) {
;       if (col < 16) *(dt + row * 16 + col) = softplusf(v + bias[col]);
;     });
;   } else {
;     bf16r* dstb = dst + (size_t)m0 * ld + c0;
;     bf16r* sT = (bf16r*)smem;
;     acc_foreach(tid, acc, [&](int row, int col, float v) {
;       int t = m0 + row;
;       float o = v;
;       if (mode == 1) o = (t >= NPADR) ? v : 0.f;
;       if (mode == 2) o = sigmf(v);
.LBB0_3366:
	s_lshl_b32 s88, s6, 7
	s_ashr_i32 s89, s88, 31
	s_cmp_lg_u32 s7, 3
	s_mov_b64 s[4:5], -1
	s_cbranch_scc0 .LBB0_3560
	v_mov_b32_e32 v106, v108
	s_movk_i32 s4, 0xffc0
	v_lshrrev_b32_e32 v107, 3, v106
	v_ashrrev_i32_e32 v96, 1, v106
	v_and_b32_e32 v107, 4, v107
	v_and_or_b32 v96, v96, s4, v107
	s_cmp_eq_u32 s7, 1
	s_cselect_b64 s[4:5], -1, 0
	v_add_u32_e32 v107, s88, v96
	s_cmp_eq_u32 s7, 2
	s_cselect_b64 s[10:11], -1, 0
	s_cmp_lg_u32 s7, 2
	v_cmp_lt_i32_e64 s[8:9], s81, v107
	s_cbranch_scc0 .Lgv_7
	s_cmp_eq_u32 s7, 1
	s_cbranch_scc0 .Lfp_7

; __device__ __forceinline__ float sigmf(float x) { return 1.f / (1.f + __expf(-x)); }
; template <int MT, int NT, class F>
; __device__ __forceinline__ void acc_foreach(int tid, f32x16 (&acc)[MT][NT], F f) {
;     ...
; #pragma unroll
;   for (int mt = 0; mt < MT; mt++)
; #pragma unroll
;     for (int nt = 0; nt < NT; nt++)
; #pragma unroll
;       for (int i = 0; i < 16; i++) {
;         int row = wm * (MT * 32) + mt * 32 + (i & 3) + 8 * (i >> 2) + 4 * hi;
;         int col = wn * (NT * 32) + nt * 32 + c;
;         f(row, col, acc[mt][nt][i]);
;         if (i == 15) __builtin_amdgcn_sched_barrier(0);
;       }
; __device__ __forceinline__ void inproj_epilogue(const Params& p, int layer, int mt, int ntile, int tid,
;                                                 f32x16 (&acc)[2][2], unsigned char* smem) {
;     ...
;     acc_foreach(tid, acc, [&](int row, int col, float v) {
;       int t = m0 + row;
;       float o = v;
;       if (mode == 1) o = (t >= NPADR) ? v : 0.f;
;       if (mode == 2) o = sigmf(v);
;       sT[row * 136 + col] = f2bf(o);
;     });
.Lfp_7:
	v_bfe_u32 v110, v16, 16, 1
	v_and_b32_e32 v106, 0x5f, v106
	v_add3_u32 v111, v16, v110, s83
	v_mul_lo_u32 v110, v96, s90
	v_lshl_add_u32 v107, v106, 1, v110
	ds_write_b16_d16_hi v107, v111
	v_add3_u32 v111, s88, v96, 1
	v_cndmask_b32_e64 v112, 0, 1, s[10:11]
	v_cmp_ne_u32_e64 s[6:7], 1, v112
	v_cmp_lt_i32_e64 s[10:11], s81, v111
	v_bfe_u32 v112, v17, 16, 1
	v_add3_u32 v112, v17, v112, s83
	v_add_u32_e32 v111, 0x110, v110
	v_lshl_add_u32 v110, v106, 1, v111
	ds_write_b16_d16_hi v110, v112
	v_add3_u32 v112, s88, v96, 2
	v_cmp_lt_i32_e64 s[12:13], s81, v112
	v_bfe_u32 v113, v18, 16, 1
	v_add3_u32 v113, v18, v113, s83
	v_add_u32_e32 v112, 0x110, v111
	v_lshl_add_u32 v111, v106, 1, v112
	ds_write_b16_d16_hi v111, v113
	v_add3_u32 v113, s88, v96, 3
	v_cmp_lt_i32_e64 s[14:15], s81, v113
	v_bfe_u32 v114, v19, 16, 1
	v_add3_u32 v114, v19, v114, s83
	v_add_u32_e32 v113, 0x110, v112
	v_lshl_add_u32 v112, v106, 1, v113
	ds_write_b16_d16_hi v112, v114
	v_add3_u32 v114, s88, v96, 8
	v_cmp_lt_i32_e64 s[16:17], s81, v114
	v_bfe_u32 v115, v20, 16, 1
	v_add3_u32 v115, v20, v115, s83
	v_add_u32_e32 v114, 0x550, v113
	v_lshl_add_u32 v113, v106, 1, v114
	ds_write_b16_d16_hi v113, v115
	v_add3_u32 v115, s88, v96, 9
	v_cmp_lt_i32_e64 s[18:19], s81, v115
	v_bfe_u32 v116, v21, 16, 1
	v_add3_u32 v116, v21, v116, s83
	v_add_u32_e32 v115, 0x110, v114
	v_lshl_add_u32 v114, v106, 1, v115
	ds_write_b16_d16_hi v114, v116
	v_add3_u32 v116, s88, v96, 10
	v_cmp_lt_i32_e64 s[20:21], s81, v116
	v_bfe_u32 v117, v22, 16, 1
	v_add3_u32 v117, v22, v117, s83
	v_add_u32_e32 v116, 0x110, v115
	v_lshl_add_u32 v115, v106, 1, v116
	ds_write_b16_d16_hi v115, v117
	v_add3_u32 v117, s88, v96, 11
	v_cmp_lt_i32_e64 s[22:23], s81, v117
	v_bfe_u32 v118, v23, 16, 1
	v_add_u32_e32 v116, 0x110, v116
	v_add3_u32 v118, v23, v118, s83
	v_lshl_add_u32 v117, v106, 1, v116
	ds_write_b16_d16_hi v117, v118
	v_add3_u32 v118, s88, v96, 16
	v_cmp_lt_i32_e64 s[24:25], s81, v118
	v_bfe_u32 v119, v24, 16, 1
	v_add_u32_e32 v116, 0x550, v116
	v_add3_u32 v119, v24, v119, s83
	v_lshl_add_u32 v118, v106, 1, v116
	ds_write_b16_d16_hi v118, v119
	v_add3_u32 v119, s88, v96, 17
	v_cmp_lt_i32_e64 s[26:27], s81, v119
	v_bfe_u32 v120, v25, 16, 1
	v_add_u32_e32 v116, 0x110, v116
	v_add3_u32 v120, v25, v120, s83
	v_lshl_add_u32 v119, v106, 1, v116
	ds_write_b16_d16_hi v119, v120
	v_add3_u32 v120, s88, v96, 18
	v_cmp_lt_i32_e64 s[28:29], s81, v120
	v_bfe_u32 v121, v26, 16, 1
	v_add_u32_e32 v116, 0x110, v116
	v_add3_u32 v121, v26, v121, s83
	v_lshl_add_u32 v120, v106, 1, v116
	ds_write_b16_d16_hi v120, v121
	v_add3_u32 v121, s88, v96, 19
	v_cmp_lt_i32_e64 s[30:31], s81, v121
	v_bfe_u32 v122, v27, 16, 1
	v_add_u32_e32 v116, 0x110, v116
	v_add3_u32 v122, v27, v122, s83
	v_lshl_add_u32 v121, v106, 1, v116
	ds_write_b16_d16_hi v121, v122
	v_add3_u32 v122, s88, v96, 24
	v_cmp_lt_i32_e64 s[34:35], s81, v122
	v_bfe_u32 v123, v28, 16, 1
	v_add_u32_e32 v116, 0x550, v116
	v_add3_u32 v123, v28, v123, s83
	v_lshl_add_u32 v122, v106, 1, v116
	ds_write_b16_d16_hi v122, v123
	v_add3_u32 v123, s88, v96, 25
	v_cmp_lt_i32_e64 s[36:37], s81, v123
	v_bfe_u32 v124, v29, 16, 1
	v_add_u32_e32 v116, 0x110, v116
	v_add3_u32 v124, v29, v124, s83
	v_lshl_add_u32 v123, v106, 1, v116
	ds_write_b16_d16_hi v123, v124
	v_add3_u32 v124, s88, v96, 26
	v_cmp_lt_i32_e64 s[38:39], s81, v124
	v_bfe_u32 v125, v30, 16, 1
	v_add_u32_e32 v116, 0x110, v116
	v_add3_u32 v124, v30, v125, s83
	v_lshl_add_u32 v116, v106, 1, v116
	ds_write_b16_d16_hi v116, v124
	v_add3_u32 v124, s88, v96, 27
	v_cmp_lt_i32_e64 s[40:41], s81, v124
	v_bfe_u32 v125, v31, 16, 1
	v_add3_u32 v124, v31, v125, s83
	ds_write_b16_d16_hi v116, v124 offset:272
	v_bfe_u32 v124, v48, 16, 1
	v_add3_u32 v48, v48, v124, s83
	ds_write_b16_d16_hi v107, v48 offset:64
	v_bfe_u32 v48, v49, 16, 1
	v_add3_u32 v48, v49, v48, s83
	ds_write_b16_d16_hi v110, v48 offset:64
	v_bfe_u32 v49, v50, 16, 1
	v_add3_u32 v48, v50, v49, s83
	ds_write_b16_d16_hi v111, v48 offset:64
	v_bfe_u32 v49, v51, 16, 1
	v_add3_u32 v48, v51, v49, s83
	ds_write_b16_d16_hi v112, v48 offset:64
	v_bfe_u32 v49, v52, 16, 1
	v_add3_u32 v48, v52, v49, s83
	ds_write_b16_d16_hi v113, v48 offset:64
	v_bfe_u32 v49, v53, 16, 1
	v_add3_u32 v48, v53, v49, s83
	ds_write_b16_d16_hi v114, v48 offset:64
	v_bfe_u32 v49, v54, 16, 1
	v_add3_u32 v48, v54, v49, s83
	ds_write_b16_d16_hi v115, v48 offset:64
	v_bfe_u32 v49, v55, 16, 1
	v_add3_u32 v48, v55, v49, s83
	ds_write_b16_d16_hi v117, v48 offset:64
	v_bfe_u32 v49, v56, 16, 1
	v_add3_u32 v48, v56, v49, s83
	ds_write_b16_d16_hi v118, v48 offset:64
	v_bfe_u32 v49, v57, 16, 1
	v_add3_u32 v48, v57, v49, s83
	ds_write_b16_d16_hi v119, v48 offset:64
	v_bfe_u32 v49, v58, 16, 1
	v_add3_u32 v48, v58, v49, s83
	ds_write_b16_d16_hi v120, v48 offset:64
	v_bfe_u32 v49, v59, 16, 1
	v_add3_u32 v48, v59, v49, s83
	ds_write_b16_d16_hi v121, v48 offset:64
	v_bfe_u32 v49, v60, 16, 1
	v_add3_u32 v48, v60, v49, s83
	ds_write_b16_d16_hi v122, v48 offset:64
	v_bfe_u32 v49, v61, 16, 1
	v_add3_u32 v48, v61, v49, s83
	ds_write_b16_d16_hi v123, v48 offset:64
	v_bfe_u32 v49, v62, 16, 1
	v_add3_u32 v48, v62, v49, s83
; __device__ __forceinline__ float sigmf(float x) { return 1.f / (1.f + __expf(-x)); }
; template <int MT, int NT, class F>
; __device__ __forceinline__ void acc_foreach(int tid, f32x16 (&acc)[MT][NT], F f) {
;     ...
; #pragma unroll
;   for (int mt = 0; mt < MT; mt++)
; #pragma unroll
;     for (int nt = 0; nt < NT; nt++)
; #pragma unroll
;       for (int i = 0; i < 16; i++) {
;         int row = wm * (MT * 32) + mt * 32 + (i & 3) + 8 * (i >> 2) + 4 * hi;
;         int col = wn * (NT * 32) + nt * 32 + c;
;         f(row, col, acc[mt][nt][i]);
;         if (i == 15) __builtin_amdgcn_sched_barrier(0);
;       }
; __device__ __forceinline__ void inproj_epilogue(const Params& p, int layer, int mt, int ntile, int tid,
;                                                 f32x16 (&acc)[2][2], unsigned char* smem) {
;     ...
;     acc_foreach(tid, acc, [&](int row, int col, float v) {
;       int t = m0 + row;
;       float o = v;
;       if (mode == 1) o = (t >= NPADR) ? v : 0.f;
;       if (mode == 2) o = sigmf(v);
;       sT[row * 136 + col] = f2bf(o);
;     });
	ds_write_b16_d16_hi v116, v48 offset:64
	v_bfe_u32 v50, v63, 16, 1
	v_add_u32_e32 v49, 0x110, v116
	v_add3_u32 v48, v63, v50, s83
	ds_write_b16_d16_hi v49, v48 offset:64
	v_or_b32_e32 v48, 32, v96
	v_add_u32_e32 v49, s88, v48
	v_cmp_lt_i32_e64 s[8:9], s81, v49
	v_bfe_u32 v50, v0, 16, 1
	v_add3_u32 v50, v0, v50, s83
	v_mul_lo_u32 v49, v48, s90
	v_lshl_add_u32 v48, v106, 1, v49
	ds_write_b16_d16_hi v48, v50
	v_add3_u32 v50, s88, v96, 33
	v_cmp_lt_i32_e64 s[10:11], s81, v50
	v_bfe_u32 v51, v1, 16, 1
	v_add3_u32 v51, v1, v51, s83
	v_add_u32_e32 v50, 0x110, v49
	v_lshl_add_u32 v49, v106, 1, v50
	ds_write_b16_d16_hi v49, v51
	v_add3_u32 v51, s88, v96, 34
	v_cmp_lt_i32_e64 s[12:13], s81, v51
	v_bfe_u32 v52, v2, 16, 1
	v_add3_u32 v52, v2, v52, s83
	v_add_u32_e32 v51, 0x110, v50
	v_lshl_add_u32 v50, v106, 1, v51
	ds_write_b16_d16_hi v50, v52
	v_add3_u32 v52, s88, v96, 35
	v_cmp_lt_i32_e64 s[14:15], s81, v52
	v_bfe_u32 v53, v3, 16, 1
	v_add3_u32 v53, v3, v53, s83
	v_add_u32_e32 v52, 0x110, v51
	v_lshl_add_u32 v51, v106, 1, v52
	ds_write_b16_d16_hi v51, v53
	v_add3_u32 v53, s88, v96, 40
	v_cmp_lt_i32_e64 s[16:17], s81, v53
	v_bfe_u32 v54, v4, 16, 1
	v_add3_u32 v54, v4, v54, s83
	v_add_u32_e32 v53, 0x550, v52
	v_lshl_add_u32 v52, v106, 1, v53
	ds_write_b16_d16_hi v52, v54
	v_add3_u32 v54, s88, v96, 41
	v_cmp_lt_i32_e64 s[18:19], s81, v54
	v_bfe_u32 v55, v5, 16, 1
	v_add3_u32 v55, v5, v55, s83
	v_add_u32_e32 v54, 0x110, v53
	v_lshl_add_u32 v53, v106, 1, v54
	ds_write_b16_d16_hi v53, v55
	v_add3_u32 v55, s88, v96, 42
	v_cmp_lt_i32_e64 s[20:21], s81, v55
	v_bfe_u32 v56, v6, 16, 1
	v_add3_u32 v56, v6, v56, s83
	v_add_u32_e32 v55, 0x110, v54
	v_lshl_add_u32 v54, v106, 1, v55
	ds_write_b16_d16_hi v54, v56
	v_add3_u32 v56, s88, v96, 43
	v_cmp_lt_i32_e64 s[22:23], s81, v56
	v_bfe_u32 v57, v7, 16, 1
	v_add_u32_e32 v55, 0x110, v55
	v_add3_u32 v57, v7, v57, s83
	v_lshl_add_u32 v56, v106, 1, v55
	ds_write_b16_d16_hi v56, v57
	v_add3_u32 v57, s88, v96, 48
	v_cmp_lt_i32_e64 s[24:25], s81, v57
	v_bfe_u32 v58, v8, 16, 1
	v_add_u32_e32 v55, 0x550, v55
	v_add3_u32 v58, v8, v58, s83
	v_lshl_add_u32 v57, v106, 1, v55
	ds_write_b16_d16_hi v57, v58
	v_add3_u32 v58, s88, v96, 49
	v_cmp_lt_i32_e64 s[26:27], s81, v58
	v_bfe_u32 v59, v9, 16, 1
	v_add_u32_e32 v55, 0x110, v55
	v_add3_u32 v59, v9, v59, s83
	v_lshl_add_u32 v58, v106, 1, v55
	ds_write_b16_d16_hi v58, v59
	v_add3_u32 v59, s88, v96, 50
	v_cmp_lt_i32_e64 s[28:29], s81, v59
	v_bfe_u32 v60, v10, 16, 1
	v_add_u32_e32 v55, 0x110, v55
	v_add3_u32 v60, v10, v60, s83
	v_lshl_add_u32 v59, v106, 1, v55
	ds_write_b16_d16_hi v59, v60
	v_add3_u32 v60, s88, v96, 51
	v_cmp_lt_i32_e64 s[30:31], s81, v60
	v_bfe_u32 v61, v11, 16, 1
	v_add_u32_e32 v55, 0x110, v55
	v_add3_u32 v61, v11, v61, s83
	v_lshl_add_u32 v60, v106, 1, v55
	ds_write_b16_d16_hi v60, v61
	v_add3_u32 v61, s88, v96, 56
	v_cmp_lt_i32_e64 s[34:35], s81, v61
	v_bfe_u32 v62, v12, 16, 1
	v_add_u32_e32 v55, 0x550, v55
	v_add3_u32 v62, v12, v62, s83
	v_lshl_add_u32 v61, v106, 1, v55
	ds_write_b16_d16_hi v61, v62
	v_add3_u32 v62, s88, v96, 57
	v_cmp_lt_i32_e64 s[36:37], s81, v62
	v_bfe_u32 v63, v13, 16, 1
	v_add_u32_e32 v55, 0x110, v55
	v_add3_u32 v63, v13, v63, s83
	v_lshl_add_u32 v62, v106, 1, v55
	ds_write_b16_d16_hi v62, v63
	v_add3_u32 v63, s88, v96, 58
	v_cmp_lt_i32_e64 s[38:39], s81, v63
	v_bfe_u32 v107, v14, 16, 1
	v_add_u32_e32 v55, 0x110, v55
	v_add3_u32 v63, v14, v107, s83
	v_lshl_add_u32 v55, v106, 1, v55
	ds_write_b16_d16_hi v55, v63
	v_add3_u32 v63, s88, v96, 59
	v_cmp_lt_i32_e64 s[40:41], s81, v63
	v_bfe_u32 v96, v15, 16, 1
	v_add3_u32 v63, v15, v96, s83
	ds_write_b16_d16_hi v55, v63 offset:272
	v_bfe_u32 v63, v32, 16, 1
	v_add3_u32 v32, v32, v63, s83
	ds_write_b16_d16_hi v48, v32 offset:64
	v_bfe_u32 v32, v33, 16, 1
	v_add3_u32 v32, v33, v32, s83
	ds_write_b16_d16_hi v49, v32 offset:64
	v_bfe_u32 v33, v34, 16, 1
	v_add3_u32 v32, v34, v33, s83
	ds_write_b16_d16_hi v50, v32 offset:64
	v_bfe_u32 v33, v35, 16, 1
	v_add3_u32 v32, v35, v33, s83
	ds_write_b16_d16_hi v51, v32 offset:64
	v_bfe_u32 v33, v36, 16, 1
	v_add3_u32 v32, v36, v33, s83
	ds_write_b16_d16_hi v52, v32 offset:64
	v_bfe_u32 v33, v37, 16, 1
	v_add3_u32 v32, v37, v33, s83
	ds_write_b16_d16_hi v53, v32 offset:64
	v_bfe_u32 v33, v38, 16, 1
	v_add3_u32 v32, v38, v33, s83
	ds_write_b16_d16_hi v54, v32 offset:64
	v_bfe_u32 v33, v39, 16, 1
	v_add3_u32 v32, v39, v33, s83
	ds_write_b16_d16_hi v56, v32 offset:64
	v_bfe_u32 v33, v40, 16, 1
	v_add3_u32 v32, v40, v33, s83
	ds_write_b16_d16_hi v57, v32 offset:64
	v_bfe_u32 v33, v41, 16, 1
	v_add3_u32 v32, v41, v33, s83
	ds_write_b16_d16_hi v58, v32 offset:64
	v_bfe_u32 v33, v42, 16, 1
	v_add3_u32 v32, v42, v33, s83
	ds_write_b16_d16_hi v59, v32 offset:64
	v_bfe_u32 v33, v43, 16, 1
	v_add3_u32 v32, v43, v33, s83
	ds_write_b16_d16_hi v60, v32 offset:64
	v_bfe_u32 v33, v44, 16, 1
	v_add3_u32 v32, v44, v33, s83
	ds_write_b16_d16_hi v61, v32 offset:64
	v_bfe_u32 v33, v45, 16, 1
	v_add3_u32 v32, v45, v33, s83
	ds_write_b16_d16_hi v62, v32 offset:64
	v_bfe_u32 v33, v46, 16, 1
	v_add3_u32 v32, v46, v33, s83
	ds_write_b16_d16_hi v55, v32 offset:64
	v_mov_b32_e32 v32, v47
	s_branch .LBB0_3559

; __device__ __forceinline__ float sigmf(float x) { return 1.f / (1.f + __expf(-x)); }
; __device__ __forceinline__ float softplusf(float x) { return fmaxf(x, 0.f) + __logf(1.f + __expf(-fabsf(x))); }
; template <int MT, int NT, class F>
; __device__ __forceinline__ void acc_foreach(int tid, f32x16 (&acc)[MT][NT], F f) {
;     ...
;   const int lane = tid & 63, w = tid >> 6;
;   const int wm = w >> 1, wn = w & 1, hi = lane >> 5, c = lane & 31;
; #pragma unroll
;   for (int mt = 0; mt < MT; mt++)
; #pragma unroll
;     for (int nt = 0; nt < NT; nt++)
; #pragma unroll
;       for (int i = 0; i < 16; i++) {
;         int row = wm * (MT * 32) + mt * 32 + (i & 3) + 8 * (i >> 2) + 4 * hi;
;         int col = wn * (NT * 32) + nt * 32 + c;
; __device__ __forceinline__ void inproj_epilogue(const Params& p, int layer, int mt, int ntile, int tid,
;                                                 f32x16 (&acc)[2][2], unsigned char* smem) {
;     ...
;   const int m0 = mt * 128;
;   if (mode == 3) {
;     float* dt = (float*)(p.ws + OFF_DT) + (size_t)m0 * 16;
;     const float* bias = p.ssd_dt_bias + layer * 16;
;     acc_foreach(tid, acc, [&](int row, int col, float v) {
;       if (col < 16) *(dt + row * 16 + col) = softplusf(v + bias[col]);
;     });
;   } else {
;     bf16r* dstb = dst + (size_t)m0 * ld + c0;
;     bf16r* sT = (bf16r*)smem;
;     acc_foreach(tid, acc, [&](int row, int col, float v) {
;       int t = m0 + row;
;       float o = v;
;       if (mode == 1) o = (t >= NPADR) ? v : 0.f;
;       if (mode == 2) o = sigmf(v);
.LBB0_4150:
	s_lshl_b32 s74, s6, 7
	s_ashr_i32 s75, s74, 31
	s_cmp_lg_u32 s7, 3
	s_mov_b64 s[4:5], -1
	s_cbranch_scc0 .LBB0_4344
	v_mov_b32_e32 v106, v108
	s_movk_i32 s4, 0xffc0
	v_lshrrev_b32_e32 v107, 3, v106
	v_ashrrev_i32_e32 v96, 1, v106
	v_and_b32_e32 v107, 4, v107
	v_and_or_b32 v96, v96, s4, v107
	s_cmp_eq_u32 s7, 1
	s_cselect_b64 s[4:5], -1, 0
	v_add_u32_e32 v107, s74, v96
	s_cmp_eq_u32 s7, 2
	s_cselect_b64 s[10:11], -1, 0
	s_cmp_lg_u32 s7, 2
	v_cmp_lt_i32_e64 s[8:9], s78, v107
	s_cbranch_scc0 .Lgv_8
	s_cmp_eq_u32 s7, 1
	s_cbranch_scc0 .Lfp_8

; __device__ __forceinline__ float sigmf(float x) { return 1.f / (1.f + __expf(-x)); }
; template <int MT, int NT, class F>
; __device__ __forceinline__ void acc_foreach(int tid, f32x16 (&acc)[MT][NT], F f) {
;     ...
; #pragma unroll
;   for (int mt = 0; mt < MT; mt++)
; #pragma unroll
;     for (int nt = 0; nt < NT; nt++)
; #pragma unroll
;       for (int i = 0; i < 16; i++) {
;         int row = wm * (MT * 32) + mt * 32 + (i & 3) + 8 * (i >> 2) + 4 * hi;
;         int col = wn * (NT * 32) + nt * 32 + c;
;         f(row, col, acc[mt][nt][i]);
;         if (i == 15) __builtin_amdgcn_sched_barrier(0);
;       }
; __device__ __forceinline__ void inproj_epilogue(const Params& p, int layer, int mt, int ntile, int tid,
;                                                 f32x16 (&acc)[2][2], unsigned char* smem) {
;     ...
;     acc_foreach(tid, acc, [&](int row, int col, float v) {
;       int t = m0 + row;
;       float o = v;
;       if (mode == 1) o = (t >= NPADR) ? v : 0.f;
;       if (mode == 2) o = sigmf(v);
;       sT[row * 136 + col] = f2bf(o);
;     });
.Lfp_8:
	v_bfe_u32 v110, v16, 16, 1
	v_and_b32_e32 v106, 0x5f, v106
	v_add3_u32 v111, v16, v110, s80
	v_mul_lo_u32 v110, v96, s81
	v_lshl_add_u32 v107, v106, 1, v110
	ds_write_b16_d16_hi v107, v111
	v_add3_u32 v111, s74, v96, 1
	v_cndmask_b32_e64 v112, 0, 1, s[10:11]
	v_cmp_ne_u32_e64 s[6:7], 1, v112
	v_cmp_lt_i32_e64 s[10:11], s78, v111
	v_bfe_u32 v112, v17, 16, 1
	v_add3_u32 v112, v17, v112, s80
	v_add_u32_e32 v111, 0x110, v110
	v_lshl_add_u32 v110, v106, 1, v111
	ds_write_b16_d16_hi v110, v112
	v_add3_u32 v112, s74, v96, 2
	v_cmp_lt_i32_e64 s[12:13], s78, v112
	v_bfe_u32 v113, v18, 16, 1
	v_add3_u32 v113, v18, v113, s80
	v_add_u32_e32 v112, 0x110, v111
	v_lshl_add_u32 v111, v106, 1, v112
	ds_write_b16_d16_hi v111, v113
	v_add3_u32 v113, s74, v96, 3
	v_cmp_lt_i32_e64 s[14:15], s78, v113
	v_bfe_u32 v114, v19, 16, 1
	v_add3_u32 v114, v19, v114, s80
	v_add_u32_e32 v113, 0x110, v112
	v_lshl_add_u32 v112, v106, 1, v113
	ds_write_b16_d16_hi v112, v114
	v_add3_u32 v114, s74, v96, 8
	v_cmp_lt_i32_e64 s[16:17], s78, v114
	v_bfe_u32 v115, v20, 16, 1
	v_add3_u32 v115, v20, v115, s80
	v_add_u32_e32 v114, 0x550, v113
	v_lshl_add_u32 v113, v106, 1, v114
	ds_write_b16_d16_hi v113, v115
	v_add3_u32 v115, s74, v96, 9
	v_cmp_lt_i32_e64 s[18:19], s78, v115
	v_bfe_u32 v116, v21, 16, 1
	v_add3_u32 v116, v21, v116, s80
	v_add_u32_e32 v115, 0x110, v114
	v_lshl_add_u32 v114, v106, 1, v115
	ds_write_b16_d16_hi v114, v116
	v_add3_u32 v116, s74, v96, 10
	v_cmp_lt_i32_e64 s[20:21], s78, v116
	v_bfe_u32 v117, v22, 16, 1
	v_add3_u32 v117, v22, v117, s80
	v_add_u32_e32 v116, 0x110, v115
	v_lshl_add_u32 v115, v106, 1, v116
	ds_write_b16_d16_hi v115, v117
	v_add3_u32 v117, s74, v96, 11
	v_cmp_lt_i32_e64 s[22:23], s78, v117
	v_bfe_u32 v118, v23, 16, 1
	v_add_u32_e32 v116, 0x110, v116
	v_add3_u32 v118, v23, v118, s80
	v_lshl_add_u32 v117, v106, 1, v116
	ds_write_b16_d16_hi v117, v118
	v_add3_u32 v118, s74, v96, 16
	v_cmp_lt_i32_e64 s[24:25], s78, v118
	v_bfe_u32 v119, v24, 16, 1
	v_add_u32_e32 v116, 0x550, v116
	v_add3_u32 v119, v24, v119, s80
	v_lshl_add_u32 v118, v106, 1, v116
	ds_write_b16_d16_hi v118, v119
	v_add3_u32 v119, s74, v96, 17
	v_cmp_lt_i32_e64 s[26:27], s78, v119
	v_bfe_u32 v120, v25, 16, 1
	v_add_u32_e32 v116, 0x110, v116
	v_add3_u32 v120, v25, v120, s80
	v_lshl_add_u32 v119, v106, 1, v116
	ds_write_b16_d16_hi v119, v120
	v_add3_u32 v120, s74, v96, 18
	v_cmp_lt_i32_e64 s[28:29], s78, v120
	v_bfe_u32 v121, v26, 16, 1
	v_add_u32_e32 v116, 0x110, v116
	v_add3_u32 v121, v26, v121, s80
	v_lshl_add_u32 v120, v106, 1, v116
	ds_write_b16_d16_hi v120, v121
	v_add3_u32 v121, s74, v96, 19
	v_cmp_lt_i32_e64 s[30:31], s78, v121
	v_bfe_u32 v122, v27, 16, 1
	v_add_u32_e32 v116, 0x110, v116
	v_add3_u32 v122, v27, v122, s80
	v_lshl_add_u32 v121, v106, 1, v116
	ds_write_b16_d16_hi v121, v122
	v_add3_u32 v122, s74, v96, 24
	v_cmp_lt_i32_e64 s[34:35], s78, v122
	v_bfe_u32 v123, v28, 16, 1
	v_add_u32_e32 v116, 0x550, v116
	v_add3_u32 v123, v28, v123, s80
	v_lshl_add_u32 v122, v106, 1, v116
	ds_write_b16_d16_hi v122, v123
	v_add3_u32 v123, s74, v96, 25
	v_cmp_lt_i32_e64 s[36:37], s78, v123
	v_bfe_u32 v124, v29, 16, 1
	v_add_u32_e32 v116, 0x110, v116
	v_add3_u32 v124, v29, v124, s80
	v_lshl_add_u32 v123, v106, 1, v116
	ds_write_b16_d16_hi v123, v124
	v_add3_u32 v124, s74, v96, 26
	v_cmp_lt_i32_e64 s[38:39], s78, v124
	v_bfe_u32 v125, v30, 16, 1
	v_add_u32_e32 v116, 0x110, v116
	v_add3_u32 v124, v30, v125, s80
	v_lshl_add_u32 v116, v106, 1, v116
	ds_write_b16_d16_hi v116, v124
	v_add3_u32 v124, s74, v96, 27
	v_cmp_lt_i32_e64 s[40:41], s78, v124
	v_bfe_u32 v125, v31, 16, 1
	v_add3_u32 v124, v31, v125, s80
	ds_write_b16_d16_hi v116, v124 offset:272
	v_bfe_u32 v124, v48, 16, 1
	v_add3_u32 v48, v48, v124, s80
	ds_write_b16_d16_hi v107, v48 offset:64
	v_bfe_u32 v48, v49, 16, 1
	v_add3_u32 v48, v49, v48, s80
	ds_write_b16_d16_hi v110, v48 offset:64
	v_bfe_u32 v49, v50, 16, 1
	v_add3_u32 v48, v50, v49, s80
	ds_write_b16_d16_hi v111, v48 offset:64
	v_bfe_u32 v49, v51, 16, 1
	v_add3_u32 v48, v51, v49, s80
	ds_write_b16_d16_hi v112, v48 offset:64
	v_bfe_u32 v49, v52, 16, 1
	v_add3_u32 v48, v52, v49, s80
	ds_write_b16_d16_hi v113, v48 offset:64
	v_bfe_u32 v49, v53, 16, 1
	v_add3_u32 v48, v53, v49, s80
	ds_write_b16_d16_hi v114, v48 offset:64
	v_bfe_u32 v49, v54, 16, 1
	v_add3_u32 v48, v54, v49, s80
	ds_write_b16_d16_hi v115, v48 offset:64
	v_bfe_u32 v49, v55, 16, 1
	v_add3_u32 v48, v55, v49, s80
	ds_write_b16_d16_hi v117, v48 offset:64
	v_bfe_u32 v49, v56, 16, 1
	v_add3_u32 v48, v56, v49, s80
	ds_write_b16_d16_hi v118, v48 offset:64
	v_bfe_u32 v49, v57, 16, 1
	v_add3_u32 v48, v57, v49, s80
	ds_write_b16_d16_hi v119, v48 offset:64
	v_bfe_u32 v49, v58, 16, 1
	v_add3_u32 v48, v58, v49, s80
	ds_write_b16_d16_hi v120, v48 offset:64
	v_bfe_u32 v49, v59, 16, 1
	v_add3_u32 v48, v59, v49, s80
	ds_write_b16_d16_hi v121, v48 offset:64
	v_bfe_u32 v49, v60, 16, 1
	v_add3_u32 v48, v60, v49, s80
	ds_write_b16_d16_hi v122, v48 offset:64
	v_bfe_u32 v49, v61, 16, 1
	v_add3_u32 v48, v61, v49, s80
	ds_write_b16_d16_hi v123, v48 offset:64
	v_bfe_u32 v49, v62, 16, 1
	v_add3_u32 v48, v62, v49, s80
; __device__ __forceinline__ float sigmf(float x) { return 1.f / (1.f + __expf(-x)); }
; template <int MT, int NT, class F>
; __device__ __forceinline__ void acc_foreach(int tid, f32x16 (&acc)[MT][NT], F f) {
;     ...
; #pragma unroll
;   for (int mt = 0; mt < MT; mt++)
; #pragma unroll
;     for (int nt = 0; nt < NT; nt++)
; #pragma unroll
;       for (int i = 0; i < 16; i++) {
;         int row = wm * (MT * 32) + mt * 32 + (i & 3) + 8 * (i >> 2) + 4 * hi;
;         int col = wn * (NT * 32) + nt * 32 + c;
;         f(row, col, acc[mt][nt][i]);
;         if (i == 15) __builtin_amdgcn_sched_barrier(0);
;       }
; __device__ __forceinline__ void inproj_epilogue(const Params& p, int layer, int mt, int ntile, int tid,
;                                                 f32x16 (&acc)[2][2], unsigned char* smem) {
;     ...
;     acc_foreach(tid, acc, [&](int row, int col, float v) {
;       int t = m0 + row;
;       float o = v;
;       if (mode == 1) o = (t >= NPADR) ? v : 0.f;
;       if (mode == 2) o = sigmf(v);
;       sT[row * 136 + col] = f2bf(o);
;     });
	ds_write_b16_d16_hi v116, v48 offset:64
	v_bfe_u32 v50, v63, 16, 1
	v_add_u32_e32 v49, 0x110, v116
	v_add3_u32 v48, v63, v50, s80
	ds_write_b16_d16_hi v49, v48 offset:64
	v_or_b32_e32 v48, 32, v96
	v_add_u32_e32 v49, s74, v48
	v_cmp_lt_i32_e64 s[8:9], s78, v49
	v_bfe_u32 v50, v0, 16, 1
	v_add3_u32 v50, v0, v50, s80
	v_mul_lo_u32 v49, v48, s81
	v_lshl_add_u32 v48, v106, 1, v49
	ds_write_b16_d16_hi v48, v50
	v_add3_u32 v50, s74, v96, 33
	v_cmp_lt_i32_e64 s[10:11], s78, v50
	v_bfe_u32 v51, v1, 16, 1
	v_add3_u32 v51, v1, v51, s80
	v_add_u32_e32 v50, 0x110, v49
	v_lshl_add_u32 v49, v106, 1, v50
	ds_write_b16_d16_hi v49, v51
	v_add3_u32 v51, s74, v96, 34
	v_cmp_lt_i32_e64 s[12:13], s78, v51
	v_bfe_u32 v52, v2, 16, 1
	v_add3_u32 v52, v2, v52, s80
	v_add_u32_e32 v51, 0x110, v50
	v_lshl_add_u32 v50, v106, 1, v51
	ds_write_b16_d16_hi v50, v52
	v_add3_u32 v52, s74, v96, 35
	v_cmp_lt_i32_e64 s[14:15], s78, v52
	v_bfe_u32 v53, v3, 16, 1
	v_add3_u32 v53, v3, v53, s80
	v_add_u32_e32 v52, 0x110, v51
	v_lshl_add_u32 v51, v106, 1, v52
	ds_write_b16_d16_hi v51, v53
	v_add3_u32 v53, s74, v96, 40
	v_cmp_lt_i32_e64 s[16:17], s78, v53
	v_bfe_u32 v54, v4, 16, 1
	v_add3_u32 v54, v4, v54, s80
	v_add_u32_e32 v53, 0x550, v52
	v_lshl_add_u32 v52, v106, 1, v53
	ds_write_b16_d16_hi v52, v54
	v_add3_u32 v54, s74, v96, 41
	v_cmp_lt_i32_e64 s[18:19], s78, v54
	v_bfe_u32 v55, v5, 16, 1
	v_add3_u32 v55, v5, v55, s80
	v_add_u32_e32 v54, 0x110, v53
	v_lshl_add_u32 v53, v106, 1, v54
	ds_write_b16_d16_hi v53, v55
	v_add3_u32 v55, s74, v96, 42
	v_cmp_lt_i32_e64 s[20:21], s78, v55
	v_bfe_u32 v56, v6, 16, 1
	v_add3_u32 v56, v6, v56, s80
	v_add_u32_e32 v55, 0x110, v54
	v_lshl_add_u32 v54, v106, 1, v55
	ds_write_b16_d16_hi v54, v56
	v_add3_u32 v56, s74, v96, 43
	v_cmp_lt_i32_e64 s[22:23], s78, v56
	v_bfe_u32 v57, v7, 16, 1
	v_add_u32_e32 v55, 0x110, v55
	v_add3_u32 v57, v7, v57, s80
	v_lshl_add_u32 v56, v106, 1, v55
	ds_write_b16_d16_hi v56, v57
	v_add3_u32 v57, s74, v96, 48
	v_cmp_lt_i32_e64 s[24:25], s78, v57
	v_bfe_u32 v58, v8, 16, 1
	v_add_u32_e32 v55, 0x550, v55
	v_add3_u32 v58, v8, v58, s80
	v_lshl_add_u32 v57, v106, 1, v55
	ds_write_b16_d16_hi v57, v58
	v_add3_u32 v58, s74, v96, 49
	v_cmp_lt_i32_e64 s[26:27], s78, v58
	v_bfe_u32 v59, v9, 16, 1
	v_add_u32_e32 v55, 0x110, v55
	v_add3_u32 v59, v9, v59, s80
	v_lshl_add_u32 v58, v106, 1, v55
	ds_write_b16_d16_hi v58, v59
	v_add3_u32 v59, s74, v96, 50
	v_cmp_lt_i32_e64 s[28:29], s78, v59
	v_bfe_u32 v60, v10, 16, 1
	v_add_u32_e32 v55, 0x110, v55
	v_add3_u32 v60, v10, v60, s80
	v_lshl_add_u32 v59, v106, 1, v55
	ds_write_b16_d16_hi v59, v60
	v_add3_u32 v60, s74, v96, 51
	v_cmp_lt_i32_e64 s[30:31], s78, v60
	v_bfe_u32 v61, v11, 16, 1
	v_add_u32_e32 v55, 0x110, v55
	v_add3_u32 v61, v11, v61, s80
	v_lshl_add_u32 v60, v106, 1, v55
	ds_write_b16_d16_hi v60, v61
	v_add3_u32 v61, s74, v96, 56
	v_cmp_lt_i32_e64 s[34:35], s78, v61
	v_bfe_u32 v62, v12, 16, 1
	v_add_u32_e32 v55, 0x550, v55
	v_add3_u32 v62, v12, v62, s80
	v_lshl_add_u32 v61, v106, 1, v55
	ds_write_b16_d16_hi v61, v62
	v_add3_u32 v62, s74, v96, 57
	v_cmp_lt_i32_e64 s[36:37], s78, v62
	v_bfe_u32 v63, v13, 16, 1
	v_add_u32_e32 v55, 0x110, v55
	v_add3_u32 v63, v13, v63, s80
	v_lshl_add_u32 v62, v106, 1, v55
	ds_write_b16_d16_hi v62, v63
	v_add3_u32 v63, s74, v96, 58
	v_cmp_lt_i32_e64 s[38:39], s78, v63
	v_bfe_u32 v107, v14, 16, 1
	v_add_u32_e32 v55, 0x110, v55
	v_add3_u32 v63, v14, v107, s80
	v_lshl_add_u32 v55, v106, 1, v55
	ds_write_b16_d16_hi v55, v63
	v_add3_u32 v63, s74, v96, 59
	v_cmp_lt_i32_e64 s[40:41], s78, v63
	v_bfe_u32 v96, v15, 16, 1
	v_add3_u32 v63, v15, v96, s80
	ds_write_b16_d16_hi v55, v63 offset:272
	v_bfe_u32 v63, v32, 16, 1
	v_add3_u32 v32, v32, v63, s80
	ds_write_b16_d16_hi v48, v32 offset:64
	v_bfe_u32 v32, v33, 16, 1
	v_add3_u32 v32, v33, v32, s80
	ds_write_b16_d16_hi v49, v32 offset:64
	v_bfe_u32 v33, v34, 16, 1
	v_add3_u32 v32, v34, v33, s80
	ds_write_b16_d16_hi v50, v32 offset:64
	v_bfe_u32 v33, v35, 16, 1
	v_add3_u32 v32, v35, v33, s80
	ds_write_b16_d16_hi v51, v32 offset:64
	v_bfe_u32 v33, v36, 16, 1
	v_add3_u32 v32, v36, v33, s80
	ds_write_b16_d16_hi v52, v32 offset:64
	v_bfe_u32 v33, v37, 16, 1
	v_add3_u32 v32, v37, v33, s80
	ds_write_b16_d16_hi v53, v32 offset:64
	v_bfe_u32 v33, v38, 16, 1
	v_add3_u32 v32, v38, v33, s80
	ds_write_b16_d16_hi v54, v32 offset:64
	v_bfe_u32 v33, v39, 16, 1
	v_add3_u32 v32, v39, v33, s80
	ds_write_b16_d16_hi v56, v32 offset:64
	v_bfe_u32 v33, v40, 16, 1
	v_add3_u32 v32, v40, v33, s80
	ds_write_b16_d16_hi v57, v32 offset:64
	v_bfe_u32 v33, v41, 16, 1
	v_add3_u32 v32, v41, v33, s80
	ds_write_b16_d16_hi v58, v32 offset:64
	v_bfe_u32 v33, v42, 16, 1
	v_add3_u32 v32, v42, v33, s80
	ds_write_b16_d16_hi v59, v32 offset:64
	v_bfe_u32 v33, v43, 16, 1
	v_add3_u32 v32, v43, v33, s80
	ds_write_b16_d16_hi v60, v32 offset:64
	v_bfe_u32 v33, v44, 16, 1
	v_add3_u32 v32, v44, v33, s80
	ds_write_b16_d16_hi v61, v32 offset:64
	v_bfe_u32 v33, v45, 16, 1
	v_add3_u32 v32, v45, v33, s80
	ds_write_b16_d16_hi v62, v32 offset:64
	v_bfe_u32 v33, v46, 16, 1
	v_add3_u32 v32, v46, v33, s80
	ds_write_b16_d16_hi v55, v32 offset:64
	v_mov_b32_e32 v32, v47
	s_branch .LBB0_4343

; __device__ __forceinline__ float sigmf(float x) { return 1.f / (1.f + __expf(-x)); }
; __device__ __forceinline__ float softplusf(float x) { return fmaxf(x, 0.f) + __logf(1.f + __expf(-fabsf(x))); }
; template <int MT, int NT, class F>
; __device__ __forceinline__ void acc_foreach(int tid, f32x16 (&acc)[MT][NT], F f) {
;     ...
;   const int lane = tid & 63, w = tid >> 6;
;   const int wm = w >> 1, wn = w & 1, hi = lane >> 5, c = lane & 31;
; #pragma unroll
;   for (int mt = 0; mt < MT; mt++)
; #pragma unroll
;     for (int nt = 0; nt < NT; nt++)
; #pragma unroll
;       for (int i = 0; i < 16; i++) {
;         int row = wm * (MT * 32) + mt * 32 + (i & 3) + 8 * (i >> 2) + 4 * hi;
;         int col = wn * (NT * 32) + nt * 32 + c;
; __device__ __forceinline__ void inproj_epilogue(const Params& p, int layer, int mt, int ntile, int tid,
;                                                 f32x16 (&acc)[2][2], unsigned char* smem) {
;     ...
;   const int m0 = mt * 128;
;   if (mode == 3) {
;     float* dt = (float*)(p.ws + OFF_DT) + (size_t)m0 * 16;
;     const float* bias = p.ssd_dt_bias + layer * 16;
;     acc_foreach(tid, acc, [&](int row, int col, float v) {
;       if (col < 16) *(dt + row * 16 + col) = softplusf(v + bias[col]);
;     });
;   } else {
;     bf16r* dstb = dst + (size_t)m0 * ld + c0;
;     bf16r* sT = (bf16r*)smem;
;     acc_foreach(tid, acc, [&](int row, int col, float v) {
;       int t = m0 + row;
;       float o = v;
;       if (mode == 1) o = (t >= NPADR) ? v : 0.f;
;       if (mode == 2) o = sigmf(v);
.LBB0_4541:
	s_lshl_b32 s74, s6, 7
	s_ashr_i32 s75, s74, 31
	s_cmp_lg_u32 s7, 3
	s_mov_b64 s[4:5], -1
	s_cbranch_scc0 .LBB0_4735
	v_mov_b32_e32 v106, v108
	s_movk_i32 s4, 0xffc0
	v_lshrrev_b32_e32 v107, 3, v106
	v_ashrrev_i32_e32 v96, 1, v106
	v_and_b32_e32 v107, 4, v107
	v_and_or_b32 v96, v96, s4, v107
	s_cmp_eq_u32 s7, 1
	s_cselect_b64 s[4:5], -1, 0
	v_add_u32_e32 v107, s74, v96
	s_cmp_eq_u32 s7, 2
	s_cselect_b64 s[10:11], -1, 0
	s_cmp_lg_u32 s7, 2
	v_cmp_lt_i32_e64 s[8:9], s81, v107
	s_cbranch_scc0 .Lgv_9
	s_cmp_eq_u32 s7, 1
	s_cbranch_scc0 .Lfp_9

; __device__ __forceinline__ float sigmf(float x) { return 1.f / (1.f + __expf(-x)); }
; template <int MT, int NT, class F>
; __device__ __forceinline__ void acc_foreach(int tid, f32x16 (&acc)[MT][NT], F f) {
;     ...
; #pragma unroll
;   for (int mt = 0; mt < MT; mt++)
; #pragma unroll
;     for (int nt = 0; nt < NT; nt++)
; #pragma unroll
;       for (int i = 0; i < 16; i++) {
;         int row = wm * (MT * 32) + mt * 32 + (i & 3) + 8 * (i >> 2) + 4 * hi;
;         int col = wn * (NT * 32) + nt * 32 + c;
;         f(row, col, acc[mt][nt][i]);
;         if (i == 15) __builtin_amdgcn_sched_barrier(0);
;       }
; __device__ __forceinline__ void inproj_epilogue(const Params& p, int layer, int mt, int ntile, int tid,
;                                                 f32x16 (&acc)[2][2], unsigned char* smem) {
;     ...
;     acc_foreach(tid, acc, [&](int row, int col, float v) {
;       int t = m0 + row;
;       float o = v;
;       if (mode == 1) o = (t >= NPADR) ? v : 0.f;
;       if (mode == 2) o = sigmf(v);
;       sT[row * 136 + col] = f2bf(o);
;     });
.Lfp_9:
	v_bfe_u32 v110, v16, 16, 1
	v_and_b32_e32 v106, 0x5f, v106
	v_add3_u32 v111, v16, v110, s83
	v_mul_lo_u32 v110, v96, s86
	v_lshl_add_u32 v107, v106, 1, v110
	ds_write_b16_d16_hi v107, v111
	v_add3_u32 v111, s74, v96, 1
	v_cndmask_b32_e64 v112, 0, 1, s[10:11]
	v_cmp_ne_u32_e64 s[6:7], 1, v112
	v_cmp_lt_i32_e64 s[10:11], s81, v111
	v_bfe_u32 v112, v17, 16, 1
	v_add3_u32 v112, v17, v112, s83
	v_add_u32_e32 v111, 0x110, v110
	v_lshl_add_u32 v110, v106, 1, v111
	ds_write_b16_d16_hi v110, v112
	v_add3_u32 v112, s74, v96, 2
	v_cmp_lt_i32_e64 s[12:13], s81, v112
	v_bfe_u32 v113, v18, 16, 1
	v_add3_u32 v113, v18, v113, s83
	v_add_u32_e32 v112, 0x110, v111
	v_lshl_add_u32 v111, v106, 1, v112
	ds_write_b16_d16_hi v111, v113
	v_add3_u32 v113, s74, v96, 3
	v_cmp_lt_i32_e64 s[14:15], s81, v113
	v_bfe_u32 v114, v19, 16, 1
	v_add3_u32 v114, v19, v114, s83
	v_add_u32_e32 v113, 0x110, v112
	v_lshl_add_u32 v112, v106, 1, v113
	ds_write_b16_d16_hi v112, v114
	v_add3_u32 v114, s74, v96, 8
	v_cmp_lt_i32_e64 s[16:17], s81, v114
	v_bfe_u32 v115, v20, 16, 1
	v_add3_u32 v115, v20, v115, s83
	v_add_u32_e32 v114, 0x550, v113
	v_lshl_add_u32 v113, v106, 1, v114
	ds_write_b16_d16_hi v113, v115
	v_add3_u32 v115, s74, v96, 9
	v_cmp_lt_i32_e64 s[18:19], s81, v115
	v_bfe_u32 v116, v21, 16, 1
	v_add3_u32 v116, v21, v116, s83
	v_add_u32_e32 v115, 0x110, v114
	v_lshl_add_u32 v114, v106, 1, v115
	ds_write_b16_d16_hi v114, v116
	v_add3_u32 v116, s74, v96, 10
	v_cmp_lt_i32_e64 s[20:21], s81, v116
	v_bfe_u32 v117, v22, 16, 1
	v_add3_u32 v117, v22, v117, s83
	v_add_u32_e32 v116, 0x110, v115
	v_lshl_add_u32 v115, v106, 1, v116
	ds_write_b16_d16_hi v115, v117
	v_add3_u32 v117, s74, v96, 11
	v_cmp_lt_i32_e64 s[22:23], s81, v117
	v_bfe_u32 v118, v23, 16, 1
	v_add_u32_e32 v116, 0x110, v116
	v_add3_u32 v118, v23, v118, s83
	v_lshl_add_u32 v117, v106, 1, v116
	ds_write_b16_d16_hi v117, v118
	v_add3_u32 v118, s74, v96, 16
	v_cmp_lt_i32_e64 s[24:25], s81, v118
	v_bfe_u32 v119, v24, 16, 1
	v_add_u32_e32 v116, 0x550, v116
	v_add3_u32 v119, v24, v119, s83
	v_lshl_add_u32 v118, v106, 1, v116
	ds_write_b16_d16_hi v118, v119
	v_add3_u32 v119, s74, v96, 17
	v_cmp_lt_i32_e64 s[26:27], s81, v119
	v_bfe_u32 v120, v25, 16, 1
	v_add_u32_e32 v116, 0x110, v116
	v_add3_u32 v120, v25, v120, s83
	v_lshl_add_u32 v119, v106, 1, v116
	ds_write_b16_d16_hi v119, v120
	v_add3_u32 v120, s74, v96, 18
	v_cmp_lt_i32_e64 s[28:29], s81, v120
	v_bfe_u32 v121, v26, 16, 1
	v_add_u32_e32 v116, 0x110, v116
	v_add3_u32 v121, v26, v121, s83
	v_lshl_add_u32 v120, v106, 1, v116
	ds_write_b16_d16_hi v120, v121
	v_add3_u32 v121, s74, v96, 19
	v_cmp_lt_i32_e64 s[30:31], s81, v121
	v_bfe_u32 v122, v27, 16, 1
	v_add_u32_e32 v116, 0x110, v116
	v_add3_u32 v122, v27, v122, s83
	v_lshl_add_u32 v121, v106, 1, v116
	ds_write_b16_d16_hi v121, v122
	v_add3_u32 v122, s74, v96, 24
	v_cmp_lt_i32_e64 s[34:35], s81, v122
	v_bfe_u32 v123, v28, 16, 1
	v_add_u32_e32 v116, 0x550, v116
	v_add3_u32 v123, v28, v123, s83
	v_lshl_add_u32 v122, v106, 1, v116
	ds_write_b16_d16_hi v122, v123
	v_add3_u32 v123, s74, v96, 25
	v_cmp_lt_i32_e64 s[36:37], s81, v123
	v_bfe_u32 v124, v29, 16, 1
	v_add_u32_e32 v116, 0x110, v116
	v_add3_u32 v124, v29, v124, s83
	v_lshl_add_u32 v123, v106, 1, v116
	ds_write_b16_d16_hi v123, v124
	v_add3_u32 v124, s74, v96, 26
	v_cmp_lt_i32_e64 s[38:39], s81, v124
	v_bfe_u32 v125, v30, 16, 1
	v_add_u32_e32 v116, 0x110, v116
	v_add3_u32 v124, v30, v125, s83
	v_lshl_add_u32 v116, v106, 1, v116
	ds_write_b16_d16_hi v116, v124
	v_add3_u32 v124, s74, v96, 27
	v_cmp_lt_i32_e64 s[40:41], s81, v124
	v_bfe_u32 v125, v31, 16, 1
	v_add3_u32 v124, v31, v125, s83
	ds_write_b16_d16_hi v116, v124 offset:272
	v_bfe_u32 v124, v48, 16, 1
	v_add3_u32 v48, v48, v124, s83
	ds_write_b16_d16_hi v107, v48 offset:64
	v_bfe_u32 v48, v49, 16, 1
	v_add3_u32 v48, v49, v48, s83
	ds_write_b16_d16_hi v110, v48 offset:64
	v_bfe_u32 v49, v50, 16, 1
	v_add3_u32 v48, v50, v49, s83
	ds_write_b16_d16_hi v111, v48 offset:64
	v_bfe_u32 v49, v51, 16, 1
	v_add3_u32 v48, v51, v49, s83
	ds_write_b16_d16_hi v112, v48 offset:64
	v_bfe_u32 v49, v52, 16, 1
	v_add3_u32 v48, v52, v49, s83
	ds_write_b16_d16_hi v113, v48 offset:64
	v_bfe_u32 v49, v53, 16, 1
	v_add3_u32 v48, v53, v49, s83
	ds_write_b16_d16_hi v114, v48 offset:64
	v_bfe_u32 v49, v54, 16, 1
	v_add3_u32 v48, v54, v49, s83
	ds_write_b16_d16_hi v115, v48 offset:64
	v_bfe_u32 v49, v55, 16, 1
	v_add3_u32 v48, v55, v49, s83
	ds_write_b16_d16_hi v117, v48 offset:64
	v_bfe_u32 v49, v56, 16, 1
	v_add3_u32 v48, v56, v49, s83
	ds_write_b16_d16_hi v118, v48 offset:64
	v_bfe_u32 v49, v57, 16, 1
	v_add3_u32 v48, v57, v49, s83
	ds_write_b16_d16_hi v119, v48 offset:64
	v_bfe_u32 v49, v58, 16, 1
	v_add3_u32 v48, v58, v49, s83
	ds_write_b16_d16_hi v120, v48 offset:64
	v_bfe_u32 v49, v59, 16, 1
	v_add3_u32 v48, v59, v49, s83
	ds_write_b16_d16_hi v121, v48 offset:64
	v_bfe_u32 v49, v60, 16, 1
	v_add3_u32 v48, v60, v49, s83
	ds_write_b16_d16_hi v122, v48 offset:64
	v_bfe_u32 v49, v61, 16, 1
	v_add3_u32 v48, v61, v49, s83
	ds_write_b16_d16_hi v123, v48 offset:64
	v_bfe_u32 v49, v62, 16, 1
	v_add3_u32 v48, v62, v49, s83
; __device__ __forceinline__ float sigmf(float x) { return 1.f / (1.f + __expf(-x)); }
; template <int MT, int NT, class F>
; __device__ __forceinline__ void acc_foreach(int tid, f32x16 (&acc)[MT][NT], F f) {
;     ...
; #pragma unroll
;   for (int mt = 0; mt < MT; mt++)
; #pragma unroll
;     for (int nt = 0; nt < NT; nt++)
; #pragma unroll
;       for (int i = 0; i < 16; i++) {
;         int row = wm * (MT * 32) + mt * 32 + (i & 3) + 8 * (i >> 2) + 4 * hi;
;         int col = wn * (NT * 32) + nt * 32 + c;
;         f(row, col, acc[mt][nt][i]);
;         if (i == 15) __builtin_amdgcn_sched_barrier(0);
;       }
; __device__ __forceinline__ void inproj_epilogue(const Params& p, int layer, int mt, int ntile, int tid,
;                                                 f32x16 (&acc)[2][2], unsigned char* smem) {
;     ...
;     acc_foreach(tid, acc, [&](int row, int col, float v) {
;       int t = m0 + row;
;       float o = v;
;       if (mode == 1) o = (t >= NPADR) ? v : 0.f;
;       if (mode == 2) o = sigmf(v);
;       sT[row * 136 + col] = f2bf(o);
;     });
	ds_write_b16_d16_hi v116, v48 offset:64
	v_bfe_u32 v50, v63, 16, 1
	v_add_u32_e32 v49, 0x110, v116
	v_add3_u32 v48, v63, v50, s83
	ds_write_b16_d16_hi v49, v48 offset:64
	v_or_b32_e32 v48, 32, v96
	v_add_u32_e32 v49, s74, v48
	v_cmp_lt_i32_e64 s[8:9], s81, v49
	v_bfe_u32 v50, v0, 16, 1
	v_add3_u32 v50, v0, v50, s83
	v_mul_lo_u32 v49, v48, s86
	v_lshl_add_u32 v48, v106, 1, v49
	ds_write_b16_d16_hi v48, v50
	v_add3_u32 v50, s74, v96, 33
	v_cmp_lt_i32_e64 s[10:11], s81, v50
	v_bfe_u32 v51, v1, 16, 1
	v_add3_u32 v51, v1, v51, s83
	v_add_u32_e32 v50, 0x110, v49
	v_lshl_add_u32 v49, v106, 1, v50
	ds_write_b16_d16_hi v49, v51
	v_add3_u32 v51, s74, v96, 34
	v_cmp_lt_i32_e64 s[12:13], s81, v51
	v_bfe_u32 v52, v2, 16, 1
	v_add3_u32 v52, v2, v52, s83
	v_add_u32_e32 v51, 0x110, v50
	v_lshl_add_u32 v50, v106, 1, v51
	ds_write_b16_d16_hi v50, v52
	v_add3_u32 v52, s74, v96, 35
	v_cmp_lt_i32_e64 s[14:15], s81, v52
	v_bfe_u32 v53, v3, 16, 1
	v_add3_u32 v53, v3, v53, s83
	v_add_u32_e32 v52, 0x110, v51
	v_lshl_add_u32 v51, v106, 1, v52
	ds_write_b16_d16_hi v51, v53
	v_add3_u32 v53, s74, v96, 40
	v_cmp_lt_i32_e64 s[16:17], s81, v53
	v_bfe_u32 v54, v4, 16, 1
	v_add3_u32 v54, v4, v54, s83
	v_add_u32_e32 v53, 0x550, v52
	v_lshl_add_u32 v52, v106, 1, v53
	ds_write_b16_d16_hi v52, v54
	v_add3_u32 v54, s74, v96, 41
	v_cmp_lt_i32_e64 s[18:19], s81, v54
	v_bfe_u32 v55, v5, 16, 1
	v_add3_u32 v55, v5, v55, s83
	v_add_u32_e32 v54, 0x110, v53
	v_lshl_add_u32 v53, v106, 1, v54
	ds_write_b16_d16_hi v53, v55
	v_add3_u32 v55, s74, v96, 42
	v_cmp_lt_i32_e64 s[20:21], s81, v55
	v_bfe_u32 v56, v6, 16, 1
	v_add3_u32 v56, v6, v56, s83
	v_add_u32_e32 v55, 0x110, v54
	v_lshl_add_u32 v54, v106, 1, v55
	ds_write_b16_d16_hi v54, v56
	v_add3_u32 v56, s74, v96, 43
	v_cmp_lt_i32_e64 s[22:23], s81, v56
	v_bfe_u32 v57, v7, 16, 1
	v_add_u32_e32 v55, 0x110, v55
	v_add3_u32 v57, v7, v57, s83
	v_lshl_add_u32 v56, v106, 1, v55
	ds_write_b16_d16_hi v56, v57
	v_add3_u32 v57, s74, v96, 48
	v_cmp_lt_i32_e64 s[24:25], s81, v57
	v_bfe_u32 v58, v8, 16, 1
	v_add_u32_e32 v55, 0x550, v55
	v_add3_u32 v58, v8, v58, s83
	v_lshl_add_u32 v57, v106, 1, v55
	ds_write_b16_d16_hi v57, v58
	v_add3_u32 v58, s74, v96, 49
	v_cmp_lt_i32_e64 s[26:27], s81, v58
	v_bfe_u32 v59, v9, 16, 1
	v_add_u32_e32 v55, 0x110, v55
	v_add3_u32 v59, v9, v59, s83
	v_lshl_add_u32 v58, v106, 1, v55
	ds_write_b16_d16_hi v58, v59
	v_add3_u32 v59, s74, v96, 50
	v_cmp_lt_i32_e64 s[28:29], s81, v59
	v_bfe_u32 v60, v10, 16, 1
	v_add_u32_e32 v55, 0x110, v55
	v_add3_u32 v60, v10, v60, s83
	v_lshl_add_u32 v59, v106, 1, v55
	ds_write_b16_d16_hi v59, v60
	v_add3_u32 v60, s74, v96, 51
	v_cmp_lt_i32_e64 s[30:31], s81, v60
	v_bfe_u32 v61, v11, 16, 1
	v_add_u32_e32 v55, 0x110, v55
	v_add3_u32 v61, v11, v61, s83
	v_lshl_add_u32 v60, v106, 1, v55
	ds_write_b16_d16_hi v60, v61
	v_add3_u32 v61, s74, v96, 56
	v_cmp_lt_i32_e64 s[34:35], s81, v61
	v_bfe_u32 v62, v12, 16, 1
	v_add_u32_e32 v55, 0x550, v55
	v_add3_u32 v62, v12, v62, s83
	v_lshl_add_u32 v61, v106, 1, v55
	ds_write_b16_d16_hi v61, v62
	v_add3_u32 v62, s74, v96, 57
	v_cmp_lt_i32_e64 s[36:37], s81, v62
	v_bfe_u32 v63, v13, 16, 1
	v_add_u32_e32 v55, 0x110, v55
	v_add3_u32 v63, v13, v63, s83
	v_lshl_add_u32 v62, v106, 1, v55
	ds_write_b16_d16_hi v62, v63
	v_add3_u32 v63, s74, v96, 58
	v_cmp_lt_i32_e64 s[38:39], s81, v63
	v_bfe_u32 v107, v14, 16, 1
	v_add_u32_e32 v55, 0x110, v55
	v_add3_u32 v63, v14, v107, s83
	v_lshl_add_u32 v55, v106, 1, v55
	ds_write_b16_d16_hi v55, v63
	v_add3_u32 v63, s74, v96, 59
	v_cmp_lt_i32_e64 s[40:41], s81, v63
	v_bfe_u32 v96, v15, 16, 1
	v_add3_u32 v63, v15, v96, s83
	ds_write_b16_d16_hi v55, v63 offset:272
	v_bfe_u32 v63, v32, 16, 1
	v_add3_u32 v32, v32, v63, s83
	ds_write_b16_d16_hi v48, v32 offset:64
	v_bfe_u32 v32, v33, 16, 1
	v_add3_u32 v32, v33, v32, s83
	ds_write_b16_d16_hi v49, v32 offset:64
	v_bfe_u32 v33, v34, 16, 1
	v_add3_u32 v32, v34, v33, s83
	ds_write_b16_d16_hi v50, v32 offset:64
	v_bfe_u32 v33, v35, 16, 1
	v_add3_u32 v32, v35, v33, s83
	ds_write_b16_d16_hi v51, v32 offset:64
	v_bfe_u32 v33, v36, 16, 1
	v_add3_u32 v32, v36, v33, s83
	ds_write_b16_d16_hi v52, v32 offset:64
	v_bfe_u32 v33, v37, 16, 1
	v_add3_u32 v32, v37, v33, s83
	ds_write_b16_d16_hi v53, v32 offset:64
	v_bfe_u32 v33, v38, 16, 1
	v_add3_u32 v32, v38, v33, s83
	ds_write_b16_d16_hi v54, v32 offset:64
	v_bfe_u32 v33, v39, 16, 1
	v_add3_u32 v32, v39, v33, s83
	ds_write_b16_d16_hi v56, v32 offset:64
	v_bfe_u32 v33, v40, 16, 1
	v_add3_u32 v32, v40, v33, s83
	ds_write_b16_d16_hi v57, v32 offset:64
	v_bfe_u32 v33, v41, 16, 1
	v_add3_u32 v32, v41, v33, s83
	ds_write_b16_d16_hi v58, v32 offset:64
	v_bfe_u32 v33, v42, 16, 1
	v_add3_u32 v32, v42, v33, s83
	ds_write_b16_d16_hi v59, v32 offset:64
	v_bfe_u32 v33, v43, 16, 1
	v_add3_u32 v32, v43, v33, s83
	ds_write_b16_d16_hi v60, v32 offset:64
	v_bfe_u32 v33, v44, 16, 1
	v_add3_u32 v32, v44, v33, s83
	ds_write_b16_d16_hi v61, v32 offset:64
	v_bfe_u32 v33, v45, 16, 1
	v_add3_u32 v32, v45, v33, s83
	ds_write_b16_d16_hi v62, v32 offset:64
	v_bfe_u32 v33, v46, 16, 1
	v_add3_u32 v32, v46, v33, s83
	ds_write_b16_d16_hi v55, v32 offset:64
	v_mov_b32_e32 v32, v47
	s_branch .LBB0_4734
